# peeled first K iteration waits for vmcnt(24) instead of 8 in its first two segments when the fast epilogue left 16+ stores in flight
# baseline (speedup 1.0000x reference)
.LBB0_106:
	s_mov_b32 s100, 0
	s_barrier
	s_mov_b64 s[2:3], 0
	s_mov_b32 s35, 0x2aaaaaab
	s_mov_b32 s38, 0x30000

.LBB0_367:
	s_mov_b32 s100, 0
	v_readlane_b32 s2, v252, 30
	v_readlane_b32 s3, v252, 31
	s_lshl_b64 s[4:5], s[2:3], 21
	v_readlane_b32 s2, v252, 26
	v_readlane_b32 s3, v252, 27
	s_and_b64 s[2:3], s[2:3], exec
	s_mov_b32 s2, 0x2800000
	s_cselect_b32 s3, s2, 0x2c00000
	s_cmp_lt_u32 s50, 5
	s_cselect_b64 s[6:7], -1, 0
	s_cmp_gt_u32 s50, 4
	s_cselect_b64 s[28:29], -1, 0
	s_lshl_b32 s2, s61, 10
	s_cmpk_gt_i32 s80, 0xff
	s_cbranch_scc1 .LBB0_380
	s_cmp_lt_i32 s50, 11
	s_cselect_b64 s[10:11], -1, 0
	s_add_i32 s8, s2, 0x400
	s_ashr_i32 s9, s8, 31
	s_add_i32 s12, s61, 1
	s_mul_hi_i32 s13, s12, 0x10200
	s_mul_i32 s12, s12, 0x10200
	s_waitcnt lgkmcnt(0)
	s_lshl_b64 s[14:15], s[8:9], 2
	s_mov_b32 s20, s80
	s_branch .LBB0_370

.LBB0_404:
	s_ashr_i32 s55, s54, 31
	s_lshl_b64 s[2:3], s[54:55], 19
	s_add_u32 s56, s60, s2
	s_addc_u32 s57, s65, s3
	s_and_b64 s[2:3], s[10:11], exec
	s_cselect_b32 s16, s57, s15
	s_cselect_b32 s17, s56, s14
	s_ashr_i32 s31, s30, 31
	s_lshl_b64 s[2:3], s[30:31], 19
	s_add_u32 s4, s66, s2
	s_addc_u32 s5, s68, s3
	s_and_b64 s[2:3], s[10:11], exec
	s_cselect_b32 s18, s5, s13
	s_cselect_b32 s19, s4, s12
	s_add_u32 s2, s14, 0x40080
	s_addc_u32 s3, s15, 0
	s_add_u32 s20, s12, 0x100
	s_addc_u32 s21, s13, 0
	s_mov_b32 s22, -2
	s_add_u32 s12, s2, 0xfffc0080
	s_addc_u32 s13, s3, -1
	s_add_i32 s23, 0, 0x10000
	s_cmp_eq_u32 s22, 12
	s_cselect_b32 s15, s16, s13
	s_cselect_b32 s14, s17, s12
	v_add_u32_e32 v96, s23, v221
	s_cselect_b32 s13, s18, s21
	s_cselect_b32 s12, s19, s20
	s_add_i32 s31, 0, 0x14000
	ds_read_b128 v[0:3], v96
	ds_read_b128 v[4:7], v96 offset:1024
	ds_read_b128 v[138:141], v96 offset:2048
	ds_read_b128 v[142:145], v96 offset:3072
	v_add_u32_e32 v96, s31, v221
	ds_read_b128 v[146:149], v96
	ds_read_b128 v[150:153], v96 offset:1024
	ds_read_b128 v[180:183], v96 offset:2048
	ds_read_b128 v[184:187], v96 offset:3072
	v_lshl_add_u64 v[170:171], s[2:3], 0, v[166:167]
	s_add_i32 m0, s69, 0xc000
	ds_read_b128 v[188:191], v231
	ds_read_b128 v[192:195], v231 offset:1024
	ds_read_b128 v[196:199], v231 offset:2048
	ds_read_b128 v[200:203], v231 offset:3072
	ds_read_b128 v[204:207], v231 offset:4096
	ds_read_b128 v[234:237], v231 offset:5120
	ds_read_b128 v[238:241], v231 offset:6144
	ds_read_b128 v[242:245], v231 offset:7168
	global_load_lds_dwordx4 v[170:171], off
	v_lshl_add_u64 v[170:171], s[2:3], 0, v[168:169]
	s_add_i32 m0, s69, 0xe000
	s_nop 0
	global_load_lds_dwordx4 v[170:171], off
	s_cmp_lg_u32 s100, 0
	s_cbranch_scc1 .Lpl_out_r1
	s_waitcnt vmcnt(8)
	s_branch .Lpl_out_j1
.Lpl_out_r1:
	s_waitcnt vmcnt(24)
.Lpl_out_j1:
	s_waitcnt lgkmcnt(0)
	s_barrier
	s_setprio 1
	s_waitcnt lgkmcnt(0)
	v_mfma_f32_16x16x32_bf16 v[134:137], v[0:3], v[188:191], 0
	v_mfma_f32_16x16x32_bf16 v[130:133], v[138:141], v[188:191], 0
	v_mfma_f32_16x16x32_bf16 v[118:121], v[0:3], v[196:199], 0
	v_mfma_f32_16x16x32_bf16 v[114:117], v[138:141], v[196:199], 0
	v_mfma_f32_16x16x32_bf16 v[102:105], v[0:3], v[204:207], 0
	v_mfma_f32_16x16x32_bf16 v[98:101], v[138:141], v[204:207], 0
	v_mfma_f32_16x16x32_bf16 v[84:87], v[0:3], v[238:241], 0
	v_mfma_f32_16x16x32_bf16 v[80:83], v[138:141], v[238:241], 0
	v_mfma_f32_16x16x32_bf16 v[134:137], v[4:7], v[192:195], v[134:137]
	v_mfma_f32_16x16x32_bf16 v[130:133], v[142:145], v[192:195], v[130:133]
	v_mfma_f32_16x16x32_bf16 v[118:121], v[4:7], v[200:203], v[118:121]
	v_mfma_f32_16x16x32_bf16 v[114:117], v[142:145], v[200:203], v[114:117]
	v_mfma_f32_16x16x32_bf16 v[102:105], v[4:7], v[234:237], v[102:105]
	v_mfma_f32_16x16x32_bf16 v[98:101], v[142:145], v[234:237], v[98:101]
	v_mfma_f32_16x16x32_bf16 v[84:87], v[4:7], v[242:245], v[84:87]
	v_mfma_f32_16x16x32_bf16 v[80:83], v[142:145], v[242:245], v[80:83]
	s_setprio 0
	s_setprio 1
	v_mfma_f32_16x16x32_bf16 v[126:129], v[146:149], v[188:191], 0
	v_mfma_f32_16x16x32_bf16 v[122:125], v[180:183], v[188:191], 0
	v_mfma_f32_16x16x32_bf16 v[110:113], v[146:149], v[196:199], 0
	v_mfma_f32_16x16x32_bf16 v[106:109], v[180:183], v[196:199], 0
	v_mfma_f32_16x16x32_bf16 v[92:95], v[146:149], v[204:207], 0
	v_mfma_f32_16x16x32_bf16 v[88:91], v[180:183], v[204:207], 0
	v_mfma_f32_16x16x32_bf16 v[76:79], v[146:149], v[238:241], 0
	v_mfma_f32_16x16x32_bf16 v[72:75], v[180:183], v[238:241], 0
	v_mfma_f32_16x16x32_bf16 v[126:129], v[150:153], v[192:195], v[126:129]
	v_mfma_f32_16x16x32_bf16 v[122:125], v[184:187], v[192:195], v[122:125]
	v_mfma_f32_16x16x32_bf16 v[110:113], v[150:153], v[200:203], v[110:113]
	v_mfma_f32_16x16x32_bf16 v[106:109], v[184:187], v[200:203], v[106:109]
	v_mfma_f32_16x16x32_bf16 v[92:95], v[150:153], v[234:237], v[92:95]
	v_mfma_f32_16x16x32_bf16 v[88:91], v[184:187], v[234:237], v[88:91]
	v_mfma_f32_16x16x32_bf16 v[76:79], v[150:153], v[242:245], v[76:79]
	v_mfma_f32_16x16x32_bf16 v[72:75], v[184:187], v[242:245], v[72:75]
	s_setprio 0
	s_barrier
	s_add_i32 s23, s23, s58
	v_lshl_add_u64 v[170:171], s[12:13], 0, v[156:157]
	s_mov_b32 m0, s23
	ds_read_b128 v[188:191], v231 offset:16384
	ds_read_b128 v[192:195], v231 offset:17408
	ds_read_b128 v[196:199], v231 offset:18432
	ds_read_b128 v[200:203], v231 offset:19456
	ds_read_b128 v[204:207], v231 offset:20480
	ds_read_b128 v[234:237], v231 offset:21504
	ds_read_b128 v[238:241], v231 offset:22528
	ds_read_b128 v[242:245], v231 offset:23552
	global_load_lds_dwordx4 v[170:171], off
	s_add_i32 m0, s23, 0x2000
	s_add_u32 s26, s12, 0x10000
	v_lshl_add_u64 v[208:209], s[12:13], 0, v[160:161]
	s_addc_u32 s27, s13, 0
	s_add_i32 s23, s31, s58
	global_load_lds_dwordx4 v[208:209], off
	v_lshl_add_u64 v[246:247], s[26:27], 0, v[156:157]
	s_mov_b32 m0, s23
	v_lshl_add_u64 v[248:249], s[14:15], 0, v[158:159]
	global_load_lds_dwordx4 v[246:247], off
	v_lshl_add_u64 v[246:247], s[26:27], 0, v[160:161]
	s_add_i32 m0, s23, 0x2000
	s_nop 0
	global_load_lds_dwordx4 v[246:247], off
	v_lshl_add_u64 v[246:247], s[14:15], 0, v[154:155]
	s_mov_b32 m0, s69
	s_nop 0
	global_load_lds_dwordx4 v[246:247], off
	s_mov_b32 m0, s70
	s_nop 0
	global_load_lds_dwordx4 v[248:249], off
	s_cmp_lg_u32 s100, 0
	s_cbranch_scc1 .Lpl_out_r2
	s_waitcnt vmcnt(8)
	s_branch .Lpl_out_j2

.Lpl_out_j2:
	s_mov_b32 s100, 0
	s_waitcnt lgkmcnt(0)
	s_barrier
	s_setprio 1
	s_waitcnt lgkmcnt(0)
	v_mfma_f32_16x16x32_bf16 v[68:71], v[0:3], v[188:191], 0
	v_mfma_f32_16x16x32_bf16 v[64:67], v[138:141], v[188:191], 0
	v_mfma_f32_16x16x32_bf16 v[52:55], v[0:3], v[196:199], 0
	v_mfma_f32_16x16x32_bf16 v[48:51], v[138:141], v[196:199], 0
	v_mfma_f32_16x16x32_bf16 v[36:39], v[0:3], v[204:207], 0
	v_mfma_f32_16x16x32_bf16 v[32:35], v[138:141], v[204:207], 0
	v_mfma_f32_16x16x32_bf16 v[0:3], v[0:3], v[238:241], 0
	v_mfma_f32_16x16x32_bf16 v[68:71], v[4:7], v[192:195], v[68:71]
	v_mfma_f32_16x16x32_bf16 v[64:67], v[142:145], v[192:195], v[64:67]
	v_mfma_f32_16x16x32_bf16 v[52:55], v[4:7], v[200:203], v[52:55]
	v_mfma_f32_16x16x32_bf16 v[48:51], v[142:145], v[200:203], v[48:51]
	v_mfma_f32_16x16x32_bf16 v[36:39], v[4:7], v[234:237], v[36:39]
	v_mfma_f32_16x16x32_bf16 v[32:35], v[142:145], v[234:237], v[32:35]
	v_mfma_f32_16x16x32_bf16 v[0:3], v[4:7], v[242:245], v[0:3]
	v_mfma_f32_16x16x32_bf16 v[4:7], v[138:141], v[238:241], 0
	v_mfma_f32_16x16x32_bf16 v[4:7], v[142:145], v[242:245], v[4:7]
	s_setprio 0
	s_setprio 1
	v_mfma_f32_16x16x32_bf16 v[16:19], v[146:149], v[188:191], 0
	v_mfma_f32_16x16x32_bf16 v[60:63], v[150:153], v[192:195], v[16:19]
	v_mfma_f32_16x16x32_bf16 v[16:19], v[180:183], v[188:191], 0
	v_mfma_f32_16x16x32_bf16 v[56:59], v[184:187], v[192:195], v[16:19]
	v_mfma_f32_16x16x32_bf16 v[16:19], v[146:149], v[196:199], 0
	v_mfma_f32_16x16x32_bf16 v[44:47], v[150:153], v[200:203], v[16:19]
	v_mfma_f32_16x16x32_bf16 v[16:19], v[180:183], v[196:199], 0
	v_mfma_f32_16x16x32_bf16 v[40:43], v[184:187], v[200:203], v[16:19]
	v_mfma_f32_16x16x32_bf16 v[16:19], v[146:149], v[204:207], 0
	v_mfma_f32_16x16x32_bf16 v[28:31], v[150:153], v[234:237], v[16:19]
	v_mfma_f32_16x16x32_bf16 v[16:19], v[180:183], v[204:207], 0
	v_mfma_f32_16x16x32_bf16 v[12:15], v[146:149], v[238:241], 0
	v_mfma_f32_16x16x32_bf16 v[8:11], v[180:183], v[238:241], 0
	v_mfma_f32_16x16x32_bf16 v[24:27], v[184:187], v[234:237], v[16:19]
	v_mfma_f32_16x16x32_bf16 v[12:15], v[150:153], v[242:245], v[12:15]
	v_mfma_f32_16x16x32_bf16 v[8:11], v[184:187], v[242:245], v[8:11]
	s_setprio 0
	s_barrier
	v_add_u32_e32 v96, s67, v221
	s_add_i32 s23, 0, 0x1c000
	ds_read_b128 v[16:19], v96
	ds_read_b128 v[20:23], v96 offset:1024
	ds_read_b128 v[138:141], v96 offset:2048
	ds_read_b128 v[142:145], v96 offset:3072
	v_add_u32_e32 v96, s23, v221
	ds_read_b128 v[146:149], v96
	ds_read_b128 v[150:153], v96 offset:1024
	ds_read_b128 v[180:183], v96 offset:2048
	ds_read_b128 v[184:187], v96 offset:3072
	s_add_u32 s14, s14, 0x40000
	s_addc_u32 s15, s15, 0
	s_mov_b32 m0, s71
	v_lshl_add_u64 v[250:251], s[14:15], 0, v[154:155]
	ds_read_b128 v[188:191], v231 offset:32768
	ds_read_b128 v[192:195], v231 offset:33792
	ds_read_b128 v[196:199], v231 offset:34816
	ds_read_b128 v[200:203], v231 offset:35840
	ds_read_b128 v[204:207], v231 offset:36864
	ds_read_b128 v[234:237], v231 offset:37888
	ds_read_b128 v[238:241], v231 offset:38912
	ds_read_b128 v[242:245], v231 offset:39936
	global_load_lds_dwordx4 v[250:251], off
	v_lshl_add_u64 v[250:251], s[14:15], 0, v[158:159]
	s_mov_b32 m0, s76
	s_nop 0
	global_load_lds_dwordx4 v[250:251], off
	s_waitcnt vmcnt(8)
	s_waitcnt lgkmcnt(0)
	s_barrier
	s_setprio 1
	s_waitcnt lgkmcnt(0)
	v_mfma_f32_16x16x32_bf16 v[134:137], v[16:19], v[188:191], v[134:137]
	v_mfma_f32_16x16x32_bf16 v[130:133], v[138:141], v[188:191], v[130:133]
	v_mfma_f32_16x16x32_bf16 v[118:121], v[16:19], v[196:199], v[118:121]
	v_mfma_f32_16x16x32_bf16 v[114:117], v[138:141], v[196:199], v[114:117]
	v_mfma_f32_16x16x32_bf16 v[102:105], v[16:19], v[204:207], v[102:105]
	v_mfma_f32_16x16x32_bf16 v[98:101], v[138:141], v[204:207], v[98:101]
	v_mfma_f32_16x16x32_bf16 v[84:87], v[16:19], v[238:241], v[84:87]
	v_mfma_f32_16x16x32_bf16 v[80:83], v[138:141], v[238:241], v[80:83]
	v_mfma_f32_16x16x32_bf16 v[134:137], v[20:23], v[192:195], v[134:137]
	v_mfma_f32_16x16x32_bf16 v[130:133], v[142:145], v[192:195], v[130:133]
	v_mfma_f32_16x16x32_bf16 v[118:121], v[20:23], v[200:203], v[118:121]
	v_mfma_f32_16x16x32_bf16 v[114:117], v[142:145], v[200:203], v[114:117]
	v_mfma_f32_16x16x32_bf16 v[102:105], v[20:23], v[234:237], v[102:105]
	v_mfma_f32_16x16x32_bf16 v[98:101], v[142:145], v[234:237], v[98:101]
	v_mfma_f32_16x16x32_bf16 v[84:87], v[20:23], v[242:245], v[84:87]
	v_mfma_f32_16x16x32_bf16 v[80:83], v[142:145], v[242:245], v[80:83]
	s_setprio 0
	s_setprio 1
	v_mfma_f32_16x16x32_bf16 v[126:129], v[146:149], v[188:191], v[126:129]
	v_mfma_f32_16x16x32_bf16 v[122:125], v[180:183], v[188:191], v[122:125]
	v_mfma_f32_16x16x32_bf16 v[110:113], v[146:149], v[196:199], v[110:113]
	v_mfma_f32_16x16x32_bf16 v[106:109], v[180:183], v[196:199], v[106:109]
	v_mfma_f32_16x16x32_bf16 v[92:95], v[146:149], v[204:207], v[92:95]
	v_mfma_f32_16x16x32_bf16 v[88:91], v[180:183], v[204:207], v[88:91]
	v_mfma_f32_16x16x32_bf16 v[76:79], v[146:149], v[238:241], v[76:79]
	v_mfma_f32_16x16x32_bf16 v[72:75], v[180:183], v[238:241], v[72:75]
	v_mfma_f32_16x16x32_bf16 v[126:129], v[150:153], v[192:195], v[126:129]
	v_mfma_f32_16x16x32_bf16 v[122:125], v[184:187], v[192:195], v[122:125]
	v_mfma_f32_16x16x32_bf16 v[110:113], v[150:153], v[200:203], v[110:113]
	v_mfma_f32_16x16x32_bf16 v[106:109], v[184:187], v[200:203], v[106:109]
	v_mfma_f32_16x16x32_bf16 v[92:95], v[150:153], v[234:237], v[92:95]
	v_mfma_f32_16x16x32_bf16 v[88:91], v[184:187], v[234:237], v[88:91]
	v_mfma_f32_16x16x32_bf16 v[76:79], v[150:153], v[242:245], v[76:79]
	v_mfma_f32_16x16x32_bf16 v[72:75], v[184:187], v[242:245], v[72:75]
	s_setprio 0
	s_barrier
	s_add_i32 s14, s67, s58
	v_lshl_add_u64 v[170:171], v[170:171], 0, s[62:63]
	s_mov_b32 m0, s14
	ds_read_b128 v[188:191], v231 offset:49152
	ds_read_b128 v[192:195], v231 offset:50176
	ds_read_b128 v[196:199], v231 offset:51200
	ds_read_b128 v[200:203], v231 offset:52224
	ds_read_b128 v[204:207], v231 offset:53248
	ds_read_b128 v[234:237], v231 offset:54272
	ds_read_b128 v[238:241], v231 offset:55296
	ds_read_b128 v[242:245], v231 offset:56320
	global_load_lds_dwordx4 v[170:171], off
	s_add_i32 m0, s14, 0x2000
	s_add_u32 s12, s12, 0x10080
	v_lshl_add_u64 v[170:171], v[208:209], 0, s[62:63]
	s_addc_u32 s13, s13, 0
	s_add_i32 s14, s23, s58
	global_load_lds_dwordx4 v[170:171], off
	v_lshl_add_u64 v[170:171], s[12:13], 0, v[156:157]
	s_mov_b32 m0, s14
	s_nop 0
	global_load_lds_dwordx4 v[170:171], off
	v_lshl_add_u64 v[170:171], s[12:13], 0, v[160:161]
	s_add_i32 m0, s14, 0x2000
	s_nop 0
	global_load_lds_dwordx4 v[170:171], off
	v_lshl_add_u64 v[170:171], v[246:247], 0, s[62:63]
	s_mov_b32 m0, s96
	s_nop 0
	global_load_lds_dwordx4 v[170:171], off
	v_lshl_add_u64 v[170:171], v[248:249], 0, s[62:63]
	s_mov_b32 m0, s36
	s_nop 0
	global_load_lds_dwordx4 v[170:171], off
	s_waitcnt vmcnt(8)
	s_waitcnt lgkmcnt(0)
	s_barrier
	s_setprio 1
	s_waitcnt lgkmcnt(0)
	v_mfma_f32_16x16x32_bf16 v[68:71], v[16:19], v[188:191], v[68:71]
	v_mfma_f32_16x16x32_bf16 v[52:55], v[16:19], v[196:199], v[52:55]
	v_mfma_f32_16x16x32_bf16 v[36:39], v[16:19], v[204:207], v[36:39]
	v_mfma_f32_16x16x32_bf16 v[0:3], v[16:19], v[238:241], v[0:3]
	v_mfma_f32_16x16x32_bf16 v[68:71], v[20:23], v[192:195], v[68:71]
	v_mfma_f32_16x16x32_bf16 v[64:67], v[138:141], v[188:191], v[64:67]
	v_mfma_f32_16x16x32_bf16 v[52:55], v[20:23], v[200:203], v[52:55]
	v_mfma_f32_16x16x32_bf16 v[48:51], v[138:141], v[196:199], v[48:51]
	v_mfma_f32_16x16x32_bf16 v[36:39], v[20:23], v[234:237], v[36:39]
	v_mfma_f32_16x16x32_bf16 v[32:35], v[138:141], v[204:207], v[32:35]
	v_mfma_f32_16x16x32_bf16 v[20:23], v[20:23], v[242:245], v[0:3]
	v_mfma_f32_16x16x32_bf16 v[0:3], v[138:141], v[238:241], v[4:7]
	v_mfma_f32_16x16x32_bf16 v[64:67], v[142:145], v[192:195], v[64:67]
	v_mfma_f32_16x16x32_bf16 v[48:51], v[142:145], v[200:203], v[48:51]
	v_mfma_f32_16x16x32_bf16 v[32:35], v[142:145], v[234:237], v[32:35]
	v_mfma_f32_16x16x32_bf16 v[16:19], v[142:145], v[242:245], v[0:3]
	s_setprio 0
	s_setprio 1
	v_mfma_f32_16x16x32_bf16 v[0:3], v[146:149], v[188:191], v[60:63]
	v_mfma_f32_16x16x32_bf16 v[60:63], v[150:153], v[192:195], v[0:3]
	v_mfma_f32_16x16x32_bf16 v[0:3], v[180:183], v[188:191], v[56:59]
	v_mfma_f32_16x16x32_bf16 v[56:59], v[184:187], v[192:195], v[0:3]
	v_mfma_f32_16x16x32_bf16 v[0:3], v[146:149], v[196:199], v[44:47]
	v_mfma_f32_16x16x32_bf16 v[44:47], v[150:153], v[200:203], v[0:3]
	v_mfma_f32_16x16x32_bf16 v[0:3], v[180:183], v[196:199], v[40:43]
	v_mfma_f32_16x16x32_bf16 v[40:43], v[184:187], v[200:203], v[0:3]
	v_mfma_f32_16x16x32_bf16 v[0:3], v[146:149], v[204:207], v[28:31]
	v_mfma_f32_16x16x32_bf16 v[28:31], v[150:153], v[234:237], v[0:3]
	v_mfma_f32_16x16x32_bf16 v[0:3], v[180:183], v[204:207], v[24:27]
	v_mfma_f32_16x16x32_bf16 v[24:27], v[184:187], v[234:237], v[0:3]
	v_mfma_f32_16x16x32_bf16 v[0:3], v[146:149], v[238:241], v[12:15]
	v_mfma_f32_16x16x32_bf16 v[12:15], v[150:153], v[242:245], v[0:3]
	v_mfma_f32_16x16x32_bf16 v[0:3], v[180:183], v[238:241], v[8:11]
	v_mfma_f32_16x16x32_bf16 v[8:11], v[184:187], v[242:245], v[0:3]
	s_setprio 0
	s_barrier
	s_add_i32 s22, s22, 2
	s_add_u32 s2, s2, 0x100
	s_addc_u32 s3, s3, 0
	s_add_u32 s20, s20, 0x100
	s_addc_u32 s21, s21, 0
	.p2align 6

.Lfo_entry:
	s_lshr_b32 s14, s34, 3
	s_mul_i32 s14, s14, 0x3000
	s_add_u32 s16, s86, s14
	s_addc_u32 s17, s87, 0
	s_add_u32 s16, s16, 0x2000
	s_addc_u32 s17, s17, 0
	s_add_u32 s86, s88, s14
	s_addc_u32 s87, s89, 0
	s_add_u32 s86, s86, 0x1000
	s_addc_u32 s87, s87, 0
	v_lshl_add_u32 v171, v170, 1, v96
	v_lshl_add_u32 v171, v222, 11, v171
	v_lshlrev_b32_e32 v170, 2, v170
	s_lshl_b32 s14, s34, 8
	s_add_i32 s14, s14, s81
	s_lshl_b32 s12, s14, 11
	s_add_u32 s14, s2, s12
	s_addc_u32 s15, s3, 0
	s_add_u32 s78, s78, s12
	s_addc_u32 s79, s79, 0
	s_add_u32 s22, s78, 0x4000
	s_addc_u32 s23, s79, 0
	s_mov_b64 s[2:3], s[14:15]
	s_add_u32 s18, s14, 0x4000
	s_addc_u32 s19, s15, 0
	s_mov_b64 s[12:13], s[18:19]
	s_and_b64 vcc, exec, s[40:41]
	s_cbranch_vccz .Lfo_nong
	global_load_dwordx4 v[142:145], v170, s[16:17]
	global_load_dwordx4 v[150:153], v170, s[16:17] offset:16
	global_load_dwordx4 v[138:141], v170, s[16:17] offset:128
	global_load_dwordx4 v[146:149], v170, s[16:17] offset:144
	global_load_dwordx4 v[196:199], v171, s[14:15]
	global_load_dwordx4 v[200:203], v171, s[12:13]
	s_add_u32 s14, s14, 0x8000
	s_addc_u32 s15, s15, 0
	s_add_u32 s12, s12, 0x8000
	s_addc_u32 s13, s13, 0
	global_load_dwordx4 v[204:207], v171, s[14:15]
	global_load_dwordx4 v[234:237], v171, s[12:13]
	global_load_dwordx4 v[180:183], v170, s[86:87]
	global_load_dwordx4 v[184:187], v170, s[86:87] offset:16
	global_load_dwordx4 v[188:191], v170, s[86:87] offset:128
	global_load_dwordx4 v[192:195], v170, s[86:87] offset:144
	global_load_dwordx4 v[0:3], v170, s[26:27]
	global_load_dwordx4 v[4:7], v170, s[26:27] offset:16
	global_load_dwordx4 v[238:241], v170, s[26:27] offset:128
	global_load_dwordx4 v[242:245], v170, s[26:27] offset:144
	s_waitcnt vmcnt(0)
	v_pk_add_f32 v[182:183], v[182:183], 1.0 op_sel_hi:[1,0]
	v_pk_add_f32 v[180:181], v[180:181], 1.0 op_sel_hi:[1,0]
	v_pk_add_f32 v[186:187], v[186:187], 1.0 op_sel_hi:[1,0]
	v_pk_add_f32 v[184:185], v[184:185], 1.0 op_sel_hi:[1,0]
	v_pk_add_f32 v[190:191], v[190:191], 1.0 op_sel_hi:[1,0]
	v_pk_add_f32 v[188:189], v[188:189], 1.0 op_sel_hi:[1,0]
	v_pk_add_f32 v[194:195], v[194:195], 1.0 op_sel_hi:[1,0]
	v_pk_add_f32 v[192:193], v[192:193], 1.0 op_sel_hi:[1,0]
	v_pk_mul_f32 v[182:183], v[2:3], v[182:183]
	v_pk_mul_f32 v[180:181], v[0:1], v[180:181]
	v_pk_mul_f32 v[186:187], v[6:7], v[186:187]
	v_pk_mul_f32 v[184:185], v[4:5], v[184:185]
	v_pk_mul_f32 v[190:191], v[240:241], v[190:191]
	v_pk_mul_f32 v[188:189], v[238:239], v[188:189]
	v_pk_mul_f32 v[194:195], v[244:245], v[194:195]
	v_pk_mul_f32 v[192:193], v[242:243], v[192:193]
	s_add_u32 s14, s14, 0x8000
	s_addc_u32 s15, s15, 0
	s_add_u32 s12, s12, 0x8000
	s_addc_u32 s13, s13, 0
	global_load_dwordx4 v[238:241], v171, s[14:15]
	global_load_dwordx4 v[242:245], v171, s[12:13]
	s_waitcnt vmcnt(2)
	s_mov_b64 vcc, s[6:7]
	v_cndmask_b32_dpp v0, v200, v196, vcc row_ror:8 row_mask:0xf bank_mask:0xf
	v_cndmask_b32_dpp v1, v201, v197, vcc row_ror:8 row_mask:0xf bank_mask:0xf
	v_cndmask_b32_dpp v2, v202, v198, vcc row_ror:8 row_mask:0xf bank_mask:0xf
	v_cndmask_b32_dpp v3, v203, v199, vcc row_ror:8 row_mask:0xf bank_mask:0xf
	s_not_b64 vcc, s[6:7]
	v_cndmask_b32_dpp v4, v196, v200, vcc row_ror:8 row_mask:0xf bank_mask:0xf
	v_cndmask_b32_dpp v5, v197, v201, vcc row_ror:8 row_mask:0xf bank_mask:0xf
	v_cndmask_b32_dpp v6, v198, v202, vcc row_ror:8 row_mask:0xf bank_mask:0xf
	v_cndmask_b32_dpp v7, v199, v203, vcc row_ror:8 row_mask:0xf bank_mask:0xf
	s_add_u32 s14, s14, 0x8000
	s_addc_u32 s15, s15, 0
	s_add_u32 s12, s12, 0x8000
	s_addc_u32 s13, s13, 0
	global_load_dwordx4 v[196:199], v171, s[14:15]
	global_load_dwordx4 v[200:203], v171, s[12:13]
	v_lshlrev_b32_e32 v246, 16, v0
	v_and_b32_e32 v247, 0xffff0000, v0
	v_pk_fma_f32 v[134:135], v[134:135], v[142:143], v[246:247]
	v_lshlrev_b32_e32 v248, 16, v1
	v_and_b32_e32 v249, 0xffff0000, v1
	v_pk_fma_f32 v[136:137], v[136:137], v[144:145], v[248:249]
	v_lshlrev_b32_e32 v250, 16, v2
	v_and_b32_e32 v251, 0xffff0000, v2
	v_pk_fma_f32 v[130:131], v[130:131], v[150:151], v[250:251]
	v_lshlrev_b32_e32 v208, 16, v3
	v_and_b32_e32 v209, 0xffff0000, v3
	v_pk_fma_f32 v[132:133], v[132:133], v[152:153], v[208:209]
	v_lshlrev_b32_e32 v246, 16, v4
	v_and_b32_e32 v247, 0xffff0000, v4
	v_pk_fma_f32 v[126:127], v[126:127], v[138:139], v[246:247]
	v_lshlrev_b32_e32 v248, 16, v5
	v_and_b32_e32 v249, 0xffff0000, v5
	v_pk_fma_f32 v[128:129], v[128:129], v[140:141], v[248:249]
	v_lshlrev_b32_e32 v250, 16, v6
	v_and_b32_e32 v251, 0xffff0000, v6
	v_pk_fma_f32 v[122:123], v[122:123], v[146:147], v[250:251]
	v_lshlrev_b32_e32 v208, 16, v7
	v_and_b32_e32 v209, 0xffff0000, v7
	v_pk_fma_f32 v[124:125], v[124:125], v[148:149], v[208:209]
	v_cvt_pk_bf16_f32 v0, v134, v135
	v_cvt_pk_bf16_f32 v1, v136, v137
	v_cvt_pk_bf16_f32 v2, v130, v131
	v_cvt_pk_bf16_f32 v3, v132, v133
	v_cvt_pk_bf16_f32 v4, v126, v127
	v_cvt_pk_bf16_f32 v5, v128, v129
	v_cvt_pk_bf16_f32 v6, v122, v123
	v_cvt_pk_bf16_f32 v7, v124, v125
	v_mul_f32_e32 v246, v135, v135
	v_mul_f32_e32 v248, v137, v137
	v_fmac_f32_e32 v246, v134, v134
	v_fmac_f32_e32 v248, v136, v136
	v_add_f32_e32 v246, v246, v248
	v_mul_f32_e32 v248, v131, v131
	v_fmac_f32_e32 v248, v130, v130
	v_add_f32_e32 v246, v246, v248
	v_mul_f32_e32 v248, v133, v133
	v_fmac_f32_e32 v248, v132, v132
	v_add_f32_e32 v246, v248, v246
	v_mul_f32_e32 v247, v127, v127
	v_mul_f32_e32 v248, v129, v129
	v_fmac_f32_e32 v247, v126, v126
	v_fmac_f32_e32 v248, v128, v128
	v_add_f32_e32 v247, v247, v248
	v_mul_f32_e32 v248, v123, v123
	v_fmac_f32_e32 v248, v122, v122
	v_add_f32_e32 v247, v247, v248
	v_mul_f32_e32 v248, v125, v125
	v_fmac_f32_e32 v248, v124, v124
	v_add_f32_e32 v247, v248, v247
	v_add_f32_e32 v246, v246, v247
	v_mov_b32_e32 v247, v246
	s_nop 1
	v_permlane16_swap_b32_e32 v246, v247
	s_nop 1
	v_add_f32_e32 v246, v246, v247
	v_mov_b32_e32 v247, v246
	s_nop 1
	v_permlane32_swap_b32_e32 v246, v247
	v_add_u32_e32 v248, s8, v223
	s_nop 0
	v_add_f32_e32 v246, v246, v247
	s_mov_b64 exec, s[44:45]
	ds_write_b32 v248, v246
	s_mov_b64 exec, -1
	v_pk_mul_f32 v[134:135], v[180:181], v[134:135]
	v_pk_mul_f32 v[136:137], v[182:183], v[136:137]
	v_pk_mul_f32 v[130:131], v[184:185], v[130:131]
	v_pk_mul_f32 v[132:133], v[186:187], v[132:133]
	v_pk_mul_f32 v[126:127], v[188:189], v[126:127]
	v_pk_mul_f32 v[128:129], v[190:191], v[128:129]
	v_pk_mul_f32 v[122:123], v[192:193], v[122:123]
	v_pk_mul_f32 v[124:125], v[194:195], v[124:125]
	v_cvt_pk_bf16_f32 v246, v134, v135
	v_cvt_pk_bf16_f32 v247, v136, v137
	v_cvt_pk_bf16_f32 v248, v130, v131
	v_cvt_pk_bf16_f32 v249, v132, v133
	v_cvt_pk_bf16_f32 v250, v126, v127
	v_cvt_pk_bf16_f32 v251, v128, v129
	v_cvt_pk_bf16_f32 v208, v122, v123
	v_cvt_pk_bf16_f32 v209, v124, v125
	s_nop 1
	s_mov_b64 vcc, s[6:7]
	v_cndmask_b32_dpp v134, v4, v0, vcc row_ror:8 row_mask:0xf bank_mask:0xf
	v_cndmask_b32_dpp v135, v5, v1, vcc row_ror:8 row_mask:0xf bank_mask:0xf
	v_cndmask_b32_dpp v136, v6, v2, vcc row_ror:8 row_mask:0xf bank_mask:0xf
	v_cndmask_b32_dpp v137, v7, v3, vcc row_ror:8 row_mask:0xf bank_mask:0xf
	v_cndmask_b32_dpp v126, v250, v246, vcc row_ror:8 row_mask:0xf bank_mask:0xf
	v_cndmask_b32_dpp v127, v251, v247, vcc row_ror:8 row_mask:0xf bank_mask:0xf
	v_cndmask_b32_dpp v128, v208, v248, vcc row_ror:8 row_mask:0xf bank_mask:0xf
	v_cndmask_b32_dpp v129, v209, v249, vcc row_ror:8 row_mask:0xf bank_mask:0xf
	s_not_b64 vcc, s[6:7]
	v_cndmask_b32_dpp v130, v0, v4, vcc row_ror:8 row_mask:0xf bank_mask:0xf
	v_cndmask_b32_dpp v131, v1, v5, vcc row_ror:8 row_mask:0xf bank_mask:0xf
	v_cndmask_b32_dpp v132, v2, v6, vcc row_ror:8 row_mask:0xf bank_mask:0xf
	v_cndmask_b32_dpp v133, v3, v7, vcc row_ror:8 row_mask:0xf bank_mask:0xf
	v_cndmask_b32_dpp v122, v246, v250, vcc row_ror:8 row_mask:0xf bank_mask:0xf
	v_cndmask_b32_dpp v123, v247, v251, vcc row_ror:8 row_mask:0xf bank_mask:0xf
	v_cndmask_b32_dpp v124, v248, v208, vcc row_ror:8 row_mask:0xf bank_mask:0xf
	v_cndmask_b32_dpp v125, v249, v209, vcc row_ror:8 row_mask:0xf bank_mask:0xf
	global_store_dwordx4 v171, v[134:137], s[2:3]
	global_store_dwordx4 v171, v[130:133], s[18:19]
	global_store_dwordx4 v171, v[126:129], s[78:79]
	global_store_dwordx4 v171, v[122:125], s[22:23]
	s_waitcnt vmcnt(8)
	s_mov_b64 vcc, s[6:7]
	v_cndmask_b32_dpp v0, v234, v204, vcc row_ror:8 row_mask:0xf bank_mask:0xf
	v_cndmask_b32_dpp v1, v235, v205, vcc row_ror:8 row_mask:0xf bank_mask:0xf
	v_cndmask_b32_dpp v2, v236, v206, vcc row_ror:8 row_mask:0xf bank_mask:0xf
	v_cndmask_b32_dpp v3, v237, v207, vcc row_ror:8 row_mask:0xf bank_mask:0xf
	s_not_b64 vcc, s[6:7]
	v_cndmask_b32_dpp v4, v204, v234, vcc row_ror:8 row_mask:0xf bank_mask:0xf
	v_cndmask_b32_dpp v5, v205, v235, vcc row_ror:8 row_mask:0xf bank_mask:0xf
	v_cndmask_b32_dpp v6, v206, v236, vcc row_ror:8 row_mask:0xf bank_mask:0xf
	v_cndmask_b32_dpp v7, v207, v237, vcc row_ror:8 row_mask:0xf bank_mask:0xf
	s_add_u32 s14, s14, 0x28000
	s_addc_u32 s15, s15, 0
	s_add_u32 s12, s12, 0x28000
	s_addc_u32 s13, s13, 0
	global_load_dwordx4 v[204:207], v171, s[14:15]
	global_load_dwordx4 v[234:237], v171, s[12:13]
	v_lshlrev_b32_e32 v246, 16, v0
	v_and_b32_e32 v247, 0xffff0000, v0
	v_pk_fma_f32 v[118:119], v[118:119], v[142:143], v[246:247]
	v_lshlrev_b32_e32 v248, 16, v1
	v_and_b32_e32 v249, 0xffff0000, v1
	v_pk_fma_f32 v[120:121], v[120:121], v[144:145], v[248:249]
	v_lshlrev_b32_e32 v250, 16, v2
	v_and_b32_e32 v251, 0xffff0000, v2
	v_pk_fma_f32 v[114:115], v[114:115], v[150:151], v[250:251]
	v_lshlrev_b32_e32 v208, 16, v3
	v_and_b32_e32 v209, 0xffff0000, v3
	v_pk_fma_f32 v[116:117], v[116:117], v[152:153], v[208:209]
	v_lshlrev_b32_e32 v246, 16, v4
	v_and_b32_e32 v247, 0xffff0000, v4
	v_pk_fma_f32 v[110:111], v[110:111], v[138:139], v[246:247]
	v_lshlrev_b32_e32 v248, 16, v5
	v_and_b32_e32 v249, 0xffff0000, v5
	v_pk_fma_f32 v[112:113], v[112:113], v[140:141], v[248:249]
	v_lshlrev_b32_e32 v250, 16, v6
	v_and_b32_e32 v251, 0xffff0000, v6
	v_pk_fma_f32 v[106:107], v[106:107], v[146:147], v[250:251]
	v_lshlrev_b32_e32 v208, 16, v7
	v_and_b32_e32 v209, 0xffff0000, v7
	v_pk_fma_f32 v[108:109], v[108:109], v[148:149], v[208:209]
	v_cvt_pk_bf16_f32 v0, v118, v119
	v_cvt_pk_bf16_f32 v1, v120, v121
	v_cvt_pk_bf16_f32 v2, v114, v115
	v_cvt_pk_bf16_f32 v3, v116, v117
	v_cvt_pk_bf16_f32 v4, v110, v111
	v_cvt_pk_bf16_f32 v5, v112, v113
	v_cvt_pk_bf16_f32 v6, v106, v107
	v_cvt_pk_bf16_f32 v7, v108, v109
	v_mul_f32_e32 v246, v119, v119
	v_mul_f32_e32 v248, v121, v121
	v_fmac_f32_e32 v246, v118, v118
	v_fmac_f32_e32 v248, v120, v120
	v_add_f32_e32 v246, v246, v248
	v_mul_f32_e32 v248, v115, v115
	v_fmac_f32_e32 v248, v114, v114
	v_add_f32_e32 v246, v246, v248
	v_mul_f32_e32 v248, v117, v117
	v_fmac_f32_e32 v248, v116, v116
	v_add_f32_e32 v246, v248, v246
	v_mul_f32_e32 v247, v111, v111
	v_mul_f32_e32 v248, v113, v113
	v_fmac_f32_e32 v247, v110, v110
	v_fmac_f32_e32 v248, v112, v112
	v_add_f32_e32 v247, v247, v248
	v_mul_f32_e32 v248, v107, v107
	v_fmac_f32_e32 v248, v106, v106
	v_add_f32_e32 v247, v247, v248
	v_mul_f32_e32 v248, v109, v109
	v_fmac_f32_e32 v248, v108, v108
	v_add_f32_e32 v247, v248, v247
	v_add_f32_e32 v246, v246, v247
	v_mov_b32_e32 v247, v246
	s_nop 1
	v_permlane16_swap_b32_e32 v246, v247
	s_nop 1
	v_add_f32_e32 v246, v246, v247
	v_mov_b32_e32 v247, v246
	s_nop 1
	v_permlane32_swap_b32_e32 v246, v247
	v_add_u32_e32 v248, s8, v223
	s_nop 0
	v_add_f32_e32 v246, v246, v247
	s_mov_b64 exec, s[44:45]
	ds_write_b32 v248, v246 offset:256
	s_mov_b64 exec, -1
	v_pk_mul_f32 v[118:119], v[180:181], v[118:119]
	v_pk_mul_f32 v[120:121], v[182:183], v[120:121]
	v_pk_mul_f32 v[114:115], v[184:185], v[114:115]
	v_pk_mul_f32 v[116:117], v[186:187], v[116:117]
	v_pk_mul_f32 v[110:111], v[188:189], v[110:111]
	v_pk_mul_f32 v[112:113], v[190:191], v[112:113]
	v_pk_mul_f32 v[106:107], v[192:193], v[106:107]
	v_pk_mul_f32 v[108:109], v[194:195], v[108:109]
	v_cvt_pk_bf16_f32 v246, v118, v119
	v_cvt_pk_bf16_f32 v247, v120, v121
	v_cvt_pk_bf16_f32 v248, v114, v115
	v_cvt_pk_bf16_f32 v249, v116, v117
	v_cvt_pk_bf16_f32 v250, v110, v111
	v_cvt_pk_bf16_f32 v251, v112, v113
	v_cvt_pk_bf16_f32 v208, v106, v107
	v_cvt_pk_bf16_f32 v209, v108, v109
	s_add_u32 s2, s2, 0x8000
	s_addc_u32 s3, s3, 0
	s_add_u32 s18, s18, 0x8000
	s_addc_u32 s19, s19, 0
	s_add_u32 s78, s78, 0x8000
	s_addc_u32 s79, s79, 0
	s_add_u32 s22, s22, 0x8000
	s_addc_u32 s23, s23, 0
	s_mov_b64 vcc, s[6:7]
	v_cndmask_b32_dpp v118, v4, v0, vcc row_ror:8 row_mask:0xf bank_mask:0xf
	v_cndmask_b32_dpp v119, v5, v1, vcc row_ror:8 row_mask:0xf bank_mask:0xf
	v_cndmask_b32_dpp v120, v6, v2, vcc row_ror:8 row_mask:0xf bank_mask:0xf
	v_cndmask_b32_dpp v121, v7, v3, vcc row_ror:8 row_mask:0xf bank_mask:0xf
	v_cndmask_b32_dpp v110, v250, v246, vcc row_ror:8 row_mask:0xf bank_mask:0xf
	v_cndmask_b32_dpp v111, v251, v247, vcc row_ror:8 row_mask:0xf bank_mask:0xf
	v_cndmask_b32_dpp v112, v208, v248, vcc row_ror:8 row_mask:0xf bank_mask:0xf
	v_cndmask_b32_dpp v113, v209, v249, vcc row_ror:8 row_mask:0xf bank_mask:0xf
	s_not_b64 vcc, s[6:7]
	v_cndmask_b32_dpp v114, v0, v4, vcc row_ror:8 row_mask:0xf bank_mask:0xf
	v_cndmask_b32_dpp v115, v1, v5, vcc row_ror:8 row_mask:0xf bank_mask:0xf
	v_cndmask_b32_dpp v116, v2, v6, vcc row_ror:8 row_mask:0xf bank_mask:0xf
	v_cndmask_b32_dpp v117, v3, v7, vcc row_ror:8 row_mask:0xf bank_mask:0xf
	v_cndmask_b32_dpp v106, v246, v250, vcc row_ror:8 row_mask:0xf bank_mask:0xf
	v_cndmask_b32_dpp v107, v247, v251, vcc row_ror:8 row_mask:0xf bank_mask:0xf
	v_cndmask_b32_dpp v108, v248, v208, vcc row_ror:8 row_mask:0xf bank_mask:0xf
	v_cndmask_b32_dpp v109, v249, v209, vcc row_ror:8 row_mask:0xf bank_mask:0xf
	global_store_dwordx4 v171, v[118:121], s[2:3]
	global_store_dwordx4 v171, v[114:117], s[18:19]
	global_store_dwordx4 v171, v[110:113], s[78:79]
	global_store_dwordx4 v171, v[106:109], s[22:23]
	s_waitcnt vmcnt(12)
	s_mov_b64 vcc, s[6:7]
	v_cndmask_b32_dpp v0, v242, v238, vcc row_ror:8 row_mask:0xf bank_mask:0xf
	v_cndmask_b32_dpp v1, v243, v239, vcc row_ror:8 row_mask:0xf bank_mask:0xf
	v_cndmask_b32_dpp v2, v244, v240, vcc row_ror:8 row_mask:0xf bank_mask:0xf
	v_cndmask_b32_dpp v3, v245, v241, vcc row_ror:8 row_mask:0xf bank_mask:0xf
	s_not_b64 vcc, s[6:7]
	v_cndmask_b32_dpp v4, v238, v242, vcc row_ror:8 row_mask:0xf bank_mask:0xf
	v_cndmask_b32_dpp v5, v239, v243, vcc row_ror:8 row_mask:0xf bank_mask:0xf
	v_cndmask_b32_dpp v6, v240, v244, vcc row_ror:8 row_mask:0xf bank_mask:0xf
	v_cndmask_b32_dpp v7, v241, v245, vcc row_ror:8 row_mask:0xf bank_mask:0xf
	s_add_u32 s14, s14, 0x8000
	s_addc_u32 s15, s15, 0
	s_add_u32 s12, s12, 0x8000
	s_addc_u32 s13, s13, 0
	global_load_dwordx4 v[238:241], v171, s[14:15]
	global_load_dwordx4 v[242:245], v171, s[12:13]
	v_lshlrev_b32_e32 v246, 16, v0
	v_and_b32_e32 v247, 0xffff0000, v0
	v_pk_fma_f32 v[102:103], v[102:103], v[142:143], v[246:247]
	v_lshlrev_b32_e32 v248, 16, v1
	v_and_b32_e32 v249, 0xffff0000, v1
	v_pk_fma_f32 v[104:105], v[104:105], v[144:145], v[248:249]
	v_lshlrev_b32_e32 v250, 16, v2
	v_and_b32_e32 v251, 0xffff0000, v2
	v_pk_fma_f32 v[98:99], v[98:99], v[150:151], v[250:251]
	v_lshlrev_b32_e32 v208, 16, v3
	v_and_b32_e32 v209, 0xffff0000, v3
	v_pk_fma_f32 v[100:101], v[100:101], v[152:153], v[208:209]
	v_lshlrev_b32_e32 v246, 16, v4
	v_and_b32_e32 v247, 0xffff0000, v4
	v_pk_fma_f32 v[92:93], v[92:93], v[138:139], v[246:247]
	v_lshlrev_b32_e32 v248, 16, v5
	v_and_b32_e32 v249, 0xffff0000, v5
	v_pk_fma_f32 v[94:95], v[94:95], v[140:141], v[248:249]
	v_lshlrev_b32_e32 v250, 16, v6
	v_and_b32_e32 v251, 0xffff0000, v6
	v_pk_fma_f32 v[88:89], v[88:89], v[146:147], v[250:251]
	v_lshlrev_b32_e32 v208, 16, v7
	v_and_b32_e32 v209, 0xffff0000, v7
	v_pk_fma_f32 v[90:91], v[90:91], v[148:149], v[208:209]
	v_cvt_pk_bf16_f32 v0, v102, v103
	v_cvt_pk_bf16_f32 v1, v104, v105
	v_cvt_pk_bf16_f32 v2, v98, v99
	v_cvt_pk_bf16_f32 v3, v100, v101
	v_cvt_pk_bf16_f32 v4, v92, v93
	v_cvt_pk_bf16_f32 v5, v94, v95
	v_cvt_pk_bf16_f32 v6, v88, v89
	v_cvt_pk_bf16_f32 v7, v90, v91
	v_mul_f32_e32 v246, v103, v103
	v_mul_f32_e32 v248, v105, v105
	v_fmac_f32_e32 v246, v102, v102
	v_fmac_f32_e32 v248, v104, v104
	v_add_f32_e32 v246, v246, v248
	v_mul_f32_e32 v248, v99, v99
	v_fmac_f32_e32 v248, v98, v98
	v_add_f32_e32 v246, v246, v248
	v_mul_f32_e32 v248, v101, v101
	v_fmac_f32_e32 v248, v100, v100
	v_add_f32_e32 v246, v248, v246
	v_mul_f32_e32 v247, v93, v93
	v_mul_f32_e32 v248, v95, v95
	v_fmac_f32_e32 v247, v92, v92
	v_fmac_f32_e32 v248, v94, v94
	v_add_f32_e32 v247, v247, v248
	v_mul_f32_e32 v248, v89, v89
	v_fmac_f32_e32 v248, v88, v88
	v_add_f32_e32 v247, v247, v248
	v_mul_f32_e32 v248, v91, v91
	v_fmac_f32_e32 v248, v90, v90
	v_add_f32_e32 v247, v248, v247
	v_add_f32_e32 v246, v246, v247
	v_mov_b32_e32 v247, v246
	s_nop 1
	v_permlane16_swap_b32_e32 v246, v247
	s_nop 1
	v_add_f32_e32 v246, v246, v247
	v_mov_b32_e32 v247, v246
	s_nop 1
	v_permlane32_swap_b32_e32 v246, v247
	v_add_u32_e32 v248, s8, v223
	s_nop 0
	v_add_f32_e32 v246, v246, v247
	s_mov_b64 exec, s[44:45]
	ds_write_b32 v248, v246 offset:512
	s_mov_b64 exec, -1
	v_pk_mul_f32 v[102:103], v[180:181], v[102:103]
	v_pk_mul_f32 v[104:105], v[182:183], v[104:105]
	v_pk_mul_f32 v[98:99], v[184:185], v[98:99]
	v_pk_mul_f32 v[100:101], v[186:187], v[100:101]
	v_pk_mul_f32 v[92:93], v[188:189], v[92:93]
	v_pk_mul_f32 v[94:95], v[190:191], v[94:95]
	v_pk_mul_f32 v[88:89], v[192:193], v[88:89]
	v_pk_mul_f32 v[90:91], v[194:195], v[90:91]
	v_cvt_pk_bf16_f32 v246, v102, v103
	v_cvt_pk_bf16_f32 v247, v104, v105
	v_cvt_pk_bf16_f32 v248, v98, v99
	v_cvt_pk_bf16_f32 v249, v100, v101
	v_cvt_pk_bf16_f32 v250, v92, v93
	v_cvt_pk_bf16_f32 v251, v94, v95
	v_cvt_pk_bf16_f32 v208, v88, v89
	v_cvt_pk_bf16_f32 v209, v90, v91
	s_add_u32 s2, s2, 0x8000
	s_addc_u32 s3, s3, 0
	s_add_u32 s18, s18, 0x8000
	s_addc_u32 s19, s19, 0
	s_add_u32 s78, s78, 0x8000
	s_addc_u32 s79, s79, 0
	s_add_u32 s22, s22, 0x8000
	s_addc_u32 s23, s23, 0
	s_mov_b64 vcc, s[6:7]
	v_cndmask_b32_dpp v102, v4, v0, vcc row_ror:8 row_mask:0xf bank_mask:0xf
	v_cndmask_b32_dpp v103, v5, v1, vcc row_ror:8 row_mask:0xf bank_mask:0xf
	v_cndmask_b32_dpp v104, v6, v2, vcc row_ror:8 row_mask:0xf bank_mask:0xf
	v_cndmask_b32_dpp v105, v7, v3, vcc row_ror:8 row_mask:0xf bank_mask:0xf
	v_cndmask_b32_dpp v92, v250, v246, vcc row_ror:8 row_mask:0xf bank_mask:0xf
	v_cndmask_b32_dpp v93, v251, v247, vcc row_ror:8 row_mask:0xf bank_mask:0xf
	v_cndmask_b32_dpp v94, v208, v248, vcc row_ror:8 row_mask:0xf bank_mask:0xf
	v_cndmask_b32_dpp v95, v209, v249, vcc row_ror:8 row_mask:0xf bank_mask:0xf
	s_not_b64 vcc, s[6:7]
	v_cndmask_b32_dpp v98, v0, v4, vcc row_ror:8 row_mask:0xf bank_mask:0xf
	v_cndmask_b32_dpp v99, v1, v5, vcc row_ror:8 row_mask:0xf bank_mask:0xf
	v_cndmask_b32_dpp v100, v2, v6, vcc row_ror:8 row_mask:0xf bank_mask:0xf
	v_cndmask_b32_dpp v101, v3, v7, vcc row_ror:8 row_mask:0xf bank_mask:0xf
	v_cndmask_b32_dpp v88, v246, v250, vcc row_ror:8 row_mask:0xf bank_mask:0xf
	v_cndmask_b32_dpp v89, v247, v251, vcc row_ror:8 row_mask:0xf bank_mask:0xf
	v_cndmask_b32_dpp v90, v248, v208, vcc row_ror:8 row_mask:0xf bank_mask:0xf
	v_cndmask_b32_dpp v91, v249, v209, vcc row_ror:8 row_mask:0xf bank_mask:0xf
	global_store_dwordx4 v171, v[102:105], s[2:3]
	global_store_dwordx4 v171, v[98:101], s[18:19]
	global_store_dwordx4 v171, v[92:95], s[78:79]
	global_store_dwordx4 v171, v[88:91], s[22:23]
	s_waitcnt vmcnt(16)
	s_mov_b64 vcc, s[6:7]
	v_cndmask_b32_dpp v0, v200, v196, vcc row_ror:8 row_mask:0xf bank_mask:0xf
	v_cndmask_b32_dpp v1, v201, v197, vcc row_ror:8 row_mask:0xf bank_mask:0xf
	v_cndmask_b32_dpp v2, v202, v198, vcc row_ror:8 row_mask:0xf bank_mask:0xf
	v_cndmask_b32_dpp v3, v203, v199, vcc row_ror:8 row_mask:0xf bank_mask:0xf
	s_not_b64 vcc, s[6:7]
	v_cndmask_b32_dpp v4, v196, v200, vcc row_ror:8 row_mask:0xf bank_mask:0xf
	v_cndmask_b32_dpp v5, v197, v201, vcc row_ror:8 row_mask:0xf bank_mask:0xf
	v_cndmask_b32_dpp v6, v198, v202, vcc row_ror:8 row_mask:0xf bank_mask:0xf
	v_cndmask_b32_dpp v7, v199, v203, vcc row_ror:8 row_mask:0xf bank_mask:0xf
	s_add_u32 s14, s14, 0x8000
	s_addc_u32 s15, s15, 0
	s_add_u32 s12, s12, 0x8000
	s_addc_u32 s13, s13, 0
	global_load_dwordx4 v[196:199], v171, s[14:15]
	global_load_dwordx4 v[200:203], v171, s[12:13]
	v_lshlrev_b32_e32 v246, 16, v0
	v_and_b32_e32 v247, 0xffff0000, v0
	v_pk_fma_f32 v[84:85], v[84:85], v[142:143], v[246:247]
	v_lshlrev_b32_e32 v248, 16, v1
	v_and_b32_e32 v249, 0xffff0000, v1
	v_pk_fma_f32 v[86:87], v[86:87], v[144:145], v[248:249]
	v_lshlrev_b32_e32 v250, 16, v2
	v_and_b32_e32 v251, 0xffff0000, v2
	v_pk_fma_f32 v[80:81], v[80:81], v[150:151], v[250:251]
	v_lshlrev_b32_e32 v208, 16, v3
	v_and_b32_e32 v209, 0xffff0000, v3
	v_pk_fma_f32 v[82:83], v[82:83], v[152:153], v[208:209]
	v_lshlrev_b32_e32 v246, 16, v4
	v_and_b32_e32 v247, 0xffff0000, v4
	v_pk_fma_f32 v[76:77], v[76:77], v[138:139], v[246:247]
	v_lshlrev_b32_e32 v248, 16, v5
	v_and_b32_e32 v249, 0xffff0000, v5
	v_pk_fma_f32 v[78:79], v[78:79], v[140:141], v[248:249]
	v_lshlrev_b32_e32 v250, 16, v6
	v_and_b32_e32 v251, 0xffff0000, v6
	v_pk_fma_f32 v[72:73], v[72:73], v[146:147], v[250:251]
	v_lshlrev_b32_e32 v208, 16, v7
	v_and_b32_e32 v209, 0xffff0000, v7
	v_pk_fma_f32 v[74:75], v[74:75], v[148:149], v[208:209]
	v_cvt_pk_bf16_f32 v0, v84, v85
	v_cvt_pk_bf16_f32 v1, v86, v87
	v_cvt_pk_bf16_f32 v2, v80, v81
	v_cvt_pk_bf16_f32 v3, v82, v83
	v_cvt_pk_bf16_f32 v4, v76, v77
	v_cvt_pk_bf16_f32 v5, v78, v79
	v_cvt_pk_bf16_f32 v6, v72, v73
	v_cvt_pk_bf16_f32 v7, v74, v75
	v_mul_f32_e32 v246, v85, v85
	v_mul_f32_e32 v248, v87, v87
	v_fmac_f32_e32 v246, v84, v84
	v_fmac_f32_e32 v248, v86, v86
	v_add_f32_e32 v246, v246, v248
	v_mul_f32_e32 v248, v81, v81
	v_fmac_f32_e32 v248, v80, v80
	v_add_f32_e32 v246, v246, v248
	v_mul_f32_e32 v248, v83, v83
	v_fmac_f32_e32 v248, v82, v82
	v_add_f32_e32 v246, v248, v246
	v_mul_f32_e32 v247, v77, v77
	v_mul_f32_e32 v248, v79, v79
	v_fmac_f32_e32 v247, v76, v76
	v_fmac_f32_e32 v248, v78, v78
	v_add_f32_e32 v247, v247, v248
	v_mul_f32_e32 v248, v73, v73
	v_fmac_f32_e32 v248, v72, v72
	v_add_f32_e32 v247, v247, v248
	v_mul_f32_e32 v248, v75, v75
	v_fmac_f32_e32 v248, v74, v74
	v_add_f32_e32 v247, v248, v247
	v_add_f32_e32 v246, v246, v247
	v_mov_b32_e32 v247, v246
	s_nop 1
	v_permlane16_swap_b32_e32 v246, v247
	s_nop 1
	v_add_f32_e32 v246, v246, v247
	v_mov_b32_e32 v247, v246
	s_nop 1
	v_permlane32_swap_b32_e32 v246, v247
	v_add_u32_e32 v248, s8, v223
	s_nop 0
	v_add_f32_e32 v246, v246, v247
	s_mov_b64 exec, s[44:45]
	ds_write_b32 v248, v246 offset:768
	s_mov_b64 exec, -1
	v_pk_mul_f32 v[84:85], v[180:181], v[84:85]
	v_pk_mul_f32 v[86:87], v[182:183], v[86:87]
	v_pk_mul_f32 v[80:81], v[184:185], v[80:81]
	v_pk_mul_f32 v[82:83], v[186:187], v[82:83]
	v_pk_mul_f32 v[76:77], v[188:189], v[76:77]
	v_pk_mul_f32 v[78:79], v[190:191], v[78:79]
	v_pk_mul_f32 v[72:73], v[192:193], v[72:73]
	v_pk_mul_f32 v[74:75], v[194:195], v[74:75]
	v_cvt_pk_bf16_f32 v246, v84, v85
	v_cvt_pk_bf16_f32 v247, v86, v87
	v_cvt_pk_bf16_f32 v248, v80, v81
	v_cvt_pk_bf16_f32 v249, v82, v83
	v_cvt_pk_bf16_f32 v250, v76, v77
	v_cvt_pk_bf16_f32 v251, v78, v79
	v_cvt_pk_bf16_f32 v208, v72, v73
	v_cvt_pk_bf16_f32 v209, v74, v75
	s_add_u32 s2, s2, 0x8000
	s_addc_u32 s3, s3, 0
	s_add_u32 s18, s18, 0x8000
	s_addc_u32 s19, s19, 0
	s_add_u32 s78, s78, 0x8000
	s_addc_u32 s79, s79, 0
	s_add_u32 s22, s22, 0x8000
	s_addc_u32 s23, s23, 0
	s_mov_b64 vcc, s[6:7]
	v_cndmask_b32_dpp v84, v4, v0, vcc row_ror:8 row_mask:0xf bank_mask:0xf
	v_cndmask_b32_dpp v85, v5, v1, vcc row_ror:8 row_mask:0xf bank_mask:0xf
	v_cndmask_b32_dpp v86, v6, v2, vcc row_ror:8 row_mask:0xf bank_mask:0xf
	v_cndmask_b32_dpp v87, v7, v3, vcc row_ror:8 row_mask:0xf bank_mask:0xf
	v_cndmask_b32_dpp v76, v250, v246, vcc row_ror:8 row_mask:0xf bank_mask:0xf
	v_cndmask_b32_dpp v77, v251, v247, vcc row_ror:8 row_mask:0xf bank_mask:0xf
	v_cndmask_b32_dpp v78, v208, v248, vcc row_ror:8 row_mask:0xf bank_mask:0xf
	v_cndmask_b32_dpp v79, v209, v249, vcc row_ror:8 row_mask:0xf bank_mask:0xf
	s_not_b64 vcc, s[6:7]
	v_cndmask_b32_dpp v80, v0, v4, vcc row_ror:8 row_mask:0xf bank_mask:0xf
	v_cndmask_b32_dpp v81, v1, v5, vcc row_ror:8 row_mask:0xf bank_mask:0xf
	v_cndmask_b32_dpp v82, v2, v6, vcc row_ror:8 row_mask:0xf bank_mask:0xf
	v_cndmask_b32_dpp v83, v3, v7, vcc row_ror:8 row_mask:0xf bank_mask:0xf
	v_cndmask_b32_dpp v72, v246, v250, vcc row_ror:8 row_mask:0xf bank_mask:0xf
	v_cndmask_b32_dpp v73, v247, v251, vcc row_ror:8 row_mask:0xf bank_mask:0xf
	v_cndmask_b32_dpp v74, v248, v208, vcc row_ror:8 row_mask:0xf bank_mask:0xf
	v_cndmask_b32_dpp v75, v249, v209, vcc row_ror:8 row_mask:0xf bank_mask:0xf
	global_store_dwordx4 v171, v[84:87], s[2:3]
	global_store_dwordx4 v171, v[80:83], s[18:19]
	global_store_dwordx4 v171, v[76:79], s[78:79]
	global_store_dwordx4 v171, v[72:75], s[22:23]
	s_waitcnt vmcnt(16)
	s_mov_b64 vcc, s[6:7]
	v_cndmask_b32_dpp v0, v234, v204, vcc row_ror:8 row_mask:0xf bank_mask:0xf
	v_cndmask_b32_dpp v1, v235, v205, vcc row_ror:8 row_mask:0xf bank_mask:0xf
	v_cndmask_b32_dpp v2, v236, v206, vcc row_ror:8 row_mask:0xf bank_mask:0xf
	v_cndmask_b32_dpp v3, v237, v207, vcc row_ror:8 row_mask:0xf bank_mask:0xf
	s_not_b64 vcc, s[6:7]
	v_cndmask_b32_dpp v4, v204, v234, vcc row_ror:8 row_mask:0xf bank_mask:0xf
	v_cndmask_b32_dpp v5, v205, v235, vcc row_ror:8 row_mask:0xf bank_mask:0xf
	v_cndmask_b32_dpp v6, v206, v236, vcc row_ror:8 row_mask:0xf bank_mask:0xf
	v_cndmask_b32_dpp v7, v207, v237, vcc row_ror:8 row_mask:0xf bank_mask:0xf
	s_add_u32 s14, s14, 0x8000
	s_addc_u32 s15, s15, 0
	s_add_u32 s12, s12, 0x8000
	s_addc_u32 s13, s13, 0
	global_load_dwordx4 v[204:207], v171, s[14:15]
	global_load_dwordx4 v[234:237], v171, s[12:13]
	v_lshlrev_b32_e32 v246, 16, v0
	v_and_b32_e32 v247, 0xffff0000, v0
	v_pk_fma_f32 v[68:69], v[68:69], v[142:143], v[246:247]
	v_lshlrev_b32_e32 v248, 16, v1
	v_and_b32_e32 v249, 0xffff0000, v1
	v_pk_fma_f32 v[70:71], v[70:71], v[144:145], v[248:249]
	v_lshlrev_b32_e32 v250, 16, v2
	v_and_b32_e32 v251, 0xffff0000, v2
	v_pk_fma_f32 v[64:65], v[64:65], v[150:151], v[250:251]
	v_lshlrev_b32_e32 v208, 16, v3
	v_and_b32_e32 v209, 0xffff0000, v3
	v_pk_fma_f32 v[66:67], v[66:67], v[152:153], v[208:209]
	v_lshlrev_b32_e32 v246, 16, v4
	v_and_b32_e32 v247, 0xffff0000, v4
	v_pk_fma_f32 v[60:61], v[60:61], v[138:139], v[246:247]
	v_lshlrev_b32_e32 v248, 16, v5
	v_and_b32_e32 v249, 0xffff0000, v5
	v_pk_fma_f32 v[62:63], v[62:63], v[140:141], v[248:249]
	v_lshlrev_b32_e32 v250, 16, v6
	v_and_b32_e32 v251, 0xffff0000, v6
	v_pk_fma_f32 v[56:57], v[56:57], v[146:147], v[250:251]
	v_lshlrev_b32_e32 v208, 16, v7
	v_and_b32_e32 v209, 0xffff0000, v7
	v_pk_fma_f32 v[58:59], v[58:59], v[148:149], v[208:209]
	v_cvt_pk_bf16_f32 v0, v68, v69
	v_cvt_pk_bf16_f32 v1, v70, v71
	v_cvt_pk_bf16_f32 v2, v64, v65
	v_cvt_pk_bf16_f32 v3, v66, v67
	v_cvt_pk_bf16_f32 v4, v60, v61
	v_cvt_pk_bf16_f32 v5, v62, v63
	v_cvt_pk_bf16_f32 v6, v56, v57
	v_cvt_pk_bf16_f32 v7, v58, v59
	v_mul_f32_e32 v246, v69, v69
	v_mul_f32_e32 v248, v71, v71
	v_fmac_f32_e32 v246, v68, v68
	v_fmac_f32_e32 v248, v70, v70
	v_add_f32_e32 v246, v246, v248
	v_mul_f32_e32 v248, v65, v65
	v_fmac_f32_e32 v248, v64, v64
	v_add_f32_e32 v246, v246, v248
	v_mul_f32_e32 v248, v67, v67
	v_fmac_f32_e32 v248, v66, v66
	v_add_f32_e32 v246, v248, v246
	v_mul_f32_e32 v247, v61, v61
	v_mul_f32_e32 v248, v63, v63
	v_fmac_f32_e32 v247, v60, v60
	v_fmac_f32_e32 v248, v62, v62
	v_add_f32_e32 v247, v247, v248
	v_mul_f32_e32 v248, v57, v57
	v_fmac_f32_e32 v248, v56, v56
	v_add_f32_e32 v247, v247, v248
	v_mul_f32_e32 v248, v59, v59
	v_fmac_f32_e32 v248, v58, v58
	v_add_f32_e32 v247, v248, v247
	v_add_f32_e32 v246, v246, v247
	v_mov_b32_e32 v247, v246
	s_nop 1
	v_permlane16_swap_b32_e32 v246, v247
	s_nop 1
	v_add_f32_e32 v246, v246, v247
	v_mov_b32_e32 v247, v246
	s_nop 1
	v_permlane32_swap_b32_e32 v246, v247
	v_add_u32_e32 v248, s8, v223
	s_nop 0
	v_add_f32_e32 v246, v246, v247
	s_mov_b64 exec, s[44:45]
	ds_write_b32 v248, v246 offset:2048
	s_mov_b64 exec, -1
	v_pk_mul_f32 v[68:69], v[180:181], v[68:69]
	v_pk_mul_f32 v[70:71], v[182:183], v[70:71]
	v_pk_mul_f32 v[64:65], v[184:185], v[64:65]
	v_pk_mul_f32 v[66:67], v[186:187], v[66:67]
	v_pk_mul_f32 v[60:61], v[188:189], v[60:61]
	v_pk_mul_f32 v[62:63], v[190:191], v[62:63]
	v_pk_mul_f32 v[56:57], v[192:193], v[56:57]
	v_pk_mul_f32 v[58:59], v[194:195], v[58:59]
	v_cvt_pk_bf16_f32 v246, v68, v69
	v_cvt_pk_bf16_f32 v247, v70, v71
	v_cvt_pk_bf16_f32 v248, v64, v65
	v_cvt_pk_bf16_f32 v249, v66, v67
	v_cvt_pk_bf16_f32 v250, v60, v61
	v_cvt_pk_bf16_f32 v251, v62, v63
	v_cvt_pk_bf16_f32 v208, v56, v57
	v_cvt_pk_bf16_f32 v209, v58, v59
	s_add_u32 s2, s2, 0x28000
	s_addc_u32 s3, s3, 0
	s_add_u32 s18, s18, 0x28000
	s_addc_u32 s19, s19, 0
	s_add_u32 s78, s78, 0x28000
	s_addc_u32 s79, s79, 0
	s_add_u32 s22, s22, 0x28000
	s_addc_u32 s23, s23, 0
	s_mov_b64 vcc, s[6:7]
	v_cndmask_b32_dpp v68, v4, v0, vcc row_ror:8 row_mask:0xf bank_mask:0xf
	v_cndmask_b32_dpp v69, v5, v1, vcc row_ror:8 row_mask:0xf bank_mask:0xf
	v_cndmask_b32_dpp v70, v6, v2, vcc row_ror:8 row_mask:0xf bank_mask:0xf
	v_cndmask_b32_dpp v71, v7, v3, vcc row_ror:8 row_mask:0xf bank_mask:0xf
	v_cndmask_b32_dpp v60, v250, v246, vcc row_ror:8 row_mask:0xf bank_mask:0xf
	v_cndmask_b32_dpp v61, v251, v247, vcc row_ror:8 row_mask:0xf bank_mask:0xf
	v_cndmask_b32_dpp v62, v208, v248, vcc row_ror:8 row_mask:0xf bank_mask:0xf
	v_cndmask_b32_dpp v63, v209, v249, vcc row_ror:8 row_mask:0xf bank_mask:0xf
	s_not_b64 vcc, s[6:7]
	v_cndmask_b32_dpp v64, v0, v4, vcc row_ror:8 row_mask:0xf bank_mask:0xf
	v_cndmask_b32_dpp v65, v1, v5, vcc row_ror:8 row_mask:0xf bank_mask:0xf
	v_cndmask_b32_dpp v66, v2, v6, vcc row_ror:8 row_mask:0xf bank_mask:0xf
	v_cndmask_b32_dpp v67, v3, v7, vcc row_ror:8 row_mask:0xf bank_mask:0xf
	v_cndmask_b32_dpp v56, v246, v250, vcc row_ror:8 row_mask:0xf bank_mask:0xf
	v_cndmask_b32_dpp v57, v247, v251, vcc row_ror:8 row_mask:0xf bank_mask:0xf
	v_cndmask_b32_dpp v58, v248, v208, vcc row_ror:8 row_mask:0xf bank_mask:0xf
	v_cndmask_b32_dpp v59, v249, v209, vcc row_ror:8 row_mask:0xf bank_mask:0xf
	global_store_dwordx4 v171, v[68:71], s[2:3]
	global_store_dwordx4 v171, v[64:67], s[18:19]
	global_store_dwordx4 v171, v[60:63], s[78:79]
	global_store_dwordx4 v171, v[56:59], s[22:23]
	s_waitcnt vmcnt(16)
	s_mov_b64 vcc, s[6:7]
	v_cndmask_b32_dpp v0, v242, v238, vcc row_ror:8 row_mask:0xf bank_mask:0xf
	v_cndmask_b32_dpp v1, v243, v239, vcc row_ror:8 row_mask:0xf bank_mask:0xf
	v_cndmask_b32_dpp v2, v244, v240, vcc row_ror:8 row_mask:0xf bank_mask:0xf
	v_cndmask_b32_dpp v3, v245, v241, vcc row_ror:8 row_mask:0xf bank_mask:0xf
	s_not_b64 vcc, s[6:7]
	v_cndmask_b32_dpp v4, v238, v242, vcc row_ror:8 row_mask:0xf bank_mask:0xf
	v_cndmask_b32_dpp v5, v239, v243, vcc row_ror:8 row_mask:0xf bank_mask:0xf
	v_cndmask_b32_dpp v6, v240, v244, vcc row_ror:8 row_mask:0xf bank_mask:0xf
	v_cndmask_b32_dpp v7, v241, v245, vcc row_ror:8 row_mask:0xf bank_mask:0xf
	v_lshlrev_b32_e32 v246, 16, v0
	v_and_b32_e32 v247, 0xffff0000, v0
	v_pk_fma_f32 v[52:53], v[52:53], v[142:143], v[246:247]
	v_lshlrev_b32_e32 v248, 16, v1
	v_and_b32_e32 v249, 0xffff0000, v1
	v_pk_fma_f32 v[54:55], v[54:55], v[144:145], v[248:249]
	v_lshlrev_b32_e32 v250, 16, v2
	v_and_b32_e32 v251, 0xffff0000, v2
	v_pk_fma_f32 v[48:49], v[48:49], v[150:151], v[250:251]
	v_lshlrev_b32_e32 v208, 16, v3
	v_and_b32_e32 v209, 0xffff0000, v3
	v_pk_fma_f32 v[50:51], v[50:51], v[152:153], v[208:209]
	v_lshlrev_b32_e32 v246, 16, v4
	v_and_b32_e32 v247, 0xffff0000, v4
	v_pk_fma_f32 v[44:45], v[44:45], v[138:139], v[246:247]
	v_lshlrev_b32_e32 v248, 16, v5
	v_and_b32_e32 v249, 0xffff0000, v5
	v_pk_fma_f32 v[46:47], v[46:47], v[140:141], v[248:249]
	v_lshlrev_b32_e32 v250, 16, v6
	v_and_b32_e32 v251, 0xffff0000, v6
	v_pk_fma_f32 v[40:41], v[40:41], v[146:147], v[250:251]
	v_lshlrev_b32_e32 v208, 16, v7
	v_and_b32_e32 v209, 0xffff0000, v7
	v_pk_fma_f32 v[42:43], v[42:43], v[148:149], v[208:209]
	v_cvt_pk_bf16_f32 v0, v52, v53
	v_cvt_pk_bf16_f32 v1, v54, v55
	v_cvt_pk_bf16_f32 v2, v48, v49
	v_cvt_pk_bf16_f32 v3, v50, v51
	v_cvt_pk_bf16_f32 v4, v44, v45
	v_cvt_pk_bf16_f32 v5, v46, v47
	v_cvt_pk_bf16_f32 v6, v40, v41
	v_cvt_pk_bf16_f32 v7, v42, v43
	v_mul_f32_e32 v246, v53, v53
	v_mul_f32_e32 v248, v55, v55
	v_fmac_f32_e32 v246, v52, v52
	v_fmac_f32_e32 v248, v54, v54
	v_add_f32_e32 v246, v246, v248
	v_mul_f32_e32 v248, v49, v49
	v_fmac_f32_e32 v248, v48, v48
	v_add_f32_e32 v246, v246, v248
	v_mul_f32_e32 v248, v51, v51
	v_fmac_f32_e32 v248, v50, v50
	v_add_f32_e32 v246, v248, v246
	v_mul_f32_e32 v247, v45, v45
	v_mul_f32_e32 v248, v47, v47
	v_fmac_f32_e32 v247, v44, v44
	v_fmac_f32_e32 v248, v46, v46
	v_add_f32_e32 v247, v247, v248
	v_mul_f32_e32 v248, v41, v41
	v_fmac_f32_e32 v248, v40, v40
	v_add_f32_e32 v247, v247, v248
	v_mul_f32_e32 v248, v43, v43
	v_fmac_f32_e32 v248, v42, v42
	v_add_f32_e32 v247, v248, v247
	v_add_f32_e32 v246, v246, v247
	v_mov_b32_e32 v247, v246
	s_nop 1
	v_permlane16_swap_b32_e32 v246, v247
	s_nop 1
	v_add_f32_e32 v246, v246, v247
	v_mov_b32_e32 v247, v246
	s_nop 1
	v_permlane32_swap_b32_e32 v246, v247
	v_add_u32_e32 v248, s8, v223
	s_nop 0
	v_add_f32_e32 v246, v246, v247
	s_mov_b64 exec, s[44:45]
	ds_write_b32 v248, v246 offset:2304
	s_mov_b64 exec, -1
	v_pk_mul_f32 v[52:53], v[180:181], v[52:53]
	v_pk_mul_f32 v[54:55], v[182:183], v[54:55]
	v_pk_mul_f32 v[48:49], v[184:185], v[48:49]
	v_pk_mul_f32 v[50:51], v[186:187], v[50:51]
	v_pk_mul_f32 v[44:45], v[188:189], v[44:45]
	v_pk_mul_f32 v[46:47], v[190:191], v[46:47]
	v_pk_mul_f32 v[40:41], v[192:193], v[40:41]
	v_pk_mul_f32 v[42:43], v[194:195], v[42:43]
	v_cvt_pk_bf16_f32 v246, v52, v53
	v_cvt_pk_bf16_f32 v247, v54, v55
	v_cvt_pk_bf16_f32 v248, v48, v49
	v_cvt_pk_bf16_f32 v249, v50, v51
	v_cvt_pk_bf16_f32 v250, v44, v45
	v_cvt_pk_bf16_f32 v251, v46, v47
	v_cvt_pk_bf16_f32 v208, v40, v41
	v_cvt_pk_bf16_f32 v209, v42, v43
	s_add_u32 s2, s2, 0x8000
	s_addc_u32 s3, s3, 0
	s_add_u32 s18, s18, 0x8000
	s_addc_u32 s19, s19, 0
	s_add_u32 s78, s78, 0x8000
	s_addc_u32 s79, s79, 0
	s_add_u32 s22, s22, 0x8000
	s_addc_u32 s23, s23, 0
	s_mov_b64 vcc, s[6:7]
	v_cndmask_b32_dpp v52, v4, v0, vcc row_ror:8 row_mask:0xf bank_mask:0xf
	v_cndmask_b32_dpp v53, v5, v1, vcc row_ror:8 row_mask:0xf bank_mask:0xf
	v_cndmask_b32_dpp v54, v6, v2, vcc row_ror:8 row_mask:0xf bank_mask:0xf
	v_cndmask_b32_dpp v55, v7, v3, vcc row_ror:8 row_mask:0xf bank_mask:0xf
	v_cndmask_b32_dpp v44, v250, v246, vcc row_ror:8 row_mask:0xf bank_mask:0xf
	v_cndmask_b32_dpp v45, v251, v247, vcc row_ror:8 row_mask:0xf bank_mask:0xf
	v_cndmask_b32_dpp v46, v208, v248, vcc row_ror:8 row_mask:0xf bank_mask:0xf
	v_cndmask_b32_dpp v47, v209, v249, vcc row_ror:8 row_mask:0xf bank_mask:0xf
	s_not_b64 vcc, s[6:7]
	v_cndmask_b32_dpp v48, v0, v4, vcc row_ror:8 row_mask:0xf bank_mask:0xf
	v_cndmask_b32_dpp v49, v1, v5, vcc row_ror:8 row_mask:0xf bank_mask:0xf
	v_cndmask_b32_dpp v50, v2, v6, vcc row_ror:8 row_mask:0xf bank_mask:0xf
	v_cndmask_b32_dpp v51, v3, v7, vcc row_ror:8 row_mask:0xf bank_mask:0xf
	v_cndmask_b32_dpp v40, v246, v250, vcc row_ror:8 row_mask:0xf bank_mask:0xf
	v_cndmask_b32_dpp v41, v247, v251, vcc row_ror:8 row_mask:0xf bank_mask:0xf
	v_cndmask_b32_dpp v42, v248, v208, vcc row_ror:8 row_mask:0xf bank_mask:0xf
	v_cndmask_b32_dpp v43, v249, v209, vcc row_ror:8 row_mask:0xf bank_mask:0xf
	global_store_dwordx4 v171, v[52:55], s[2:3]
	global_store_dwordx4 v171, v[48:51], s[18:19]
	global_store_dwordx4 v171, v[44:47], s[78:79]
	global_store_dwordx4 v171, v[40:43], s[22:23]
	s_waitcnt vmcnt(14)
	s_mov_b64 vcc, s[6:7]
	v_cndmask_b32_dpp v0, v200, v196, vcc row_ror:8 row_mask:0xf bank_mask:0xf
	v_cndmask_b32_dpp v1, v201, v197, vcc row_ror:8 row_mask:0xf bank_mask:0xf
	v_cndmask_b32_dpp v2, v202, v198, vcc row_ror:8 row_mask:0xf bank_mask:0xf
	v_cndmask_b32_dpp v3, v203, v199, vcc row_ror:8 row_mask:0xf bank_mask:0xf
	s_not_b64 vcc, s[6:7]
	v_cndmask_b32_dpp v4, v196, v200, vcc row_ror:8 row_mask:0xf bank_mask:0xf
	v_cndmask_b32_dpp v5, v197, v201, vcc row_ror:8 row_mask:0xf bank_mask:0xf
	v_cndmask_b32_dpp v6, v198, v202, vcc row_ror:8 row_mask:0xf bank_mask:0xf
	v_cndmask_b32_dpp v7, v199, v203, vcc row_ror:8 row_mask:0xf bank_mask:0xf
	v_lshlrev_b32_e32 v246, 16, v0
	v_and_b32_e32 v247, 0xffff0000, v0
	v_pk_fma_f32 v[36:37], v[36:37], v[142:143], v[246:247]
	v_lshlrev_b32_e32 v248, 16, v1
	v_and_b32_e32 v249, 0xffff0000, v1
	v_pk_fma_f32 v[38:39], v[38:39], v[144:145], v[248:249]
	v_lshlrev_b32_e32 v250, 16, v2
	v_and_b32_e32 v251, 0xffff0000, v2
	v_pk_fma_f32 v[32:33], v[32:33], v[150:151], v[250:251]
	v_lshlrev_b32_e32 v208, 16, v3
	v_and_b32_e32 v209, 0xffff0000, v3
	v_pk_fma_f32 v[34:35], v[34:35], v[152:153], v[208:209]
	v_lshlrev_b32_e32 v246, 16, v4
	v_and_b32_e32 v247, 0xffff0000, v4
	v_pk_fma_f32 v[28:29], v[28:29], v[138:139], v[246:247]
	v_lshlrev_b32_e32 v248, 16, v5
	v_and_b32_e32 v249, 0xffff0000, v5
	v_pk_fma_f32 v[30:31], v[30:31], v[140:141], v[248:249]
	v_lshlrev_b32_e32 v250, 16, v6
	v_and_b32_e32 v251, 0xffff0000, v6
	v_pk_fma_f32 v[24:25], v[24:25], v[146:147], v[250:251]
	v_lshlrev_b32_e32 v208, 16, v7
	v_and_b32_e32 v209, 0xffff0000, v7
	v_pk_fma_f32 v[26:27], v[26:27], v[148:149], v[208:209]
	v_cvt_pk_bf16_f32 v0, v36, v37
	v_cvt_pk_bf16_f32 v1, v38, v39
	v_cvt_pk_bf16_f32 v2, v32, v33
	v_cvt_pk_bf16_f32 v3, v34, v35
	v_cvt_pk_bf16_f32 v4, v28, v29
	v_cvt_pk_bf16_f32 v5, v30, v31
	v_cvt_pk_bf16_f32 v6, v24, v25
	v_cvt_pk_bf16_f32 v7, v26, v27
	v_mul_f32_e32 v246, v37, v37
	v_mul_f32_e32 v248, v39, v39
	v_fmac_f32_e32 v246, v36, v36
	v_fmac_f32_e32 v248, v38, v38
	v_add_f32_e32 v246, v246, v248
	v_mul_f32_e32 v248, v33, v33
	v_fmac_f32_e32 v248, v32, v32
	v_add_f32_e32 v246, v246, v248
	v_mul_f32_e32 v248, v35, v35
	v_fmac_f32_e32 v248, v34, v34
	v_add_f32_e32 v246, v248, v246
	v_mul_f32_e32 v247, v29, v29
	v_mul_f32_e32 v248, v31, v31
	v_fmac_f32_e32 v247, v28, v28
	v_fmac_f32_e32 v248, v30, v30
	v_add_f32_e32 v247, v247, v248
	v_mul_f32_e32 v248, v25, v25
	v_fmac_f32_e32 v248, v24, v24
	v_add_f32_e32 v247, v247, v248
	v_mul_f32_e32 v248, v27, v27
	v_fmac_f32_e32 v248, v26, v26
	v_add_f32_e32 v247, v248, v247
	v_add_f32_e32 v246, v246, v247
	v_mov_b32_e32 v247, v246
	s_nop 1
	v_permlane16_swap_b32_e32 v246, v247
	s_nop 1
	v_add_f32_e32 v246, v246, v247
	v_mov_b32_e32 v247, v246
	s_nop 1
	v_permlane32_swap_b32_e32 v246, v247
	v_add_u32_e32 v248, s8, v223
	s_nop 0
	v_add_f32_e32 v246, v246, v247
	s_mov_b64 exec, s[44:45]
	ds_write_b32 v248, v246 offset:2560
	s_mov_b64 exec, -1
	v_pk_mul_f32 v[36:37], v[180:181], v[36:37]
	v_pk_mul_f32 v[38:39], v[182:183], v[38:39]
	v_pk_mul_f32 v[32:33], v[184:185], v[32:33]
	v_pk_mul_f32 v[34:35], v[186:187], v[34:35]
	v_pk_mul_f32 v[28:29], v[188:189], v[28:29]
	v_pk_mul_f32 v[30:31], v[190:191], v[30:31]
	v_pk_mul_f32 v[24:25], v[192:193], v[24:25]
	v_pk_mul_f32 v[26:27], v[194:195], v[26:27]
	v_cvt_pk_bf16_f32 v246, v36, v37
	v_cvt_pk_bf16_f32 v247, v38, v39
	v_cvt_pk_bf16_f32 v248, v32, v33
	v_cvt_pk_bf16_f32 v249, v34, v35
	v_cvt_pk_bf16_f32 v250, v28, v29
	v_cvt_pk_bf16_f32 v251, v30, v31
	v_cvt_pk_bf16_f32 v208, v24, v25
	v_cvt_pk_bf16_f32 v209, v26, v27
	s_add_u32 s2, s2, 0x8000
	s_addc_u32 s3, s3, 0
	s_add_u32 s18, s18, 0x8000
	s_addc_u32 s19, s19, 0
	s_add_u32 s78, s78, 0x8000
	s_addc_u32 s79, s79, 0
	s_add_u32 s22, s22, 0x8000
	s_addc_u32 s23, s23, 0
	s_mov_b64 vcc, s[6:7]
	v_cndmask_b32_dpp v36, v4, v0, vcc row_ror:8 row_mask:0xf bank_mask:0xf
	v_cndmask_b32_dpp v37, v5, v1, vcc row_ror:8 row_mask:0xf bank_mask:0xf
	v_cndmask_b32_dpp v38, v6, v2, vcc row_ror:8 row_mask:0xf bank_mask:0xf
	v_cndmask_b32_dpp v39, v7, v3, vcc row_ror:8 row_mask:0xf bank_mask:0xf
	v_cndmask_b32_dpp v28, v250, v246, vcc row_ror:8 row_mask:0xf bank_mask:0xf
	v_cndmask_b32_dpp v29, v251, v247, vcc row_ror:8 row_mask:0xf bank_mask:0xf
	v_cndmask_b32_dpp v30, v208, v248, vcc row_ror:8 row_mask:0xf bank_mask:0xf
	v_cndmask_b32_dpp v31, v209, v249, vcc row_ror:8 row_mask:0xf bank_mask:0xf
	s_not_b64 vcc, s[6:7]
	v_cndmask_b32_dpp v32, v0, v4, vcc row_ror:8 row_mask:0xf bank_mask:0xf
	v_cndmask_b32_dpp v33, v1, v5, vcc row_ror:8 row_mask:0xf bank_mask:0xf
	v_cndmask_b32_dpp v34, v2, v6, vcc row_ror:8 row_mask:0xf bank_mask:0xf
	v_cndmask_b32_dpp v35, v3, v7, vcc row_ror:8 row_mask:0xf bank_mask:0xf
	v_cndmask_b32_dpp v24, v246, v250, vcc row_ror:8 row_mask:0xf bank_mask:0xf
	v_cndmask_b32_dpp v25, v247, v251, vcc row_ror:8 row_mask:0xf bank_mask:0xf
	v_cndmask_b32_dpp v26, v248, v208, vcc row_ror:8 row_mask:0xf bank_mask:0xf
	v_cndmask_b32_dpp v27, v249, v209, vcc row_ror:8 row_mask:0xf bank_mask:0xf
	global_store_dwordx4 v171, v[36:39], s[2:3]
	global_store_dwordx4 v171, v[32:35], s[18:19]
	global_store_dwordx4 v171, v[28:31], s[78:79]
	global_store_dwordx4 v171, v[24:27], s[22:23]
	s_waitcnt vmcnt(12)
	s_mov_b64 vcc, s[6:7]
	v_cndmask_b32_dpp v0, v234, v204, vcc row_ror:8 row_mask:0xf bank_mask:0xf
	v_cndmask_b32_dpp v1, v235, v205, vcc row_ror:8 row_mask:0xf bank_mask:0xf
	v_cndmask_b32_dpp v2, v236, v206, vcc row_ror:8 row_mask:0xf bank_mask:0xf
	v_cndmask_b32_dpp v3, v237, v207, vcc row_ror:8 row_mask:0xf bank_mask:0xf
	s_not_b64 vcc, s[6:7]
	v_cndmask_b32_dpp v4, v204, v234, vcc row_ror:8 row_mask:0xf bank_mask:0xf
	v_cndmask_b32_dpp v5, v205, v235, vcc row_ror:8 row_mask:0xf bank_mask:0xf
	v_cndmask_b32_dpp v6, v206, v236, vcc row_ror:8 row_mask:0xf bank_mask:0xf
	v_cndmask_b32_dpp v7, v207, v237, vcc row_ror:8 row_mask:0xf bank_mask:0xf
	v_lshlrev_b32_e32 v246, 16, v0
	v_and_b32_e32 v247, 0xffff0000, v0
	v_pk_fma_f32 v[20:21], v[20:21], v[142:143], v[246:247]
	v_lshlrev_b32_e32 v248, 16, v1
	v_and_b32_e32 v249, 0xffff0000, v1
	v_pk_fma_f32 v[22:23], v[22:23], v[144:145], v[248:249]
	v_lshlrev_b32_e32 v250, 16, v2
	v_and_b32_e32 v251, 0xffff0000, v2
	v_pk_fma_f32 v[16:17], v[16:17], v[150:151], v[250:251]
	v_lshlrev_b32_e32 v208, 16, v3
	v_and_b32_e32 v209, 0xffff0000, v3
	v_pk_fma_f32 v[18:19], v[18:19], v[152:153], v[208:209]
	v_lshlrev_b32_e32 v246, 16, v4
	v_and_b32_e32 v247, 0xffff0000, v4
	v_pk_fma_f32 v[12:13], v[12:13], v[138:139], v[246:247]
	v_lshlrev_b32_e32 v248, 16, v5
	v_and_b32_e32 v249, 0xffff0000, v5
	v_pk_fma_f32 v[14:15], v[14:15], v[140:141], v[248:249]
	v_lshlrev_b32_e32 v250, 16, v6
	v_and_b32_e32 v251, 0xffff0000, v6
	v_pk_fma_f32 v[8:9], v[8:9], v[146:147], v[250:251]
	v_lshlrev_b32_e32 v208, 16, v7
	v_and_b32_e32 v209, 0xffff0000, v7
	v_pk_fma_f32 v[10:11], v[10:11], v[148:149], v[208:209]
	v_cvt_pk_bf16_f32 v0, v20, v21
	v_cvt_pk_bf16_f32 v1, v22, v23
	v_cvt_pk_bf16_f32 v2, v16, v17
	v_cvt_pk_bf16_f32 v3, v18, v19
	v_cvt_pk_bf16_f32 v4, v12, v13
	v_cvt_pk_bf16_f32 v5, v14, v15
	v_cvt_pk_bf16_f32 v6, v8, v9
	v_cvt_pk_bf16_f32 v7, v10, v11
	v_mul_f32_e32 v246, v21, v21
	v_mul_f32_e32 v248, v23, v23
	v_fmac_f32_e32 v246, v20, v20
	v_fmac_f32_e32 v248, v22, v22
	v_add_f32_e32 v246, v246, v248
	v_mul_f32_e32 v248, v17, v17
	v_fmac_f32_e32 v248, v16, v16
	v_add_f32_e32 v246, v246, v248
	v_mul_f32_e32 v248, v19, v19
	v_fmac_f32_e32 v248, v18, v18
	v_add_f32_e32 v246, v248, v246
	v_mul_f32_e32 v247, v13, v13
	v_mul_f32_e32 v248, v15, v15
	v_fmac_f32_e32 v247, v12, v12
	v_fmac_f32_e32 v248, v14, v14
	v_add_f32_e32 v247, v247, v248
	v_mul_f32_e32 v248, v9, v9
	v_fmac_f32_e32 v248, v8, v8
	v_add_f32_e32 v247, v247, v248
	v_mul_f32_e32 v248, v11, v11
	v_fmac_f32_e32 v248, v10, v10
	v_add_f32_e32 v247, v248, v247
	v_add_f32_e32 v246, v246, v247
	v_mov_b32_e32 v247, v246
	s_nop 1
	v_permlane16_swap_b32_e32 v246, v247
	s_nop 1
	v_add_f32_e32 v246, v246, v247
	v_mov_b32_e32 v247, v246
	s_nop 1
	v_permlane32_swap_b32_e32 v246, v247
	v_add_u32_e32 v248, s8, v223
	s_nop 0
	v_add_f32_e32 v246, v246, v247
	s_mov_b64 exec, s[44:45]
	ds_write_b32 v248, v246 offset:2816
	s_mov_b64 exec, -1
	v_pk_mul_f32 v[20:21], v[180:181], v[20:21]
	v_pk_mul_f32 v[22:23], v[182:183], v[22:23]
	v_pk_mul_f32 v[16:17], v[184:185], v[16:17]
	v_pk_mul_f32 v[18:19], v[186:187], v[18:19]
	v_pk_mul_f32 v[12:13], v[188:189], v[12:13]
	v_pk_mul_f32 v[14:15], v[190:191], v[14:15]
	v_pk_mul_f32 v[8:9], v[192:193], v[8:9]
	v_pk_mul_f32 v[10:11], v[194:195], v[10:11]
	v_cvt_pk_bf16_f32 v246, v20, v21
	v_cvt_pk_bf16_f32 v247, v22, v23
	v_cvt_pk_bf16_f32 v248, v16, v17
	v_cvt_pk_bf16_f32 v249, v18, v19
	v_cvt_pk_bf16_f32 v250, v12, v13
	v_cvt_pk_bf16_f32 v251, v14, v15
	v_cvt_pk_bf16_f32 v208, v8, v9
	v_cvt_pk_bf16_f32 v209, v10, v11
	s_add_u32 s2, s2, 0x8000
	s_addc_u32 s3, s3, 0
	s_add_u32 s18, s18, 0x8000
	s_addc_u32 s19, s19, 0
	s_add_u32 s78, s78, 0x8000
	s_addc_u32 s79, s79, 0
	s_add_u32 s22, s22, 0x8000
	s_addc_u32 s23, s23, 0
	s_mov_b64 vcc, s[6:7]
	v_cndmask_b32_dpp v20, v4, v0, vcc row_ror:8 row_mask:0xf bank_mask:0xf
	v_cndmask_b32_dpp v21, v5, v1, vcc row_ror:8 row_mask:0xf bank_mask:0xf
	v_cndmask_b32_dpp v22, v6, v2, vcc row_ror:8 row_mask:0xf bank_mask:0xf
	v_cndmask_b32_dpp v23, v7, v3, vcc row_ror:8 row_mask:0xf bank_mask:0xf
	v_cndmask_b32_dpp v12, v250, v246, vcc row_ror:8 row_mask:0xf bank_mask:0xf
	v_cndmask_b32_dpp v13, v251, v247, vcc row_ror:8 row_mask:0xf bank_mask:0xf
	v_cndmask_b32_dpp v14, v208, v248, vcc row_ror:8 row_mask:0xf bank_mask:0xf
	v_cndmask_b32_dpp v15, v209, v249, vcc row_ror:8 row_mask:0xf bank_mask:0xf
	s_not_b64 vcc, s[6:7]
	v_cndmask_b32_dpp v16, v0, v4, vcc row_ror:8 row_mask:0xf bank_mask:0xf
	v_cndmask_b32_dpp v17, v1, v5, vcc row_ror:8 row_mask:0xf bank_mask:0xf
	v_cndmask_b32_dpp v18, v2, v6, vcc row_ror:8 row_mask:0xf bank_mask:0xf
	v_cndmask_b32_dpp v19, v3, v7, vcc row_ror:8 row_mask:0xf bank_mask:0xf
	v_cndmask_b32_dpp v8, v246, v250, vcc row_ror:8 row_mask:0xf bank_mask:0xf
	v_cndmask_b32_dpp v9, v247, v251, vcc row_ror:8 row_mask:0xf bank_mask:0xf
	v_cndmask_b32_dpp v10, v248, v208, vcc row_ror:8 row_mask:0xf bank_mask:0xf
	v_cndmask_b32_dpp v11, v249, v209, vcc row_ror:8 row_mask:0xf bank_mask:0xf
	global_store_dwordx4 v171, v[20:23], s[2:3]
	global_store_dwordx4 v171, v[16:19], s[18:19]
	global_store_dwordx4 v171, v[12:15], s[78:79]
	global_store_dwordx4 v171, v[8:11], s[22:23]
	s_mov_b32 s100, 1
	s_branch .LBB0_714
.Lfo_nong:
	global_load_dwordx4 v[142:145], v170, s[16:17]
	global_load_dwordx4 v[150:153], v170, s[16:17] offset:16
	global_load_dwordx4 v[138:141], v170, s[16:17] offset:128
	global_load_dwordx4 v[146:149], v170, s[16:17] offset:144
	global_load_dwordx4 v[196:199], v171, s[14:15]
	global_load_dwordx4 v[200:203], v171, s[12:13]
	s_add_u32 s14, s14, 0x8000
	s_addc_u32 s15, s15, 0
	s_add_u32 s12, s12, 0x8000
	s_addc_u32 s13, s13, 0
	global_load_dwordx4 v[204:207], v171, s[14:15]
	global_load_dwordx4 v[234:237], v171, s[12:13]
	s_add_u32 s14, s14, 0x8000
	s_addc_u32 s15, s15, 0
	s_add_u32 s12, s12, 0x8000
	s_addc_u32 s13, s13, 0
	global_load_dwordx4 v[238:241], v171, s[14:15]
	global_load_dwordx4 v[242:245], v171, s[12:13]
	s_waitcnt vmcnt(4)
	s_mov_b64 vcc, s[6:7]
	v_cndmask_b32_dpp v0, v200, v196, vcc row_ror:8 row_mask:0xf bank_mask:0xf
	v_cndmask_b32_dpp v1, v201, v197, vcc row_ror:8 row_mask:0xf bank_mask:0xf
	v_cndmask_b32_dpp v2, v202, v198, vcc row_ror:8 row_mask:0xf bank_mask:0xf
	v_cndmask_b32_dpp v3, v203, v199, vcc row_ror:8 row_mask:0xf bank_mask:0xf
	s_not_b64 vcc, s[6:7]
	v_cndmask_b32_dpp v4, v196, v200, vcc row_ror:8 row_mask:0xf bank_mask:0xf
	v_cndmask_b32_dpp v5, v197, v201, vcc row_ror:8 row_mask:0xf bank_mask:0xf
	v_cndmask_b32_dpp v6, v198, v202, vcc row_ror:8 row_mask:0xf bank_mask:0xf
	v_cndmask_b32_dpp v7, v199, v203, vcc row_ror:8 row_mask:0xf bank_mask:0xf
	s_add_u32 s14, s14, 0x8000
	s_addc_u32 s15, s15, 0
	s_add_u32 s12, s12, 0x8000
	s_addc_u32 s13, s13, 0
	global_load_dwordx4 v[196:199], v171, s[14:15]
	global_load_dwordx4 v[200:203], v171, s[12:13]
	v_lshlrev_b32_e32 v246, 16, v0
	v_and_b32_e32 v247, 0xffff0000, v0
	v_pk_fma_f32 v[134:135], v[134:135], v[142:143], v[246:247]
	v_lshlrev_b32_e32 v248, 16, v1
	v_and_b32_e32 v249, 0xffff0000, v1
	v_pk_fma_f32 v[136:137], v[136:137], v[144:145], v[248:249]
	v_lshlrev_b32_e32 v250, 16, v2
	v_and_b32_e32 v251, 0xffff0000, v2
	v_pk_fma_f32 v[130:131], v[130:131], v[150:151], v[250:251]
	v_lshlrev_b32_e32 v208, 16, v3
	v_and_b32_e32 v209, 0xffff0000, v3
	v_pk_fma_f32 v[132:133], v[132:133], v[152:153], v[208:209]
	v_lshlrev_b32_e32 v246, 16, v4
	v_and_b32_e32 v247, 0xffff0000, v4
	v_pk_fma_f32 v[126:127], v[126:127], v[138:139], v[246:247]
	v_lshlrev_b32_e32 v248, 16, v5
	v_and_b32_e32 v249, 0xffff0000, v5
	v_pk_fma_f32 v[128:129], v[128:129], v[140:141], v[248:249]
	v_lshlrev_b32_e32 v250, 16, v6
	v_and_b32_e32 v251, 0xffff0000, v6
	v_pk_fma_f32 v[122:123], v[122:123], v[146:147], v[250:251]
	v_lshlrev_b32_e32 v208, 16, v7
	v_and_b32_e32 v209, 0xffff0000, v7
	v_pk_fma_f32 v[124:125], v[124:125], v[148:149], v[208:209]
	v_cvt_pk_bf16_f32 v0, v134, v135
	v_cvt_pk_bf16_f32 v1, v136, v137
	v_cvt_pk_bf16_f32 v2, v130, v131
	v_cvt_pk_bf16_f32 v3, v132, v133
	v_cvt_pk_bf16_f32 v4, v126, v127
	v_cvt_pk_bf16_f32 v5, v128, v129
	v_cvt_pk_bf16_f32 v6, v122, v123
	v_cvt_pk_bf16_f32 v7, v124, v125
	v_mul_f32_e32 v246, v135, v135
	v_mul_f32_e32 v248, v137, v137
	v_fmac_f32_e32 v246, v134, v134
	v_fmac_f32_e32 v248, v136, v136
	v_add_f32_e32 v246, v246, v248
	v_mul_f32_e32 v248, v131, v131
	v_fmac_f32_e32 v248, v130, v130
	v_add_f32_e32 v246, v246, v248
	v_mul_f32_e32 v248, v133, v133
	v_fmac_f32_e32 v248, v132, v132
	v_add_f32_e32 v246, v248, v246
	v_mul_f32_e32 v247, v127, v127
	v_mul_f32_e32 v248, v129, v129
	v_fmac_f32_e32 v247, v126, v126
	v_fmac_f32_e32 v248, v128, v128
	v_add_f32_e32 v247, v247, v248
	v_mul_f32_e32 v248, v123, v123
	v_fmac_f32_e32 v248, v122, v122
	v_add_f32_e32 v247, v247, v248
	v_mul_f32_e32 v248, v125, v125
	v_fmac_f32_e32 v248, v124, v124
	v_add_f32_e32 v247, v248, v247
	v_add_f32_e32 v246, v246, v247
	v_mov_b32_e32 v247, v246
	s_nop 1
	v_permlane16_swap_b32_e32 v246, v247
	s_nop 1
	v_add_f32_e32 v246, v246, v247
	v_mov_b32_e32 v247, v246
	s_nop 1
	v_permlane32_swap_b32_e32 v246, v247
	v_add_u32_e32 v248, s8, v223
	s_nop 0
	v_add_f32_e32 v246, v246, v247
	s_mov_b64 exec, s[44:45]
	ds_write_b32 v248, v246
	s_mov_b64 exec, -1
	s_nop 1
	s_mov_b64 vcc, s[6:7]
	v_cndmask_b32_dpp v134, v4, v0, vcc row_ror:8 row_mask:0xf bank_mask:0xf
	v_cndmask_b32_dpp v135, v5, v1, vcc row_ror:8 row_mask:0xf bank_mask:0xf
	v_cndmask_b32_dpp v136, v6, v2, vcc row_ror:8 row_mask:0xf bank_mask:0xf
	v_cndmask_b32_dpp v137, v7, v3, vcc row_ror:8 row_mask:0xf bank_mask:0xf
	s_not_b64 vcc, s[6:7]
	v_cndmask_b32_dpp v130, v0, v4, vcc row_ror:8 row_mask:0xf bank_mask:0xf
	v_cndmask_b32_dpp v131, v1, v5, vcc row_ror:8 row_mask:0xf bank_mask:0xf
	v_cndmask_b32_dpp v132, v2, v6, vcc row_ror:8 row_mask:0xf bank_mask:0xf
	v_cndmask_b32_dpp v133, v3, v7, vcc row_ror:8 row_mask:0xf bank_mask:0xf
	global_store_dwordx4 v171, v[134:137], s[2:3]
	global_store_dwordx4 v171, v[130:133], s[18:19]
	s_waitcnt vmcnt(6)
	s_mov_b64 vcc, s[6:7]
	v_cndmask_b32_dpp v0, v234, v204, vcc row_ror:8 row_mask:0xf bank_mask:0xf
	v_cndmask_b32_dpp v1, v235, v205, vcc row_ror:8 row_mask:0xf bank_mask:0xf
	v_cndmask_b32_dpp v2, v236, v206, vcc row_ror:8 row_mask:0xf bank_mask:0xf
	v_cndmask_b32_dpp v3, v237, v207, vcc row_ror:8 row_mask:0xf bank_mask:0xf
	s_not_b64 vcc, s[6:7]
	v_cndmask_b32_dpp v4, v204, v234, vcc row_ror:8 row_mask:0xf bank_mask:0xf
	v_cndmask_b32_dpp v5, v205, v235, vcc row_ror:8 row_mask:0xf bank_mask:0xf
	v_cndmask_b32_dpp v6, v206, v236, vcc row_ror:8 row_mask:0xf bank_mask:0xf
	v_cndmask_b32_dpp v7, v207, v237, vcc row_ror:8 row_mask:0xf bank_mask:0xf
	s_add_u32 s14, s14, 0x28000
	s_addc_u32 s15, s15, 0
	s_add_u32 s12, s12, 0x28000
	s_addc_u32 s13, s13, 0
	global_load_dwordx4 v[204:207], v171, s[14:15]
	global_load_dwordx4 v[234:237], v171, s[12:13]
	v_lshlrev_b32_e32 v246, 16, v0
	v_and_b32_e32 v247, 0xffff0000, v0
	v_pk_fma_f32 v[118:119], v[118:119], v[142:143], v[246:247]
	v_lshlrev_b32_e32 v248, 16, v1
	v_and_b32_e32 v249, 0xffff0000, v1
	v_pk_fma_f32 v[120:121], v[120:121], v[144:145], v[248:249]
	v_lshlrev_b32_e32 v250, 16, v2
	v_and_b32_e32 v251, 0xffff0000, v2
	v_pk_fma_f32 v[114:115], v[114:115], v[150:151], v[250:251]
	v_lshlrev_b32_e32 v208, 16, v3
	v_and_b32_e32 v209, 0xffff0000, v3
	v_pk_fma_f32 v[116:117], v[116:117], v[152:153], v[208:209]
	v_lshlrev_b32_e32 v246, 16, v4
	v_and_b32_e32 v247, 0xffff0000, v4
	v_pk_fma_f32 v[110:111], v[110:111], v[138:139], v[246:247]
	v_lshlrev_b32_e32 v248, 16, v5
	v_and_b32_e32 v249, 0xffff0000, v5
	v_pk_fma_f32 v[112:113], v[112:113], v[140:141], v[248:249]
	v_lshlrev_b32_e32 v250, 16, v6
	v_and_b32_e32 v251, 0xffff0000, v6
	v_pk_fma_f32 v[106:107], v[106:107], v[146:147], v[250:251]
	v_lshlrev_b32_e32 v208, 16, v7
	v_and_b32_e32 v209, 0xffff0000, v7
	v_pk_fma_f32 v[108:109], v[108:109], v[148:149], v[208:209]
	v_cvt_pk_bf16_f32 v0, v118, v119
	v_cvt_pk_bf16_f32 v1, v120, v121
	v_cvt_pk_bf16_f32 v2, v114, v115
	v_cvt_pk_bf16_f32 v3, v116, v117
	v_cvt_pk_bf16_f32 v4, v110, v111
	v_cvt_pk_bf16_f32 v5, v112, v113
	v_cvt_pk_bf16_f32 v6, v106, v107
	v_cvt_pk_bf16_f32 v7, v108, v109
	v_mul_f32_e32 v246, v119, v119
	v_mul_f32_e32 v248, v121, v121
	v_fmac_f32_e32 v246, v118, v118
	v_fmac_f32_e32 v248, v120, v120
	v_add_f32_e32 v246, v246, v248
	v_mul_f32_e32 v248, v115, v115
	v_fmac_f32_e32 v248, v114, v114
	v_add_f32_e32 v246, v246, v248
	v_mul_f32_e32 v248, v117, v117
	v_fmac_f32_e32 v248, v116, v116
	v_add_f32_e32 v246, v248, v246
	v_mul_f32_e32 v247, v111, v111
	v_mul_f32_e32 v248, v113, v113
	v_fmac_f32_e32 v247, v110, v110
	v_fmac_f32_e32 v248, v112, v112
	v_add_f32_e32 v247, v247, v248
	v_mul_f32_e32 v248, v107, v107
	v_fmac_f32_e32 v248, v106, v106
	v_add_f32_e32 v247, v247, v248
	v_mul_f32_e32 v248, v109, v109
	v_fmac_f32_e32 v248, v108, v108
	v_add_f32_e32 v247, v248, v247
	v_add_f32_e32 v246, v246, v247
	v_mov_b32_e32 v247, v246
	s_nop 1
	v_permlane16_swap_b32_e32 v246, v247
	s_nop 1
	v_add_f32_e32 v246, v246, v247
	v_mov_b32_e32 v247, v246
	s_nop 1
	v_permlane32_swap_b32_e32 v246, v247
	v_add_u32_e32 v248, s8, v223
	s_nop 0
	v_add_f32_e32 v246, v246, v247
	s_mov_b64 exec, s[44:45]
	ds_write_b32 v248, v246 offset:256
	s_mov_b64 exec, -1
	s_add_u32 s2, s2, 0x8000
	s_addc_u32 s3, s3, 0
	s_add_u32 s18, s18, 0x8000
	s_addc_u32 s19, s19, 0
	s_mov_b64 vcc, s[6:7]
	v_cndmask_b32_dpp v118, v4, v0, vcc row_ror:8 row_mask:0xf bank_mask:0xf
	v_cndmask_b32_dpp v119, v5, v1, vcc row_ror:8 row_mask:0xf bank_mask:0xf
	v_cndmask_b32_dpp v120, v6, v2, vcc row_ror:8 row_mask:0xf bank_mask:0xf
	v_cndmask_b32_dpp v121, v7, v3, vcc row_ror:8 row_mask:0xf bank_mask:0xf
	s_not_b64 vcc, s[6:7]
	v_cndmask_b32_dpp v114, v0, v4, vcc row_ror:8 row_mask:0xf bank_mask:0xf
	v_cndmask_b32_dpp v115, v1, v5, vcc row_ror:8 row_mask:0xf bank_mask:0xf
	v_cndmask_b32_dpp v116, v2, v6, vcc row_ror:8 row_mask:0xf bank_mask:0xf
	v_cndmask_b32_dpp v117, v3, v7, vcc row_ror:8 row_mask:0xf bank_mask:0xf
	global_store_dwordx4 v171, v[118:121], s[2:3]
	global_store_dwordx4 v171, v[114:117], s[18:19]
	s_waitcnt vmcnt(8)
	s_mov_b64 vcc, s[6:7]
	v_cndmask_b32_dpp v0, v242, v238, vcc row_ror:8 row_mask:0xf bank_mask:0xf
	v_cndmask_b32_dpp v1, v243, v239, vcc row_ror:8 row_mask:0xf bank_mask:0xf
	v_cndmask_b32_dpp v2, v244, v240, vcc row_ror:8 row_mask:0xf bank_mask:0xf
	v_cndmask_b32_dpp v3, v245, v241, vcc row_ror:8 row_mask:0xf bank_mask:0xf
	s_not_b64 vcc, s[6:7]
	v_cndmask_b32_dpp v4, v238, v242, vcc row_ror:8 row_mask:0xf bank_mask:0xf
	v_cndmask_b32_dpp v5, v239, v243, vcc row_ror:8 row_mask:0xf bank_mask:0xf
	v_cndmask_b32_dpp v6, v240, v244, vcc row_ror:8 row_mask:0xf bank_mask:0xf
	v_cndmask_b32_dpp v7, v241, v245, vcc row_ror:8 row_mask:0xf bank_mask:0xf
	s_add_u32 s14, s14, 0x8000
	s_addc_u32 s15, s15, 0
	s_add_u32 s12, s12, 0x8000
	s_addc_u32 s13, s13, 0
	global_load_dwordx4 v[238:241], v171, s[14:15]
	global_load_dwordx4 v[242:245], v171, s[12:13]
	v_lshlrev_b32_e32 v246, 16, v0
	v_and_b32_e32 v247, 0xffff0000, v0
	v_pk_fma_f32 v[102:103], v[102:103], v[142:143], v[246:247]
	v_lshlrev_b32_e32 v248, 16, v1
	v_and_b32_e32 v249, 0xffff0000, v1
	v_pk_fma_f32 v[104:105], v[104:105], v[144:145], v[248:249]
	v_lshlrev_b32_e32 v250, 16, v2
	v_and_b32_e32 v251, 0xffff0000, v2
	v_pk_fma_f32 v[98:99], v[98:99], v[150:151], v[250:251]
	v_lshlrev_b32_e32 v208, 16, v3
	v_and_b32_e32 v209, 0xffff0000, v3
	v_pk_fma_f32 v[100:101], v[100:101], v[152:153], v[208:209]
	v_lshlrev_b32_e32 v246, 16, v4
	v_and_b32_e32 v247, 0xffff0000, v4
	v_pk_fma_f32 v[92:93], v[92:93], v[138:139], v[246:247]
	v_lshlrev_b32_e32 v248, 16, v5
	v_and_b32_e32 v249, 0xffff0000, v5
	v_pk_fma_f32 v[94:95], v[94:95], v[140:141], v[248:249]
	v_lshlrev_b32_e32 v250, 16, v6
	v_and_b32_e32 v251, 0xffff0000, v6
	v_pk_fma_f32 v[88:89], v[88:89], v[146:147], v[250:251]
	v_lshlrev_b32_e32 v208, 16, v7
	v_and_b32_e32 v209, 0xffff0000, v7
	v_pk_fma_f32 v[90:91], v[90:91], v[148:149], v[208:209]
	v_cvt_pk_bf16_f32 v0, v102, v103
	v_cvt_pk_bf16_f32 v1, v104, v105
	v_cvt_pk_bf16_f32 v2, v98, v99
	v_cvt_pk_bf16_f32 v3, v100, v101
	v_cvt_pk_bf16_f32 v4, v92, v93
	v_cvt_pk_bf16_f32 v5, v94, v95
	v_cvt_pk_bf16_f32 v6, v88, v89
	v_cvt_pk_bf16_f32 v7, v90, v91
	v_mul_f32_e32 v246, v103, v103
	v_mul_f32_e32 v248, v105, v105
	v_fmac_f32_e32 v246, v102, v102
	v_fmac_f32_e32 v248, v104, v104
	v_add_f32_e32 v246, v246, v248
	v_mul_f32_e32 v248, v99, v99
	v_fmac_f32_e32 v248, v98, v98
	v_add_f32_e32 v246, v246, v248
	v_mul_f32_e32 v248, v101, v101
	v_fmac_f32_e32 v248, v100, v100
	v_add_f32_e32 v246, v248, v246
	v_mul_f32_e32 v247, v93, v93
	v_mul_f32_e32 v248, v95, v95
	v_fmac_f32_e32 v247, v92, v92
	v_fmac_f32_e32 v248, v94, v94
	v_add_f32_e32 v247, v247, v248
	v_mul_f32_e32 v248, v89, v89
	v_fmac_f32_e32 v248, v88, v88
	v_add_f32_e32 v247, v247, v248
	v_mul_f32_e32 v248, v91, v91
	v_fmac_f32_e32 v248, v90, v90
	v_add_f32_e32 v247, v248, v247
	v_add_f32_e32 v246, v246, v247
	v_mov_b32_e32 v247, v246
	s_nop 1
	v_permlane16_swap_b32_e32 v246, v247
	s_nop 1
	v_add_f32_e32 v246, v246, v247
	v_mov_b32_e32 v247, v246
	s_nop 1
	v_permlane32_swap_b32_e32 v246, v247
	v_add_u32_e32 v248, s8, v223
	s_nop 0
	v_add_f32_e32 v246, v246, v247
	s_mov_b64 exec, s[44:45]
	ds_write_b32 v248, v246 offset:512
	s_mov_b64 exec, -1
	s_add_u32 s2, s2, 0x8000
	s_addc_u32 s3, s3, 0
	s_add_u32 s18, s18, 0x8000
	s_addc_u32 s19, s19, 0
	s_mov_b64 vcc, s[6:7]
	v_cndmask_b32_dpp v102, v4, v0, vcc row_ror:8 row_mask:0xf bank_mask:0xf
	v_cndmask_b32_dpp v103, v5, v1, vcc row_ror:8 row_mask:0xf bank_mask:0xf
	v_cndmask_b32_dpp v104, v6, v2, vcc row_ror:8 row_mask:0xf bank_mask:0xf
	v_cndmask_b32_dpp v105, v7, v3, vcc row_ror:8 row_mask:0xf bank_mask:0xf
	s_not_b64 vcc, s[6:7]
	v_cndmask_b32_dpp v98, v0, v4, vcc row_ror:8 row_mask:0xf bank_mask:0xf
	v_cndmask_b32_dpp v99, v1, v5, vcc row_ror:8 row_mask:0xf bank_mask:0xf
	v_cndmask_b32_dpp v100, v2, v6, vcc row_ror:8 row_mask:0xf bank_mask:0xf
	v_cndmask_b32_dpp v101, v3, v7, vcc row_ror:8 row_mask:0xf bank_mask:0xf
	global_store_dwordx4 v171, v[102:105], s[2:3]
	global_store_dwordx4 v171, v[98:101], s[18:19]
	s_waitcnt vmcnt(10)
	s_mov_b64 vcc, s[6:7]
	v_cndmask_b32_dpp v0, v200, v196, vcc row_ror:8 row_mask:0xf bank_mask:0xf
	v_cndmask_b32_dpp v1, v201, v197, vcc row_ror:8 row_mask:0xf bank_mask:0xf
	v_cndmask_b32_dpp v2, v202, v198, vcc row_ror:8 row_mask:0xf bank_mask:0xf
	v_cndmask_b32_dpp v3, v203, v199, vcc row_ror:8 row_mask:0xf bank_mask:0xf
	s_not_b64 vcc, s[6:7]
	v_cndmask_b32_dpp v4, v196, v200, vcc row_ror:8 row_mask:0xf bank_mask:0xf
	v_cndmask_b32_dpp v5, v197, v201, vcc row_ror:8 row_mask:0xf bank_mask:0xf
	v_cndmask_b32_dpp v6, v198, v202, vcc row_ror:8 row_mask:0xf bank_mask:0xf
	v_cndmask_b32_dpp v7, v199, v203, vcc row_ror:8 row_mask:0xf bank_mask:0xf
	s_add_u32 s14, s14, 0x8000
	s_addc_u32 s15, s15, 0
	s_add_u32 s12, s12, 0x8000
	s_addc_u32 s13, s13, 0
	global_load_dwordx4 v[196:199], v171, s[14:15]
	global_load_dwordx4 v[200:203], v171, s[12:13]
	v_lshlrev_b32_e32 v246, 16, v0
	v_and_b32_e32 v247, 0xffff0000, v0
	v_pk_fma_f32 v[84:85], v[84:85], v[142:143], v[246:247]
	v_lshlrev_b32_e32 v248, 16, v1
	v_and_b32_e32 v249, 0xffff0000, v1
	v_pk_fma_f32 v[86:87], v[86:87], v[144:145], v[248:249]
	v_lshlrev_b32_e32 v250, 16, v2
	v_and_b32_e32 v251, 0xffff0000, v2
	v_pk_fma_f32 v[80:81], v[80:81], v[150:151], v[250:251]
	v_lshlrev_b32_e32 v208, 16, v3
	v_and_b32_e32 v209, 0xffff0000, v3
	v_pk_fma_f32 v[82:83], v[82:83], v[152:153], v[208:209]
	v_lshlrev_b32_e32 v246, 16, v4
	v_and_b32_e32 v247, 0xffff0000, v4
	v_pk_fma_f32 v[76:77], v[76:77], v[138:139], v[246:247]
	v_lshlrev_b32_e32 v248, 16, v5
	v_and_b32_e32 v249, 0xffff0000, v5
	v_pk_fma_f32 v[78:79], v[78:79], v[140:141], v[248:249]
	v_lshlrev_b32_e32 v250, 16, v6
	v_and_b32_e32 v251, 0xffff0000, v6
	v_pk_fma_f32 v[72:73], v[72:73], v[146:147], v[250:251]
	v_lshlrev_b32_e32 v208, 16, v7
	v_and_b32_e32 v209, 0xffff0000, v7
	v_pk_fma_f32 v[74:75], v[74:75], v[148:149], v[208:209]
	v_cvt_pk_bf16_f32 v0, v84, v85
	v_cvt_pk_bf16_f32 v1, v86, v87
	v_cvt_pk_bf16_f32 v2, v80, v81
	v_cvt_pk_bf16_f32 v3, v82, v83
	v_cvt_pk_bf16_f32 v4, v76, v77
	v_cvt_pk_bf16_f32 v5, v78, v79
	v_cvt_pk_bf16_f32 v6, v72, v73
	v_cvt_pk_bf16_f32 v7, v74, v75
	v_mul_f32_e32 v246, v85, v85
	v_mul_f32_e32 v248, v87, v87
	v_fmac_f32_e32 v246, v84, v84
	v_fmac_f32_e32 v248, v86, v86
	v_add_f32_e32 v246, v246, v248
	v_mul_f32_e32 v248, v81, v81
	v_fmac_f32_e32 v248, v80, v80
	v_add_f32_e32 v246, v246, v248
	v_mul_f32_e32 v248, v83, v83
	v_fmac_f32_e32 v248, v82, v82
	v_add_f32_e32 v246, v248, v246
	v_mul_f32_e32 v247, v77, v77
	v_mul_f32_e32 v248, v79, v79
	v_fmac_f32_e32 v247, v76, v76
	v_fmac_f32_e32 v248, v78, v78
	v_add_f32_e32 v247, v247, v248
	v_mul_f32_e32 v248, v73, v73
	v_fmac_f32_e32 v248, v72, v72
	v_add_f32_e32 v247, v247, v248
	v_mul_f32_e32 v248, v75, v75
	v_fmac_f32_e32 v248, v74, v74
	v_add_f32_e32 v247, v248, v247
	v_add_f32_e32 v246, v246, v247
	v_mov_b32_e32 v247, v246
	s_nop 1
	v_permlane16_swap_b32_e32 v246, v247
	s_nop 1
	v_add_f32_e32 v246, v246, v247
	v_mov_b32_e32 v247, v246
	s_nop 1
	v_permlane32_swap_b32_e32 v246, v247
	v_add_u32_e32 v248, s8, v223
	s_nop 0
	v_add_f32_e32 v246, v246, v247
	s_mov_b64 exec, s[44:45]
	ds_write_b32 v248, v246 offset:768
	s_mov_b64 exec, -1
	s_add_u32 s2, s2, 0x8000
	s_addc_u32 s3, s3, 0
	s_add_u32 s18, s18, 0x8000
	s_addc_u32 s19, s19, 0
	s_mov_b64 vcc, s[6:7]
	v_cndmask_b32_dpp v84, v4, v0, vcc row_ror:8 row_mask:0xf bank_mask:0xf
	v_cndmask_b32_dpp v85, v5, v1, vcc row_ror:8 row_mask:0xf bank_mask:0xf
	v_cndmask_b32_dpp v86, v6, v2, vcc row_ror:8 row_mask:0xf bank_mask:0xf
	v_cndmask_b32_dpp v87, v7, v3, vcc row_ror:8 row_mask:0xf bank_mask:0xf
	s_not_b64 vcc, s[6:7]
	v_cndmask_b32_dpp v80, v0, v4, vcc row_ror:8 row_mask:0xf bank_mask:0xf
	v_cndmask_b32_dpp v81, v1, v5, vcc row_ror:8 row_mask:0xf bank_mask:0xf
	v_cndmask_b32_dpp v82, v2, v6, vcc row_ror:8 row_mask:0xf bank_mask:0xf
	v_cndmask_b32_dpp v83, v3, v7, vcc row_ror:8 row_mask:0xf bank_mask:0xf
	global_store_dwordx4 v171, v[84:87], s[2:3]
	global_store_dwordx4 v171, v[80:83], s[18:19]
	s_waitcnt vmcnt(10)
	s_mov_b64 vcc, s[6:7]
	v_cndmask_b32_dpp v0, v234, v204, vcc row_ror:8 row_mask:0xf bank_mask:0xf
	v_cndmask_b32_dpp v1, v235, v205, vcc row_ror:8 row_mask:0xf bank_mask:0xf
	v_cndmask_b32_dpp v2, v236, v206, vcc row_ror:8 row_mask:0xf bank_mask:0xf
	v_cndmask_b32_dpp v3, v237, v207, vcc row_ror:8 row_mask:0xf bank_mask:0xf
	s_not_b64 vcc, s[6:7]
	v_cndmask_b32_dpp v4, v204, v234, vcc row_ror:8 row_mask:0xf bank_mask:0xf
	v_cndmask_b32_dpp v5, v205, v235, vcc row_ror:8 row_mask:0xf bank_mask:0xf
	v_cndmask_b32_dpp v6, v206, v236, vcc row_ror:8 row_mask:0xf bank_mask:0xf
	v_cndmask_b32_dpp v7, v207, v237, vcc row_ror:8 row_mask:0xf bank_mask:0xf
	s_add_u32 s14, s14, 0x8000
	s_addc_u32 s15, s15, 0
	s_add_u32 s12, s12, 0x8000
	s_addc_u32 s13, s13, 0
	global_load_dwordx4 v[204:207], v171, s[14:15]
	global_load_dwordx4 v[234:237], v171, s[12:13]
	v_lshlrev_b32_e32 v246, 16, v0
	v_and_b32_e32 v247, 0xffff0000, v0
	v_pk_fma_f32 v[68:69], v[68:69], v[142:143], v[246:247]
	v_lshlrev_b32_e32 v248, 16, v1
	v_and_b32_e32 v249, 0xffff0000, v1
	v_pk_fma_f32 v[70:71], v[70:71], v[144:145], v[248:249]
	v_lshlrev_b32_e32 v250, 16, v2
	v_and_b32_e32 v251, 0xffff0000, v2
	v_pk_fma_f32 v[64:65], v[64:65], v[150:151], v[250:251]
	v_lshlrev_b32_e32 v208, 16, v3
	v_and_b32_e32 v209, 0xffff0000, v3
	v_pk_fma_f32 v[66:67], v[66:67], v[152:153], v[208:209]
	v_lshlrev_b32_e32 v246, 16, v4
	v_and_b32_e32 v247, 0xffff0000, v4
	v_pk_fma_f32 v[60:61], v[60:61], v[138:139], v[246:247]
	v_lshlrev_b32_e32 v248, 16, v5
	v_and_b32_e32 v249, 0xffff0000, v5
	v_pk_fma_f32 v[62:63], v[62:63], v[140:141], v[248:249]
	v_lshlrev_b32_e32 v250, 16, v6
	v_and_b32_e32 v251, 0xffff0000, v6
	v_pk_fma_f32 v[56:57], v[56:57], v[146:147], v[250:251]
	v_lshlrev_b32_e32 v208, 16, v7
	v_and_b32_e32 v209, 0xffff0000, v7
	v_pk_fma_f32 v[58:59], v[58:59], v[148:149], v[208:209]
	v_cvt_pk_bf16_f32 v0, v68, v69
	v_cvt_pk_bf16_f32 v1, v70, v71
	v_cvt_pk_bf16_f32 v2, v64, v65
	v_cvt_pk_bf16_f32 v3, v66, v67
	v_cvt_pk_bf16_f32 v4, v60, v61
	v_cvt_pk_bf16_f32 v5, v62, v63
	v_cvt_pk_bf16_f32 v6, v56, v57
	v_cvt_pk_bf16_f32 v7, v58, v59
	v_mul_f32_e32 v246, v69, v69
	v_mul_f32_e32 v248, v71, v71
	v_fmac_f32_e32 v246, v68, v68
	v_fmac_f32_e32 v248, v70, v70
	v_add_f32_e32 v246, v246, v248
	v_mul_f32_e32 v248, v65, v65
	v_fmac_f32_e32 v248, v64, v64
	v_add_f32_e32 v246, v246, v248
	v_mul_f32_e32 v248, v67, v67
	v_fmac_f32_e32 v248, v66, v66
	v_add_f32_e32 v246, v248, v246
	v_mul_f32_e32 v247, v61, v61
	v_mul_f32_e32 v248, v63, v63
	v_fmac_f32_e32 v247, v60, v60
	v_fmac_f32_e32 v248, v62, v62
	v_add_f32_e32 v247, v247, v248
	v_mul_f32_e32 v248, v57, v57
	v_fmac_f32_e32 v248, v56, v56
	v_add_f32_e32 v247, v247, v248
	v_mul_f32_e32 v248, v59, v59
	v_fmac_f32_e32 v248, v58, v58
	v_add_f32_e32 v247, v248, v247
	v_add_f32_e32 v246, v246, v247
	v_mov_b32_e32 v247, v246
	s_nop 1
	v_permlane16_swap_b32_e32 v246, v247
	s_nop 1
	v_add_f32_e32 v246, v246, v247
	v_mov_b32_e32 v247, v246
	s_nop 1
	v_permlane32_swap_b32_e32 v246, v247
	v_add_u32_e32 v248, s8, v223
	s_nop 0
	v_add_f32_e32 v246, v246, v247
	s_mov_b64 exec, s[44:45]
	ds_write_b32 v248, v246 offset:2048
	s_mov_b64 exec, -1
	s_add_u32 s2, s2, 0x28000
	s_addc_u32 s3, s3, 0
	s_add_u32 s18, s18, 0x28000
	s_addc_u32 s19, s19, 0
	s_mov_b64 vcc, s[6:7]
	v_cndmask_b32_dpp v68, v4, v0, vcc row_ror:8 row_mask:0xf bank_mask:0xf
	v_cndmask_b32_dpp v69, v5, v1, vcc row_ror:8 row_mask:0xf bank_mask:0xf
	v_cndmask_b32_dpp v70, v6, v2, vcc row_ror:8 row_mask:0xf bank_mask:0xf
	v_cndmask_b32_dpp v71, v7, v3, vcc row_ror:8 row_mask:0xf bank_mask:0xf
	s_not_b64 vcc, s[6:7]
	v_cndmask_b32_dpp v64, v0, v4, vcc row_ror:8 row_mask:0xf bank_mask:0xf
	v_cndmask_b32_dpp v65, v1, v5, vcc row_ror:8 row_mask:0xf bank_mask:0xf
	v_cndmask_b32_dpp v66, v2, v6, vcc row_ror:8 row_mask:0xf bank_mask:0xf
	v_cndmask_b32_dpp v67, v3, v7, vcc row_ror:8 row_mask:0xf bank_mask:0xf
	global_store_dwordx4 v171, v[68:71], s[2:3]
	global_store_dwordx4 v171, v[64:67], s[18:19]
	s_waitcnt vmcnt(10)
	s_mov_b64 vcc, s[6:7]
	v_cndmask_b32_dpp v0, v242, v238, vcc row_ror:8 row_mask:0xf bank_mask:0xf
	v_cndmask_b32_dpp v1, v243, v239, vcc row_ror:8 row_mask:0xf bank_mask:0xf
	v_cndmask_b32_dpp v2, v244, v240, vcc row_ror:8 row_mask:0xf bank_mask:0xf
	v_cndmask_b32_dpp v3, v245, v241, vcc row_ror:8 row_mask:0xf bank_mask:0xf
	s_not_b64 vcc, s[6:7]
	v_cndmask_b32_dpp v4, v238, v242, vcc row_ror:8 row_mask:0xf bank_mask:0xf
	v_cndmask_b32_dpp v5, v239, v243, vcc row_ror:8 row_mask:0xf bank_mask:0xf
	v_cndmask_b32_dpp v6, v240, v244, vcc row_ror:8 row_mask:0xf bank_mask:0xf
	v_cndmask_b32_dpp v7, v241, v245, vcc row_ror:8 row_mask:0xf bank_mask:0xf
	v_lshlrev_b32_e32 v246, 16, v0
	v_and_b32_e32 v247, 0xffff0000, v0
	v_pk_fma_f32 v[52:53], v[52:53], v[142:143], v[246:247]
	v_lshlrev_b32_e32 v248, 16, v1
	v_and_b32_e32 v249, 0xffff0000, v1
	v_pk_fma_f32 v[54:55], v[54:55], v[144:145], v[248:249]
	v_lshlrev_b32_e32 v250, 16, v2
	v_and_b32_e32 v251, 0xffff0000, v2
	v_pk_fma_f32 v[48:49], v[48:49], v[150:151], v[250:251]
	v_lshlrev_b32_e32 v208, 16, v3
	v_and_b32_e32 v209, 0xffff0000, v3
	v_pk_fma_f32 v[50:51], v[50:51], v[152:153], v[208:209]
	v_lshlrev_b32_e32 v246, 16, v4
	v_and_b32_e32 v247, 0xffff0000, v4
	v_pk_fma_f32 v[44:45], v[44:45], v[138:139], v[246:247]
	v_lshlrev_b32_e32 v248, 16, v5
	v_and_b32_e32 v249, 0xffff0000, v5
	v_pk_fma_f32 v[46:47], v[46:47], v[140:141], v[248:249]
	v_lshlrev_b32_e32 v250, 16, v6
	v_and_b32_e32 v251, 0xffff0000, v6
	v_pk_fma_f32 v[40:41], v[40:41], v[146:147], v[250:251]
	v_lshlrev_b32_e32 v208, 16, v7
	v_and_b32_e32 v209, 0xffff0000, v7
	v_pk_fma_f32 v[42:43], v[42:43], v[148:149], v[208:209]
	v_cvt_pk_bf16_f32 v0, v52, v53
	v_cvt_pk_bf16_f32 v1, v54, v55
	v_cvt_pk_bf16_f32 v2, v48, v49
	v_cvt_pk_bf16_f32 v3, v50, v51
	v_cvt_pk_bf16_f32 v4, v44, v45
	v_cvt_pk_bf16_f32 v5, v46, v47
	v_cvt_pk_bf16_f32 v6, v40, v41
	v_cvt_pk_bf16_f32 v7, v42, v43
	v_mul_f32_e32 v246, v53, v53
	v_mul_f32_e32 v248, v55, v55
	v_fmac_f32_e32 v246, v52, v52
	v_fmac_f32_e32 v248, v54, v54
	v_add_f32_e32 v246, v246, v248
	v_mul_f32_e32 v248, v49, v49
	v_fmac_f32_e32 v248, v48, v48
	v_add_f32_e32 v246, v246, v248
	v_mul_f32_e32 v248, v51, v51
	v_fmac_f32_e32 v248, v50, v50
	v_add_f32_e32 v246, v248, v246
	v_mul_f32_e32 v247, v45, v45
	v_mul_f32_e32 v248, v47, v47
	v_fmac_f32_e32 v247, v44, v44
	v_fmac_f32_e32 v248, v46, v46
	v_add_f32_e32 v247, v247, v248
	v_mul_f32_e32 v248, v41, v41
	v_fmac_f32_e32 v248, v40, v40
	v_add_f32_e32 v247, v247, v248
	v_mul_f32_e32 v248, v43, v43
	v_fmac_f32_e32 v248, v42, v42
	v_add_f32_e32 v247, v248, v247
	v_add_f32_e32 v246, v246, v247
	v_mov_b32_e32 v247, v246
	s_nop 1
	v_permlane16_swap_b32_e32 v246, v247
	s_nop 1
	v_add_f32_e32 v246, v246, v247
	v_mov_b32_e32 v247, v246
	s_nop 1
	v_permlane32_swap_b32_e32 v246, v247
	v_add_u32_e32 v248, s8, v223
	s_nop 0
	v_add_f32_e32 v246, v246, v247
	s_mov_b64 exec, s[44:45]
	ds_write_b32 v248, v246 offset:2304
	s_mov_b64 exec, -1
	s_add_u32 s2, s2, 0x8000
	s_addc_u32 s3, s3, 0
	s_add_u32 s18, s18, 0x8000
	s_addc_u32 s19, s19, 0
	s_mov_b64 vcc, s[6:7]
	v_cndmask_b32_dpp v52, v4, v0, vcc row_ror:8 row_mask:0xf bank_mask:0xf
	v_cndmask_b32_dpp v53, v5, v1, vcc row_ror:8 row_mask:0xf bank_mask:0xf
	v_cndmask_b32_dpp v54, v6, v2, vcc row_ror:8 row_mask:0xf bank_mask:0xf
	v_cndmask_b32_dpp v55, v7, v3, vcc row_ror:8 row_mask:0xf bank_mask:0xf
	s_not_b64 vcc, s[6:7]
	v_cndmask_b32_dpp v48, v0, v4, vcc row_ror:8 row_mask:0xf bank_mask:0xf
	v_cndmask_b32_dpp v49, v1, v5, vcc row_ror:8 row_mask:0xf bank_mask:0xf
	v_cndmask_b32_dpp v50, v2, v6, vcc row_ror:8 row_mask:0xf bank_mask:0xf
	v_cndmask_b32_dpp v51, v3, v7, vcc row_ror:8 row_mask:0xf bank_mask:0xf
	global_store_dwordx4 v171, v[52:55], s[2:3]
	global_store_dwordx4 v171, v[48:51], s[18:19]
	s_waitcnt vmcnt(8)
	s_mov_b64 vcc, s[6:7]
	v_cndmask_b32_dpp v0, v200, v196, vcc row_ror:8 row_mask:0xf bank_mask:0xf
	v_cndmask_b32_dpp v1, v201, v197, vcc row_ror:8 row_mask:0xf bank_mask:0xf
	v_cndmask_b32_dpp v2, v202, v198, vcc row_ror:8 row_mask:0xf bank_mask:0xf
	v_cndmask_b32_dpp v3, v203, v199, vcc row_ror:8 row_mask:0xf bank_mask:0xf
	s_not_b64 vcc, s[6:7]
	v_cndmask_b32_dpp v4, v196, v200, vcc row_ror:8 row_mask:0xf bank_mask:0xf
	v_cndmask_b32_dpp v5, v197, v201, vcc row_ror:8 row_mask:0xf bank_mask:0xf
	v_cndmask_b32_dpp v6, v198, v202, vcc row_ror:8 row_mask:0xf bank_mask:0xf
	v_cndmask_b32_dpp v7, v199, v203, vcc row_ror:8 row_mask:0xf bank_mask:0xf
	v_lshlrev_b32_e32 v246, 16, v0
	v_and_b32_e32 v247, 0xffff0000, v0
	v_pk_fma_f32 v[36:37], v[36:37], v[142:143], v[246:247]
	v_lshlrev_b32_e32 v248, 16, v1
	v_and_b32_e32 v249, 0xffff0000, v1
	v_pk_fma_f32 v[38:39], v[38:39], v[144:145], v[248:249]
	v_lshlrev_b32_e32 v250, 16, v2
	v_and_b32_e32 v251, 0xffff0000, v2
	v_pk_fma_f32 v[32:33], v[32:33], v[150:151], v[250:251]
	v_lshlrev_b32_e32 v208, 16, v3
	v_and_b32_e32 v209, 0xffff0000, v3
	v_pk_fma_f32 v[34:35], v[34:35], v[152:153], v[208:209]
	v_lshlrev_b32_e32 v246, 16, v4
	v_and_b32_e32 v247, 0xffff0000, v4
	v_pk_fma_f32 v[28:29], v[28:29], v[138:139], v[246:247]
	v_lshlrev_b32_e32 v248, 16, v5
	v_and_b32_e32 v249, 0xffff0000, v5
	v_pk_fma_f32 v[30:31], v[30:31], v[140:141], v[248:249]
	v_lshlrev_b32_e32 v250, 16, v6
	v_and_b32_e32 v251, 0xffff0000, v6
	v_pk_fma_f32 v[24:25], v[24:25], v[146:147], v[250:251]
	v_lshlrev_b32_e32 v208, 16, v7
	v_and_b32_e32 v209, 0xffff0000, v7
	v_pk_fma_f32 v[26:27], v[26:27], v[148:149], v[208:209]
	v_cvt_pk_bf16_f32 v0, v36, v37
	v_cvt_pk_bf16_f32 v1, v38, v39
	v_cvt_pk_bf16_f32 v2, v32, v33
	v_cvt_pk_bf16_f32 v3, v34, v35
	v_cvt_pk_bf16_f32 v4, v28, v29
	v_cvt_pk_bf16_f32 v5, v30, v31
	v_cvt_pk_bf16_f32 v6, v24, v25
	v_cvt_pk_bf16_f32 v7, v26, v27
	v_mul_f32_e32 v246, v37, v37
	v_mul_f32_e32 v248, v39, v39
	v_fmac_f32_e32 v246, v36, v36
	v_fmac_f32_e32 v248, v38, v38
	v_add_f32_e32 v246, v246, v248
	v_mul_f32_e32 v248, v33, v33
	v_fmac_f32_e32 v248, v32, v32
	v_add_f32_e32 v246, v246, v248
	v_mul_f32_e32 v248, v35, v35
	v_fmac_f32_e32 v248, v34, v34
	v_add_f32_e32 v246, v248, v246
	v_mul_f32_e32 v247, v29, v29
	v_mul_f32_e32 v248, v31, v31
	v_fmac_f32_e32 v247, v28, v28
	v_fmac_f32_e32 v248, v30, v30
	v_add_f32_e32 v247, v247, v248
	v_mul_f32_e32 v248, v25, v25
	v_fmac_f32_e32 v248, v24, v24
	v_add_f32_e32 v247, v247, v248
	v_mul_f32_e32 v248, v27, v27
	v_fmac_f32_e32 v248, v26, v26
	v_add_f32_e32 v247, v248, v247
	v_add_f32_e32 v246, v246, v247
	v_mov_b32_e32 v247, v246
	s_nop 1
	v_permlane16_swap_b32_e32 v246, v247
	s_nop 1
	v_add_f32_e32 v246, v246, v247
	v_mov_b32_e32 v247, v246
	s_nop 1
	v_permlane32_swap_b32_e32 v246, v247
	v_add_u32_e32 v248, s8, v223
	s_nop 0
	v_add_f32_e32 v246, v246, v247
	s_mov_b64 exec, s[44:45]
	ds_write_b32 v248, v246 offset:2560
	s_mov_b64 exec, -1
	s_add_u32 s2, s2, 0x8000
	s_addc_u32 s3, s3, 0
	s_add_u32 s18, s18, 0x8000
	s_addc_u32 s19, s19, 0
	s_mov_b64 vcc, s[6:7]
	v_cndmask_b32_dpp v36, v4, v0, vcc row_ror:8 row_mask:0xf bank_mask:0xf
	v_cndmask_b32_dpp v37, v5, v1, vcc row_ror:8 row_mask:0xf bank_mask:0xf
	v_cndmask_b32_dpp v38, v6, v2, vcc row_ror:8 row_mask:0xf bank_mask:0xf
	v_cndmask_b32_dpp v39, v7, v3, vcc row_ror:8 row_mask:0xf bank_mask:0xf
	s_not_b64 vcc, s[6:7]
	v_cndmask_b32_dpp v32, v0, v4, vcc row_ror:8 row_mask:0xf bank_mask:0xf
	v_cndmask_b32_dpp v33, v1, v5, vcc row_ror:8 row_mask:0xf bank_mask:0xf
	v_cndmask_b32_dpp v34, v2, v6, vcc row_ror:8 row_mask:0xf bank_mask:0xf
	v_cndmask_b32_dpp v35, v3, v7, vcc row_ror:8 row_mask:0xf bank_mask:0xf
	global_store_dwordx4 v171, v[36:39], s[2:3]
	global_store_dwordx4 v171, v[32:35], s[18:19]
	s_waitcnt vmcnt(6)
	s_mov_b64 vcc, s[6:7]
	v_cndmask_b32_dpp v0, v234, v204, vcc row_ror:8 row_mask:0xf bank_mask:0xf
	v_cndmask_b32_dpp v1, v235, v205, vcc row_ror:8 row_mask:0xf bank_mask:0xf
	v_cndmask_b32_dpp v2, v236, v206, vcc row_ror:8 row_mask:0xf bank_mask:0xf
	v_cndmask_b32_dpp v3, v237, v207, vcc row_ror:8 row_mask:0xf bank_mask:0xf
	s_not_b64 vcc, s[6:7]
	v_cndmask_b32_dpp v4, v204, v234, vcc row_ror:8 row_mask:0xf bank_mask:0xf
	v_cndmask_b32_dpp v5, v205, v235, vcc row_ror:8 row_mask:0xf bank_mask:0xf
	v_cndmask_b32_dpp v6, v206, v236, vcc row_ror:8 row_mask:0xf bank_mask:0xf
	v_cndmask_b32_dpp v7, v207, v237, vcc row_ror:8 row_mask:0xf bank_mask:0xf
	v_lshlrev_b32_e32 v246, 16, v0
	v_and_b32_e32 v247, 0xffff0000, v0
	v_pk_fma_f32 v[20:21], v[20:21], v[142:143], v[246:247]
	v_lshlrev_b32_e32 v248, 16, v1
	v_and_b32_e32 v249, 0xffff0000, v1
	v_pk_fma_f32 v[22:23], v[22:23], v[144:145], v[248:249]
	v_lshlrev_b32_e32 v250, 16, v2
	v_and_b32_e32 v251, 0xffff0000, v2
	v_pk_fma_f32 v[16:17], v[16:17], v[150:151], v[250:251]
	v_lshlrev_b32_e32 v208, 16, v3
	v_and_b32_e32 v209, 0xffff0000, v3
	v_pk_fma_f32 v[18:19], v[18:19], v[152:153], v[208:209]
	v_lshlrev_b32_e32 v246, 16, v4
	v_and_b32_e32 v247, 0xffff0000, v4
	v_pk_fma_f32 v[12:13], v[12:13], v[138:139], v[246:247]
	v_lshlrev_b32_e32 v248, 16, v5
	v_and_b32_e32 v249, 0xffff0000, v5
	v_pk_fma_f32 v[14:15], v[14:15], v[140:141], v[248:249]
	v_lshlrev_b32_e32 v250, 16, v6
	v_and_b32_e32 v251, 0xffff0000, v6
	v_pk_fma_f32 v[8:9], v[8:9], v[146:147], v[250:251]
	v_lshlrev_b32_e32 v208, 16, v7
	v_and_b32_e32 v209, 0xffff0000, v7
	v_pk_fma_f32 v[10:11], v[10:11], v[148:149], v[208:209]
	v_cvt_pk_bf16_f32 v0, v20, v21
	v_cvt_pk_bf16_f32 v1, v22, v23
	v_cvt_pk_bf16_f32 v2, v16, v17
	v_cvt_pk_bf16_f32 v3, v18, v19
	v_cvt_pk_bf16_f32 v4, v12, v13
	v_cvt_pk_bf16_f32 v5, v14, v15
	v_cvt_pk_bf16_f32 v6, v8, v9
	v_cvt_pk_bf16_f32 v7, v10, v11
	v_mul_f32_e32 v246, v21, v21
	v_mul_f32_e32 v248, v23, v23
	v_fmac_f32_e32 v246, v20, v20
	v_fmac_f32_e32 v248, v22, v22
	v_add_f32_e32 v246, v246, v248
	v_mul_f32_e32 v248, v17, v17
	v_fmac_f32_e32 v248, v16, v16
	v_add_f32_e32 v246, v246, v248
	v_mul_f32_e32 v248, v19, v19
	v_fmac_f32_e32 v248, v18, v18
	v_add_f32_e32 v246, v248, v246
	v_mul_f32_e32 v247, v13, v13
	v_mul_f32_e32 v248, v15, v15
	v_fmac_f32_e32 v247, v12, v12
	v_fmac_f32_e32 v248, v14, v14
	v_add_f32_e32 v247, v247, v248
	v_mul_f32_e32 v248, v9, v9
	v_fmac_f32_e32 v248, v8, v8
	v_add_f32_e32 v247, v247, v248
	v_mul_f32_e32 v248, v11, v11
	v_fmac_f32_e32 v248, v10, v10
	v_add_f32_e32 v247, v248, v247
	v_add_f32_e32 v246, v246, v247
	v_mov_b32_e32 v247, v246
	s_nop 1
	v_permlane16_swap_b32_e32 v246, v247
	s_nop 1
	v_add_f32_e32 v246, v246, v247
	v_mov_b32_e32 v247, v246
	s_nop 1
	v_permlane32_swap_b32_e32 v246, v247
	v_add_u32_e32 v248, s8, v223
	s_nop 0
	v_add_f32_e32 v246, v246, v247
	s_mov_b64 exec, s[44:45]
	ds_write_b32 v248, v246 offset:2816
	s_mov_b64 exec, -1
	s_add_u32 s2, s2, 0x8000
	s_addc_u32 s3, s3, 0
	s_add_u32 s18, s18, 0x8000
	s_addc_u32 s19, s19, 0
	s_mov_b64 vcc, s[6:7]
	v_cndmask_b32_dpp v20, v4, v0, vcc row_ror:8 row_mask:0xf bank_mask:0xf
	v_cndmask_b32_dpp v21, v5, v1, vcc row_ror:8 row_mask:0xf bank_mask:0xf
	v_cndmask_b32_dpp v22, v6, v2, vcc row_ror:8 row_mask:0xf bank_mask:0xf
	v_cndmask_b32_dpp v23, v7, v3, vcc row_ror:8 row_mask:0xf bank_mask:0xf
	s_not_b64 vcc, s[6:7]
	v_cndmask_b32_dpp v16, v0, v4, vcc row_ror:8 row_mask:0xf bank_mask:0xf
	v_cndmask_b32_dpp v17, v1, v5, vcc row_ror:8 row_mask:0xf bank_mask:0xf
	v_cndmask_b32_dpp v18, v2, v6, vcc row_ror:8 row_mask:0xf bank_mask:0xf
	v_cndmask_b32_dpp v19, v3, v7, vcc row_ror:8 row_mask:0xf bank_mask:0xf
	global_store_dwordx4 v171, v[20:23], s[2:3]
	global_store_dwordx4 v171, v[16:19], s[18:19]
	s_mov_b32 s100, 1
	s_branch .LBB0_714
.LBB0_721:
	s_mov_b32 s100, 0
	v_readlane_b32 s2, v252, 26
	v_readlane_b32 s3, v252, 27
	s_and_b64 s[2:3], s[2:3], exec
	s_cselect_b32 s10, 8, 10
	s_cselect_b32 s2, 0x88, 0
	s_mul_i32 s28, s10, 0x102
	s_add_i32 s30, s28, s2
	s_cmp_lt_i32 s80, s30
	s_waitcnt vmcnt(0)
	v_mov_b32 v0, v210
	s_cselect_b64 s[4:5], -1, 0
	s_cmp_ge_i32 s80, s30
	v_readfirstlane_b32 s11, v0
	s_cbranch_scc1 .LBB0_730
	s_ashr_i32 s81, s80, 31
	s_not_b64 s[2:3], s[80:81]
	s_add_u32 s6, s30, s2
	s_addc_u32 s7, 0, s3
	s_and_b64 s[2:3], s[82:83], exec
	s_cselect_b32 s7, s7, s81
	s_cselect_b32 s6, s6, s80
	v_mov_b32_e32 v96, s28
	v_cmp_lt_i64_e32 vcc, s[6:7], v[96:97]
	s_mov_b64 s[8:9], -1
	s_cbranch_vccnz .LBB0_724
	s_sub_i32 s2, s6, s28
	s_ashr_i32 s3, s2, 2
	s_and_b32 s2, s6, 3
	s_lshl_b32 s7, s3, 3
	s_or_b32 s2, s2, 8
	s_or_b32 s7, s7, 7
	s_add_i32 s8, s3, 0xe0
	s_cmp_lt_i32 s3, 32
	s_cselect_b32 s36, s7, s8
	s_mov_b64 s[8:9], 0

.LBB0_749:
	s_ashr_i32 s49, s48, 31
	s_waitcnt lgkmcnt(0)
	s_lshl_b64 s[14:15], s[48:49], 19
	s_add_u32 s38, s22, s14
	s_addc_u32 s39, s23, s15
	s_and_b64 s[14:15], s[8:9], exec
	s_cselect_b32 s3, s39, s5
	s_cselect_b32 s16, s38, s4
	s_ashr_i32 s35, s34, 31
	s_lshl_b64 s[14:15], s[34:35], 19
	s_add_u32 s40, s56, s14
	s_addc_u32 s41, s57, s15
	s_and_b64 s[14:15], s[8:9], exec
	s_cselect_b32 s17, s41, s13
	s_cselect_b32 s18, s40, s12
	s_add_u32 s4, s4, 0x40080
	s_addc_u32 s5, s5, 0
	s_add_u32 s19, s12, 0x100
	s_addc_u32 s26, s13, 0
	s_mov_b32 s27, -2
	s_add_u32 s12, s4, 0xfffc0080
	s_addc_u32 s13, s5, -1
	s_add_i32 s33, 0, 0x10000
	s_cmp_eq_u32 s27, 12
	s_cselect_b32 s15, s3, s13
	s_cselect_b32 s14, s16, s12
	v_add_u32_e32 v96, s33, v165
	s_cselect_b32 s13, s17, s26
	s_cselect_b32 s12, s18, s19
	s_add_i32 s35, 0, 0x14000
	ds_read_b128 v[0:3], v96
	ds_read_b128 v[4:7], v96 offset:1024
	ds_read_b128 v[138:141], v96 offset:2048
	ds_read_b128 v[142:145], v96 offset:3072
	v_add_u32_e32 v96, s35, v165
	ds_read_b128 v[146:149], v96
	ds_read_b128 v[150:153], v96 offset:1024
	ds_read_b128 v[182:185], v96 offset:2048
	ds_read_b128 v[186:189], v96 offset:3072
	v_lshl_add_u64 v[238:239], s[4:5], 0, v[168:169]
	s_add_i32 m0, s79, 0xc000
	ds_read_b128 v[190:193], v221
	ds_read_b128 v[194:197], v221 offset:1024
	ds_read_b128 v[198:201], v221 offset:2048
	ds_read_b128 v[202:205], v221 offset:3072
	ds_read_b128 v[222:225], v221 offset:4096
	ds_read_b128 v[226:229], v221 offset:5120
	ds_read_b128 v[230:233], v221 offset:6144
	ds_read_b128 v[234:237], v221 offset:7168
	global_load_lds_dwordx4 v[238:239], off
	v_lshl_add_u64 v[238:239], s[4:5], 0, v[170:171]
	s_add_i32 m0, s79, 0xe000
	s_nop 0
	global_load_lds_dwordx4 v[238:239], off
	s_cmp_lg_u32 s100, 0
	s_cbranch_scc1 .Lpl_in_r1
	s_waitcnt vmcnt(8)
	s_branch .Lpl_in_j1

.Lpl_in_j1:
	s_waitcnt lgkmcnt(0)
	s_barrier
	s_setprio 1
	s_waitcnt lgkmcnt(0)
	v_mfma_f32_16x16x32_bf16 v[134:137], v[0:3], v[190:193], 0
	v_mfma_f32_16x16x32_bf16 v[130:133], v[138:141], v[190:193], 0
	v_mfma_f32_16x16x32_bf16 v[118:121], v[0:3], v[198:201], 0
	v_mfma_f32_16x16x32_bf16 v[114:117], v[138:141], v[198:201], 0
	v_mfma_f32_16x16x32_bf16 v[102:105], v[0:3], v[222:225], 0
	v_mfma_f32_16x16x32_bf16 v[98:101], v[138:141], v[222:225], 0
	v_mfma_f32_16x16x32_bf16 v[84:87], v[0:3], v[230:233], 0
	v_mfma_f32_16x16x32_bf16 v[80:83], v[138:141], v[230:233], 0
	v_mfma_f32_16x16x32_bf16 v[134:137], v[4:7], v[194:197], v[134:137]
	v_mfma_f32_16x16x32_bf16 v[130:133], v[142:145], v[194:197], v[130:133]
	v_mfma_f32_16x16x32_bf16 v[118:121], v[4:7], v[202:205], v[118:121]
	v_mfma_f32_16x16x32_bf16 v[114:117], v[142:145], v[202:205], v[114:117]
	v_mfma_f32_16x16x32_bf16 v[102:105], v[4:7], v[226:229], v[102:105]
	v_mfma_f32_16x16x32_bf16 v[98:101], v[142:145], v[226:229], v[98:101]
	v_mfma_f32_16x16x32_bf16 v[84:87], v[4:7], v[234:237], v[84:87]
	v_mfma_f32_16x16x32_bf16 v[80:83], v[142:145], v[234:237], v[80:83]
	s_setprio 0
	s_setprio 1
	v_mfma_f32_16x16x32_bf16 v[126:129], v[146:149], v[190:193], 0
	v_mfma_f32_16x16x32_bf16 v[122:125], v[182:185], v[190:193], 0
	v_mfma_f32_16x16x32_bf16 v[110:113], v[146:149], v[198:201], 0
	v_mfma_f32_16x16x32_bf16 v[106:109], v[182:185], v[198:201], 0
	v_mfma_f32_16x16x32_bf16 v[92:95], v[146:149], v[222:225], 0
	v_mfma_f32_16x16x32_bf16 v[88:91], v[182:185], v[222:225], 0
	v_mfma_f32_16x16x32_bf16 v[76:79], v[146:149], v[230:233], 0
	v_mfma_f32_16x16x32_bf16 v[72:75], v[182:185], v[230:233], 0
	v_mfma_f32_16x16x32_bf16 v[126:129], v[150:153], v[194:197], v[126:129]
	v_mfma_f32_16x16x32_bf16 v[122:125], v[186:189], v[194:197], v[122:125]
	v_mfma_f32_16x16x32_bf16 v[110:113], v[150:153], v[202:205], v[110:113]
	v_mfma_f32_16x16x32_bf16 v[106:109], v[186:189], v[202:205], v[106:109]
	v_mfma_f32_16x16x32_bf16 v[92:95], v[150:153], v[226:229], v[92:95]
	v_mfma_f32_16x16x32_bf16 v[88:91], v[186:189], v[226:229], v[88:91]
	v_mfma_f32_16x16x32_bf16 v[76:79], v[150:153], v[234:237], v[76:79]
	v_mfma_f32_16x16x32_bf16 v[72:75], v[186:189], v[234:237], v[72:75]
	s_setprio 0
	s_barrier
	s_add_i32 s33, s33, s78
	v_lshl_add_u64 v[238:239], s[12:13], 0, v[156:157]
	s_mov_b32 m0, s33
	ds_read_b128 v[190:193], v221 offset:16384
	ds_read_b128 v[194:197], v221 offset:17408
	ds_read_b128 v[198:201], v221 offset:18432
	ds_read_b128 v[202:205], v221 offset:19456
	ds_read_b128 v[222:225], v221 offset:20480
	ds_read_b128 v[226:229], v221 offset:21504
	ds_read_b128 v[230:233], v221 offset:22528
	ds_read_b128 v[234:237], v221 offset:23552
	global_load_lds_dwordx4 v[238:239], off
	s_add_i32 m0, s33, 0x2000
	s_add_u32 s42, s12, 0x10000
	v_lshl_add_u64 v[240:241], s[12:13], 0, v[160:161]
	s_addc_u32 s43, s13, 0
	s_add_i32 s33, s35, s78
	global_load_lds_dwordx4 v[240:241], off
	v_lshl_add_u64 v[242:243], s[42:43], 0, v[156:157]
	s_mov_b32 m0, s33
	v_lshl_add_u64 v[244:245], s[14:15], 0, v[158:159]
	global_load_lds_dwordx4 v[242:243], off
	v_lshl_add_u64 v[242:243], s[42:43], 0, v[160:161]
	s_add_i32 m0, s33, 0x2000
	s_nop 0
	global_load_lds_dwordx4 v[242:243], off
	v_lshl_add_u64 v[242:243], s[14:15], 0, v[154:155]
	s_mov_b32 m0, s79
	s_nop 0
	global_load_lds_dwordx4 v[242:243], off
	s_mov_b32 m0, s81
	s_nop 0
	global_load_lds_dwordx4 v[244:245], off
	s_cmp_lg_u32 s100, 0
	s_cbranch_scc1 .Lpl_in_r2
	s_waitcnt vmcnt(8)
	s_branch .Lpl_in_j2

.Lpl_in_j2:
	s_mov_b32 s100, 0
	s_waitcnt lgkmcnt(0)
	s_barrier
	s_setprio 1
	s_waitcnt lgkmcnt(0)
	v_mfma_f32_16x16x32_bf16 v[68:71], v[0:3], v[190:193], 0
	v_mfma_f32_16x16x32_bf16 v[64:67], v[138:141], v[190:193], 0
	v_mfma_f32_16x16x32_bf16 v[52:55], v[0:3], v[198:201], 0
	v_mfma_f32_16x16x32_bf16 v[48:51], v[138:141], v[198:201], 0
	v_mfma_f32_16x16x32_bf16 v[36:39], v[0:3], v[222:225], 0
	v_mfma_f32_16x16x32_bf16 v[32:35], v[138:141], v[222:225], 0
	v_mfma_f32_16x16x32_bf16 v[0:3], v[0:3], v[230:233], 0
	v_mfma_f32_16x16x32_bf16 v[68:71], v[4:7], v[194:197], v[68:71]
	v_mfma_f32_16x16x32_bf16 v[64:67], v[142:145], v[194:197], v[64:67]
	v_mfma_f32_16x16x32_bf16 v[52:55], v[4:7], v[202:205], v[52:55]
	v_mfma_f32_16x16x32_bf16 v[48:51], v[142:145], v[202:205], v[48:51]
	v_mfma_f32_16x16x32_bf16 v[36:39], v[4:7], v[226:229], v[36:39]
	v_mfma_f32_16x16x32_bf16 v[32:35], v[142:145], v[226:229], v[32:35]
	v_mfma_f32_16x16x32_bf16 v[0:3], v[4:7], v[234:237], v[0:3]
	v_mfma_f32_16x16x32_bf16 v[4:7], v[138:141], v[230:233], 0
	v_mfma_f32_16x16x32_bf16 v[4:7], v[142:145], v[234:237], v[4:7]
	s_setprio 0
	s_setprio 1
	v_mfma_f32_16x16x32_bf16 v[16:19], v[146:149], v[190:193], 0
	v_mfma_f32_16x16x32_bf16 v[60:63], v[150:153], v[194:197], v[16:19]
	v_mfma_f32_16x16x32_bf16 v[16:19], v[182:185], v[190:193], 0
	v_mfma_f32_16x16x32_bf16 v[56:59], v[186:189], v[194:197], v[16:19]
	v_mfma_f32_16x16x32_bf16 v[16:19], v[146:149], v[198:201], 0
	v_mfma_f32_16x16x32_bf16 v[44:47], v[150:153], v[202:205], v[16:19]
	v_mfma_f32_16x16x32_bf16 v[16:19], v[182:185], v[198:201], 0
	v_mfma_f32_16x16x32_bf16 v[40:43], v[186:189], v[202:205], v[16:19]
	v_mfma_f32_16x16x32_bf16 v[16:19], v[146:149], v[222:225], 0
	v_mfma_f32_16x16x32_bf16 v[28:31], v[150:153], v[226:229], v[16:19]
	v_mfma_f32_16x16x32_bf16 v[16:19], v[182:185], v[222:225], 0
	v_mfma_f32_16x16x32_bf16 v[12:15], v[146:149], v[230:233], 0
	v_mfma_f32_16x16x32_bf16 v[8:11], v[182:185], v[230:233], 0
	v_mfma_f32_16x16x32_bf16 v[24:27], v[186:189], v[226:229], v[16:19]
	v_mfma_f32_16x16x32_bf16 v[12:15], v[150:153], v[234:237], v[12:15]
	v_mfma_f32_16x16x32_bf16 v[8:11], v[186:189], v[234:237], v[8:11]
	s_setprio 0
	s_barrier
	v_add_u32_e32 v96, s67, v165
	s_add_i32 s33, 0, 0x1c000
	ds_read_b128 v[16:19], v96
	ds_read_b128 v[20:23], v96 offset:1024
	ds_read_b128 v[138:141], v96 offset:2048
	ds_read_b128 v[142:145], v96 offset:3072
	v_add_u32_e32 v96, s33, v165
	ds_read_b128 v[146:149], v96
	ds_read_b128 v[150:153], v96 offset:1024
	ds_read_b128 v[182:185], v96 offset:2048
	ds_read_b128 v[186:189], v96 offset:3072
	s_add_u32 s14, s14, 0x40000
	s_addc_u32 s15, s15, 0
	s_mov_b32 m0, s92
	v_lshl_add_u64 v[246:247], s[14:15], 0, v[154:155]
	ds_read_b128 v[190:193], v221 offset:32768
	ds_read_b128 v[194:197], v221 offset:33792
	ds_read_b128 v[198:201], v221 offset:34816
	ds_read_b128 v[202:205], v221 offset:35840
	ds_read_b128 v[222:225], v221 offset:36864
	ds_read_b128 v[226:229], v221 offset:37888
	ds_read_b128 v[230:233], v221 offset:38912
	ds_read_b128 v[234:237], v221 offset:39936
	global_load_lds_dwordx4 v[246:247], off
	v_lshl_add_u64 v[246:247], s[14:15], 0, v[158:159]
	s_mov_b32 m0, s93
	s_nop 0
	global_load_lds_dwordx4 v[246:247], off
	s_waitcnt vmcnt(8)
	s_waitcnt lgkmcnt(0)
	s_barrier
	s_setprio 1
	s_waitcnt lgkmcnt(0)
	v_mfma_f32_16x16x32_bf16 v[134:137], v[16:19], v[190:193], v[134:137]
	v_mfma_f32_16x16x32_bf16 v[130:133], v[138:141], v[190:193], v[130:133]
	v_mfma_f32_16x16x32_bf16 v[118:121], v[16:19], v[198:201], v[118:121]
	v_mfma_f32_16x16x32_bf16 v[114:117], v[138:141], v[198:201], v[114:117]
	v_mfma_f32_16x16x32_bf16 v[102:105], v[16:19], v[222:225], v[102:105]
	v_mfma_f32_16x16x32_bf16 v[98:101], v[138:141], v[222:225], v[98:101]
	v_mfma_f32_16x16x32_bf16 v[84:87], v[16:19], v[230:233], v[84:87]
	v_mfma_f32_16x16x32_bf16 v[80:83], v[138:141], v[230:233], v[80:83]
	v_mfma_f32_16x16x32_bf16 v[134:137], v[20:23], v[194:197], v[134:137]
	v_mfma_f32_16x16x32_bf16 v[130:133], v[142:145], v[194:197], v[130:133]
	v_mfma_f32_16x16x32_bf16 v[118:121], v[20:23], v[202:205], v[118:121]
	v_mfma_f32_16x16x32_bf16 v[114:117], v[142:145], v[202:205], v[114:117]
	v_mfma_f32_16x16x32_bf16 v[102:105], v[20:23], v[226:229], v[102:105]
	v_mfma_f32_16x16x32_bf16 v[98:101], v[142:145], v[226:229], v[98:101]
	v_mfma_f32_16x16x32_bf16 v[84:87], v[20:23], v[234:237], v[84:87]
	v_mfma_f32_16x16x32_bf16 v[80:83], v[142:145], v[234:237], v[80:83]
	s_setprio 0
	s_setprio 1
	v_mfma_f32_16x16x32_bf16 v[126:129], v[146:149], v[190:193], v[126:129]
	v_mfma_f32_16x16x32_bf16 v[122:125], v[182:185], v[190:193], v[122:125]
	v_mfma_f32_16x16x32_bf16 v[110:113], v[146:149], v[198:201], v[110:113]
	v_mfma_f32_16x16x32_bf16 v[106:109], v[182:185], v[198:201], v[106:109]
	v_mfma_f32_16x16x32_bf16 v[92:95], v[146:149], v[222:225], v[92:95]
	v_mfma_f32_16x16x32_bf16 v[88:91], v[182:185], v[222:225], v[88:91]
	v_mfma_f32_16x16x32_bf16 v[76:79], v[146:149], v[230:233], v[76:79]
	v_mfma_f32_16x16x32_bf16 v[72:75], v[182:185], v[230:233], v[72:75]
	v_mfma_f32_16x16x32_bf16 v[126:129], v[150:153], v[194:197], v[126:129]
	v_mfma_f32_16x16x32_bf16 v[122:125], v[186:189], v[194:197], v[122:125]
	v_mfma_f32_16x16x32_bf16 v[110:113], v[150:153], v[202:205], v[110:113]
	v_mfma_f32_16x16x32_bf16 v[106:109], v[186:189], v[202:205], v[106:109]
	v_mfma_f32_16x16x32_bf16 v[92:95], v[150:153], v[226:229], v[92:95]
	v_mfma_f32_16x16x32_bf16 v[88:91], v[186:189], v[226:229], v[88:91]
	v_mfma_f32_16x16x32_bf16 v[76:79], v[150:153], v[234:237], v[76:79]
	v_mfma_f32_16x16x32_bf16 v[72:75], v[186:189], v[234:237], v[72:75]
	s_setprio 0
	s_barrier
	s_add_i32 s14, s67, s78
	v_lshl_add_u64 v[238:239], v[238:239], 0, s[62:63]
	s_mov_b32 m0, s14
	ds_read_b128 v[190:193], v221 offset:49152
	ds_read_b128 v[194:197], v221 offset:50176
	ds_read_b128 v[198:201], v221 offset:51200
	ds_read_b128 v[202:205], v221 offset:52224
	ds_read_b128 v[222:225], v221 offset:53248
	ds_read_b128 v[226:229], v221 offset:54272
	ds_read_b128 v[230:233], v221 offset:55296
	ds_read_b128 v[234:237], v221 offset:56320
	global_load_lds_dwordx4 v[238:239], off
	s_add_i32 m0, s14, 0x2000
	s_add_u32 s12, s12, 0x10080
	v_lshl_add_u64 v[238:239], v[240:241], 0, s[62:63]
	s_addc_u32 s13, s13, 0
	s_add_i32 s14, s33, s78
	global_load_lds_dwordx4 v[238:239], off
	v_lshl_add_u64 v[238:239], s[12:13], 0, v[156:157]
	s_mov_b32 m0, s14
	s_nop 0
	global_load_lds_dwordx4 v[238:239], off
	v_lshl_add_u64 v[238:239], s[12:13], 0, v[160:161]
	s_add_i32 m0, s14, 0x2000
	s_nop 0
	global_load_lds_dwordx4 v[238:239], off
	v_lshl_add_u64 v[238:239], v[242:243], 0, s[62:63]
	s_mov_b32 m0, s21
	s_nop 0
	global_load_lds_dwordx4 v[238:239], off
	v_lshl_add_u64 v[238:239], v[244:245], 0, s[62:63]
	s_mov_b32 m0, s61
	s_nop 0
	global_load_lds_dwordx4 v[238:239], off
	s_waitcnt vmcnt(8)
	s_waitcnt lgkmcnt(0)
	s_barrier
	s_setprio 1
	s_waitcnt lgkmcnt(0)
	v_mfma_f32_16x16x32_bf16 v[68:71], v[16:19], v[190:193], v[68:71]
	v_mfma_f32_16x16x32_bf16 v[52:55], v[16:19], v[198:201], v[52:55]
	v_mfma_f32_16x16x32_bf16 v[36:39], v[16:19], v[222:225], v[36:39]
	v_mfma_f32_16x16x32_bf16 v[0:3], v[16:19], v[230:233], v[0:3]
	v_mfma_f32_16x16x32_bf16 v[68:71], v[20:23], v[194:197], v[68:71]
	v_mfma_f32_16x16x32_bf16 v[64:67], v[138:141], v[190:193], v[64:67]
	v_mfma_f32_16x16x32_bf16 v[52:55], v[20:23], v[202:205], v[52:55]
	v_mfma_f32_16x16x32_bf16 v[48:51], v[138:141], v[198:201], v[48:51]
	v_mfma_f32_16x16x32_bf16 v[36:39], v[20:23], v[226:229], v[36:39]
	v_mfma_f32_16x16x32_bf16 v[32:35], v[138:141], v[222:225], v[32:35]
	v_mfma_f32_16x16x32_bf16 v[20:23], v[20:23], v[234:237], v[0:3]
	v_mfma_f32_16x16x32_bf16 v[0:3], v[138:141], v[230:233], v[4:7]
	v_mfma_f32_16x16x32_bf16 v[64:67], v[142:145], v[194:197], v[64:67]
	v_mfma_f32_16x16x32_bf16 v[48:51], v[142:145], v[202:205], v[48:51]
	v_mfma_f32_16x16x32_bf16 v[32:35], v[142:145], v[226:229], v[32:35]
	v_mfma_f32_16x16x32_bf16 v[16:19], v[142:145], v[234:237], v[0:3]
	s_setprio 0
	s_setprio 1
	v_mfma_f32_16x16x32_bf16 v[0:3], v[146:149], v[190:193], v[60:63]
	v_mfma_f32_16x16x32_bf16 v[60:63], v[150:153], v[194:197], v[0:3]
	v_mfma_f32_16x16x32_bf16 v[0:3], v[182:185], v[190:193], v[56:59]
	v_mfma_f32_16x16x32_bf16 v[56:59], v[186:189], v[194:197], v[0:3]
	v_mfma_f32_16x16x32_bf16 v[0:3], v[146:149], v[198:201], v[44:47]
	v_mfma_f32_16x16x32_bf16 v[44:47], v[150:153], v[202:205], v[0:3]
	v_mfma_f32_16x16x32_bf16 v[0:3], v[182:185], v[198:201], v[40:43]
	v_mfma_f32_16x16x32_bf16 v[40:43], v[186:189], v[202:205], v[0:3]
	v_mfma_f32_16x16x32_bf16 v[0:3], v[146:149], v[222:225], v[28:31]
	v_mfma_f32_16x16x32_bf16 v[28:31], v[150:153], v[226:229], v[0:3]
	v_mfma_f32_16x16x32_bf16 v[0:3], v[182:185], v[222:225], v[24:27]
	v_mfma_f32_16x16x32_bf16 v[24:27], v[186:189], v[226:229], v[0:3]
	v_mfma_f32_16x16x32_bf16 v[0:3], v[146:149], v[230:233], v[12:15]
	v_mfma_f32_16x16x32_bf16 v[12:15], v[150:153], v[234:237], v[0:3]
	v_mfma_f32_16x16x32_bf16 v[0:3], v[182:185], v[230:233], v[8:11]
	v_mfma_f32_16x16x32_bf16 v[8:11], v[186:189], v[234:237], v[0:3]
	s_setprio 0
	s_barrier
	s_add_i32 s27, s27, 2
	s_add_u32 s4, s4, 0x100
	s_addc_u32 s5, s5, 0
	s_add_u32 s19, s19, 0x100
	s_addc_u32 s26, s26, 0
	.p2align 6

.Lfi_entry:
	v_readlane_b32 s10, v252, 42
	v_add_u32_e32 v1, s71, v208
	s_add_i32 s10, s10, s71
	v_add_u32_e32 v0, s10, v209
	ds_read_b128 v[186:189], v1
	ds_read_b128 v[190:193], v1 offset:256
	ds_read_b128 v[194:197], v1 offset:512
	ds_read_b128 v[198:201], v1 offset:768
	ds_read_b128 v[202:205], v1 offset:2048
	ds_read_b128 v[222:225], v1 offset:2304
	ds_read_b128 v[226:229], v1 offset:2560
	ds_read_b128 v[230:233], v1 offset:2816
	ds_read_b128 v[150:153], v0 offset:4096
	ds_read_b128 v[146:149], v0 offset:4112
	ds_read_b128 v[142:145], v0 offset:4224
	ds_read_b128 v[138:141], v0 offset:4240
	s_cmp_eq_u32 s35, 0
	s_cselect_b32 s12, s4, s50
	s_cselect_b32 s13, s5, s51
	s_lshl_b32 s14, s36, 8
	s_add_i32 s14, s14, s20
	s_lshl_b32 s14, s14, 11
	s_add_u32 s12, s12, s14
	s_addc_u32 s13, s13, 0
	v_add_u32_e32 v2, v182, v162
	v_lshlrev_b32_e32 v2, 1, v2
	v_lshl_add_u32 v246, v207, 11, v2
	v_add_u32_e32 v247, 0x4000, v246
	s_mov_b32 s16, s42
	s_mov_b32 s17, s42
	v_readlane_b32 s18, v252, 28
	v_readlane_b32 s19, v252, 29
	s_waitcnt lgkmcnt(0)
	s_cmp_eq_u32 s35, 0
	s_cbranch_scc0 .Lfi_kind1
	s_cmp_eq_u32 s42, 1.0
	s_cbranch_scc1 .Lfi_plain
	v_add_f32_e32 v4, v186, v187
	v_add_f32_e32 v5, v188, v189
	v_add_f32_e32 v4, v4, v5
	v_fmamk_f32 v4, v4, 0x3a800000, v212
	v_rsq_f32_e32 v6, v4
	s_nop 1
	v_pk_fma_f32 v[136:137], v[136:137], v[6:7], v[152:153] op_sel_hi:[1,0,1]
	v_pk_fma_f32 v[134:135], v[134:135], v[6:7], v[150:151] op_sel_hi:[1,0,1]
	v_pk_fma_f32 v[132:133], v[132:133], v[6:7], v[148:149] op_sel_hi:[1,0,1]
	v_pk_fma_f32 v[130:131], v[130:131], v[6:7], v[146:147] op_sel_hi:[1,0,1]
	v_pk_fma_f32 v[128:129], v[128:129], v[6:7], v[144:145] op_sel_hi:[1,0,1]
	v_pk_fma_f32 v[126:127], v[126:127], v[6:7], v[142:143] op_sel_hi:[1,0,1]
	v_pk_fma_f32 v[124:125], v[124:125], v[6:7], v[140:141] op_sel_hi:[1,0,1]
	v_pk_fma_f32 v[122:123], v[122:123], v[6:7], v[138:139] op_sel_hi:[1,0,1]
	v_pk_mul_f32 v[136:137], s[16:17], v[136:137]
	v_pk_mul_f32 v[134:135], s[16:17], v[134:135]
	v_pk_mul_f32 v[132:133], s[16:17], v[132:133]
	v_pk_mul_f32 v[130:131], s[16:17], v[130:131]
	v_pk_mul_f32 v[128:129], s[16:17], v[128:129]
	v_pk_mul_f32 v[126:127], s[16:17], v[126:127]
	v_pk_mul_f32 v[124:125], s[16:17], v[124:125]
	v_pk_mul_f32 v[122:123], s[16:17], v[122:123]
	v_cvt_pk_bf16_f32 v234, v134, v135
	v_cvt_pk_bf16_f32 v235, v136, v137
	v_cvt_pk_bf16_f32 v236, v130, v131
	v_cvt_pk_bf16_f32 v237, v132, v133
	v_cvt_pk_bf16_f32 v238, v126, v127
	v_cvt_pk_bf16_f32 v239, v128, v129
	v_cvt_pk_bf16_f32 v240, v122, v123
	v_cvt_pk_bf16_f32 v241, v124, v125
	s_mov_b64 vcc, s[6:7]
	v_cndmask_b32_dpp v134, v238, v234, vcc row_ror:8 row_mask:0xf bank_mask:0xf
	v_cndmask_b32_dpp v135, v239, v235, vcc row_ror:8 row_mask:0xf bank_mask:0xf
	v_cndmask_b32_dpp v136, v240, v236, vcc row_ror:8 row_mask:0xf bank_mask:0xf
	v_cndmask_b32_dpp v137, v241, v237, vcc row_ror:8 row_mask:0xf bank_mask:0xf
	s_not_b64 vcc, s[6:7]
	v_cndmask_b32_dpp v130, v234, v238, vcc row_ror:8 row_mask:0xf bank_mask:0xf
	v_cndmask_b32_dpp v131, v235, v239, vcc row_ror:8 row_mask:0xf bank_mask:0xf
	v_cndmask_b32_dpp v132, v236, v240, vcc row_ror:8 row_mask:0xf bank_mask:0xf
	v_cndmask_b32_dpp v133, v237, v241, vcc row_ror:8 row_mask:0xf bank_mask:0xf
	global_store_dwordx4 v246, v[134:137], s[12:13]
	global_store_dwordx4 v247, v[130:133], s[12:13]
	v_add_f32_e32 v4, v190, v191
	v_add_f32_e32 v5, v192, v193
	v_add_f32_e32 v4, v4, v5
	v_fmamk_f32 v4, v4, 0x3a800000, v212
	v_rsq_f32_e32 v6, v4
	s_add_u32 s12, s12, 0x8000
	s_addc_u32 s13, s13, 0
	v_pk_fma_f32 v[120:121], v[120:121], v[6:7], v[152:153] op_sel_hi:[1,0,1]
	v_pk_fma_f32 v[118:119], v[118:119], v[6:7], v[150:151] op_sel_hi:[1,0,1]
	v_pk_fma_f32 v[116:117], v[116:117], v[6:7], v[148:149] op_sel_hi:[1,0,1]
	v_pk_fma_f32 v[114:115], v[114:115], v[6:7], v[146:147] op_sel_hi:[1,0,1]
	v_pk_fma_f32 v[112:113], v[112:113], v[6:7], v[144:145] op_sel_hi:[1,0,1]
	v_pk_fma_f32 v[110:111], v[110:111], v[6:7], v[142:143] op_sel_hi:[1,0,1]
	v_pk_fma_f32 v[108:109], v[108:109], v[6:7], v[140:141] op_sel_hi:[1,0,1]
	v_pk_fma_f32 v[106:107], v[106:107], v[6:7], v[138:139] op_sel_hi:[1,0,1]
	v_pk_mul_f32 v[120:121], s[16:17], v[120:121]
	v_pk_mul_f32 v[118:119], s[16:17], v[118:119]
	v_pk_mul_f32 v[116:117], s[16:17], v[116:117]
	v_pk_mul_f32 v[114:115], s[16:17], v[114:115]
	v_pk_mul_f32 v[112:113], s[16:17], v[112:113]
	v_pk_mul_f32 v[110:111], s[16:17], v[110:111]
	v_pk_mul_f32 v[108:109], s[16:17], v[108:109]
	v_pk_mul_f32 v[106:107], s[16:17], v[106:107]
	v_cvt_pk_bf16_f32 v234, v118, v119
	v_cvt_pk_bf16_f32 v235, v120, v121
	v_cvt_pk_bf16_f32 v236, v114, v115
	v_cvt_pk_bf16_f32 v237, v116, v117
	v_cvt_pk_bf16_f32 v238, v110, v111
	v_cvt_pk_bf16_f32 v239, v112, v113
	v_cvt_pk_bf16_f32 v240, v106, v107
	v_cvt_pk_bf16_f32 v241, v108, v109
	s_mov_b64 vcc, s[6:7]
	v_cndmask_b32_dpp v118, v238, v234, vcc row_ror:8 row_mask:0xf bank_mask:0xf
	v_cndmask_b32_dpp v119, v239, v235, vcc row_ror:8 row_mask:0xf bank_mask:0xf
	v_cndmask_b32_dpp v120, v240, v236, vcc row_ror:8 row_mask:0xf bank_mask:0xf
	v_cndmask_b32_dpp v121, v241, v237, vcc row_ror:8 row_mask:0xf bank_mask:0xf
	s_not_b64 vcc, s[6:7]
	v_cndmask_b32_dpp v114, v234, v238, vcc row_ror:8 row_mask:0xf bank_mask:0xf
	v_cndmask_b32_dpp v115, v235, v239, vcc row_ror:8 row_mask:0xf bank_mask:0xf
	v_cndmask_b32_dpp v116, v236, v240, vcc row_ror:8 row_mask:0xf bank_mask:0xf
	v_cndmask_b32_dpp v117, v237, v241, vcc row_ror:8 row_mask:0xf bank_mask:0xf
	global_store_dwordx4 v246, v[118:121], s[12:13]
	global_store_dwordx4 v247, v[114:117], s[12:13]
	v_add_f32_e32 v4, v194, v195
	v_add_f32_e32 v5, v196, v197
	v_add_f32_e32 v4, v4, v5
	v_fmamk_f32 v4, v4, 0x3a800000, v212
	v_rsq_f32_e32 v6, v4
	s_add_u32 s12, s12, 0x8000
	s_addc_u32 s13, s13, 0
	v_pk_fma_f32 v[104:105], v[104:105], v[6:7], v[152:153] op_sel_hi:[1,0,1]
	v_pk_fma_f32 v[102:103], v[102:103], v[6:7], v[150:151] op_sel_hi:[1,0,1]
	v_pk_fma_f32 v[100:101], v[100:101], v[6:7], v[148:149] op_sel_hi:[1,0,1]
	v_pk_fma_f32 v[98:99], v[98:99], v[6:7], v[146:147] op_sel_hi:[1,0,1]
	v_pk_fma_f32 v[94:95], v[94:95], v[6:7], v[144:145] op_sel_hi:[1,0,1]
	v_pk_fma_f32 v[92:93], v[92:93], v[6:7], v[142:143] op_sel_hi:[1,0,1]
	v_pk_fma_f32 v[90:91], v[90:91], v[6:7], v[140:141] op_sel_hi:[1,0,1]
	v_pk_fma_f32 v[88:89], v[88:89], v[6:7], v[138:139] op_sel_hi:[1,0,1]
	v_pk_mul_f32 v[104:105], s[16:17], v[104:105]
	v_pk_mul_f32 v[102:103], s[16:17], v[102:103]
	v_pk_mul_f32 v[100:101], s[16:17], v[100:101]
	v_pk_mul_f32 v[98:99], s[16:17], v[98:99]
	v_pk_mul_f32 v[94:95], s[16:17], v[94:95]
	v_pk_mul_f32 v[92:93], s[16:17], v[92:93]
	v_pk_mul_f32 v[90:91], s[16:17], v[90:91]
	v_pk_mul_f32 v[88:89], s[16:17], v[88:89]
	v_cvt_pk_bf16_f32 v234, v102, v103
	v_cvt_pk_bf16_f32 v235, v104, v105
	v_cvt_pk_bf16_f32 v236, v98, v99
	v_cvt_pk_bf16_f32 v237, v100, v101
	v_cvt_pk_bf16_f32 v238, v92, v93
	v_cvt_pk_bf16_f32 v239, v94, v95
	v_cvt_pk_bf16_f32 v240, v88, v89
	v_cvt_pk_bf16_f32 v241, v90, v91
	s_mov_b64 vcc, s[6:7]
	v_cndmask_b32_dpp v102, v238, v234, vcc row_ror:8 row_mask:0xf bank_mask:0xf
	v_cndmask_b32_dpp v103, v239, v235, vcc row_ror:8 row_mask:0xf bank_mask:0xf
	v_cndmask_b32_dpp v104, v240, v236, vcc row_ror:8 row_mask:0xf bank_mask:0xf
	v_cndmask_b32_dpp v105, v241, v237, vcc row_ror:8 row_mask:0xf bank_mask:0xf
	s_not_b64 vcc, s[6:7]
	v_cndmask_b32_dpp v98, v234, v238, vcc row_ror:8 row_mask:0xf bank_mask:0xf
	v_cndmask_b32_dpp v99, v235, v239, vcc row_ror:8 row_mask:0xf bank_mask:0xf
	v_cndmask_b32_dpp v100, v236, v240, vcc row_ror:8 row_mask:0xf bank_mask:0xf
	v_cndmask_b32_dpp v101, v237, v241, vcc row_ror:8 row_mask:0xf bank_mask:0xf
	global_store_dwordx4 v246, v[102:105], s[12:13]
	global_store_dwordx4 v247, v[98:101], s[12:13]
	v_add_f32_e32 v4, v198, v199
	v_add_f32_e32 v5, v200, v201
	v_add_f32_e32 v4, v4, v5
	v_fmamk_f32 v4, v4, 0x3a800000, v212
	v_rsq_f32_e32 v6, v4
	s_add_u32 s12, s12, 0x8000
	s_addc_u32 s13, s13, 0
	v_pk_fma_f32 v[86:87], v[86:87], v[6:7], v[152:153] op_sel_hi:[1,0,1]
	v_pk_fma_f32 v[84:85], v[84:85], v[6:7], v[150:151] op_sel_hi:[1,0,1]
	v_pk_fma_f32 v[82:83], v[82:83], v[6:7], v[148:149] op_sel_hi:[1,0,1]
	v_pk_fma_f32 v[80:81], v[80:81], v[6:7], v[146:147] op_sel_hi:[1,0,1]
	v_pk_fma_f32 v[78:79], v[78:79], v[6:7], v[144:145] op_sel_hi:[1,0,1]
	v_pk_fma_f32 v[76:77], v[76:77], v[6:7], v[142:143] op_sel_hi:[1,0,1]
	v_pk_fma_f32 v[74:75], v[74:75], v[6:7], v[140:141] op_sel_hi:[1,0,1]
	v_pk_fma_f32 v[72:73], v[72:73], v[6:7], v[138:139] op_sel_hi:[1,0,1]
	v_pk_mul_f32 v[86:87], s[16:17], v[86:87]
	v_pk_mul_f32 v[84:85], s[16:17], v[84:85]
	v_pk_mul_f32 v[82:83], s[16:17], v[82:83]
	v_pk_mul_f32 v[80:81], s[16:17], v[80:81]
	v_pk_mul_f32 v[78:79], s[16:17], v[78:79]
	v_pk_mul_f32 v[76:77], s[16:17], v[76:77]
	v_pk_mul_f32 v[74:75], s[16:17], v[74:75]
	v_pk_mul_f32 v[72:73], s[16:17], v[72:73]
	v_cvt_pk_bf16_f32 v234, v84, v85
	v_cvt_pk_bf16_f32 v235, v86, v87
	v_cvt_pk_bf16_f32 v236, v80, v81
	v_cvt_pk_bf16_f32 v237, v82, v83
	v_cvt_pk_bf16_f32 v238, v76, v77
	v_cvt_pk_bf16_f32 v239, v78, v79
	v_cvt_pk_bf16_f32 v240, v72, v73
	v_cvt_pk_bf16_f32 v241, v74, v75
	s_mov_b64 vcc, s[6:7]
	v_cndmask_b32_dpp v84, v238, v234, vcc row_ror:8 row_mask:0xf bank_mask:0xf
	v_cndmask_b32_dpp v85, v239, v235, vcc row_ror:8 row_mask:0xf bank_mask:0xf
	v_cndmask_b32_dpp v86, v240, v236, vcc row_ror:8 row_mask:0xf bank_mask:0xf
	v_cndmask_b32_dpp v87, v241, v237, vcc row_ror:8 row_mask:0xf bank_mask:0xf
	s_not_b64 vcc, s[6:7]
	v_cndmask_b32_dpp v80, v234, v238, vcc row_ror:8 row_mask:0xf bank_mask:0xf
	v_cndmask_b32_dpp v81, v235, v239, vcc row_ror:8 row_mask:0xf bank_mask:0xf
	v_cndmask_b32_dpp v82, v236, v240, vcc row_ror:8 row_mask:0xf bank_mask:0xf
	v_cndmask_b32_dpp v83, v237, v241, vcc row_ror:8 row_mask:0xf bank_mask:0xf
	global_store_dwordx4 v246, v[84:87], s[12:13]
	global_store_dwordx4 v247, v[80:83], s[12:13]
	v_add_f32_e32 v4, v202, v203
	v_add_f32_e32 v5, v204, v205
	v_add_f32_e32 v4, v4, v5
	v_fmamk_f32 v4, v4, 0x3a800000, v212
	v_rsq_f32_e32 v6, v4
	s_add_u32 s12, s12, 0x28000
	s_addc_u32 s13, s13, 0
	v_pk_fma_f32 v[70:71], v[70:71], v[6:7], v[152:153] op_sel_hi:[1,0,1]
	v_pk_fma_f32 v[68:69], v[68:69], v[6:7], v[150:151] op_sel_hi:[1,0,1]
	v_pk_fma_f32 v[66:67], v[66:67], v[6:7], v[148:149] op_sel_hi:[1,0,1]
	v_pk_fma_f32 v[64:65], v[64:65], v[6:7], v[146:147] op_sel_hi:[1,0,1]
	v_pk_fma_f32 v[62:63], v[62:63], v[6:7], v[144:145] op_sel_hi:[1,0,1]
	v_pk_fma_f32 v[60:61], v[60:61], v[6:7], v[142:143] op_sel_hi:[1,0,1]
	v_pk_fma_f32 v[58:59], v[58:59], v[6:7], v[140:141] op_sel_hi:[1,0,1]
	v_pk_fma_f32 v[56:57], v[56:57], v[6:7], v[138:139] op_sel_hi:[1,0,1]
	v_pk_mul_f32 v[70:71], s[16:17], v[70:71]
	v_pk_mul_f32 v[68:69], s[16:17], v[68:69]
	v_pk_mul_f32 v[66:67], s[16:17], v[66:67]
	v_pk_mul_f32 v[64:65], s[16:17], v[64:65]
	v_pk_mul_f32 v[62:63], s[16:17], v[62:63]
	v_pk_mul_f32 v[60:61], s[16:17], v[60:61]
	v_pk_mul_f32 v[58:59], s[16:17], v[58:59]
	v_pk_mul_f32 v[56:57], s[16:17], v[56:57]
	v_cvt_pk_bf16_f32 v234, v68, v69
	v_cvt_pk_bf16_f32 v235, v70, v71
	v_cvt_pk_bf16_f32 v236, v64, v65
	v_cvt_pk_bf16_f32 v237, v66, v67
	v_cvt_pk_bf16_f32 v238, v60, v61
	v_cvt_pk_bf16_f32 v239, v62, v63
	v_cvt_pk_bf16_f32 v240, v56, v57
	v_cvt_pk_bf16_f32 v241, v58, v59
	s_mov_b64 vcc, s[6:7]
	v_cndmask_b32_dpp v68, v238, v234, vcc row_ror:8 row_mask:0xf bank_mask:0xf
	v_cndmask_b32_dpp v69, v239, v235, vcc row_ror:8 row_mask:0xf bank_mask:0xf
	v_cndmask_b32_dpp v70, v240, v236, vcc row_ror:8 row_mask:0xf bank_mask:0xf
	v_cndmask_b32_dpp v71, v241, v237, vcc row_ror:8 row_mask:0xf bank_mask:0xf
	s_not_b64 vcc, s[6:7]
	v_cndmask_b32_dpp v64, v234, v238, vcc row_ror:8 row_mask:0xf bank_mask:0xf
	v_cndmask_b32_dpp v65, v235, v239, vcc row_ror:8 row_mask:0xf bank_mask:0xf
	v_cndmask_b32_dpp v66, v236, v240, vcc row_ror:8 row_mask:0xf bank_mask:0xf
	v_cndmask_b32_dpp v67, v237, v241, vcc row_ror:8 row_mask:0xf bank_mask:0xf
	global_store_dwordx4 v246, v[68:71], s[12:13]
	global_store_dwordx4 v247, v[64:67], s[12:13]
	v_add_f32_e32 v4, v222, v223
	v_add_f32_e32 v5, v224, v225
	v_add_f32_e32 v4, v4, v5
	v_fmamk_f32 v4, v4, 0x3a800000, v212
	v_rsq_f32_e32 v6, v4
	s_add_u32 s12, s12, 0x8000
	s_addc_u32 s13, s13, 0
	v_pk_fma_f32 v[54:55], v[54:55], v[6:7], v[152:153] op_sel_hi:[1,0,1]
	v_pk_fma_f32 v[52:53], v[52:53], v[6:7], v[150:151] op_sel_hi:[1,0,1]
	v_pk_fma_f32 v[50:51], v[50:51], v[6:7], v[148:149] op_sel_hi:[1,0,1]
	v_pk_fma_f32 v[48:49], v[48:49], v[6:7], v[146:147] op_sel_hi:[1,0,1]
	v_pk_fma_f32 v[46:47], v[46:47], v[6:7], v[144:145] op_sel_hi:[1,0,1]
	v_pk_fma_f32 v[44:45], v[44:45], v[6:7], v[142:143] op_sel_hi:[1,0,1]
	v_pk_fma_f32 v[42:43], v[42:43], v[6:7], v[140:141] op_sel_hi:[1,0,1]
	v_pk_fma_f32 v[40:41], v[40:41], v[6:7], v[138:139] op_sel_hi:[1,0,1]
	v_pk_mul_f32 v[54:55], s[16:17], v[54:55]
	v_pk_mul_f32 v[52:53], s[16:17], v[52:53]
	v_pk_mul_f32 v[50:51], s[16:17], v[50:51]
	v_pk_mul_f32 v[48:49], s[16:17], v[48:49]
	v_pk_mul_f32 v[46:47], s[16:17], v[46:47]
	v_pk_mul_f32 v[44:45], s[16:17], v[44:45]
	v_pk_mul_f32 v[42:43], s[16:17], v[42:43]
	v_pk_mul_f32 v[40:41], s[16:17], v[40:41]
	v_cvt_pk_bf16_f32 v234, v52, v53
	v_cvt_pk_bf16_f32 v235, v54, v55
	v_cvt_pk_bf16_f32 v236, v48, v49
	v_cvt_pk_bf16_f32 v237, v50, v51
	v_cvt_pk_bf16_f32 v238, v44, v45
	v_cvt_pk_bf16_f32 v239, v46, v47
	v_cvt_pk_bf16_f32 v240, v40, v41
	v_cvt_pk_bf16_f32 v241, v42, v43
	s_mov_b64 vcc, s[6:7]
	v_cndmask_b32_dpp v52, v238, v234, vcc row_ror:8 row_mask:0xf bank_mask:0xf
	v_cndmask_b32_dpp v53, v239, v235, vcc row_ror:8 row_mask:0xf bank_mask:0xf
	v_cndmask_b32_dpp v54, v240, v236, vcc row_ror:8 row_mask:0xf bank_mask:0xf
	v_cndmask_b32_dpp v55, v241, v237, vcc row_ror:8 row_mask:0xf bank_mask:0xf
	s_not_b64 vcc, s[6:7]
	v_cndmask_b32_dpp v48, v234, v238, vcc row_ror:8 row_mask:0xf bank_mask:0xf
	v_cndmask_b32_dpp v49, v235, v239, vcc row_ror:8 row_mask:0xf bank_mask:0xf
	v_cndmask_b32_dpp v50, v236, v240, vcc row_ror:8 row_mask:0xf bank_mask:0xf
	v_cndmask_b32_dpp v51, v237, v241, vcc row_ror:8 row_mask:0xf bank_mask:0xf
	global_store_dwordx4 v246, v[52:55], s[12:13]
	global_store_dwordx4 v247, v[48:51], s[12:13]
	v_add_f32_e32 v4, v226, v227
	v_add_f32_e32 v5, v228, v229
	v_add_f32_e32 v4, v4, v5
	v_fmamk_f32 v4, v4, 0x3a800000, v212
	v_rsq_f32_e32 v6, v4
	s_add_u32 s12, s12, 0x8000
	s_addc_u32 s13, s13, 0
	v_pk_fma_f32 v[38:39], v[38:39], v[6:7], v[152:153] op_sel_hi:[1,0,1]
	v_pk_fma_f32 v[36:37], v[36:37], v[6:7], v[150:151] op_sel_hi:[1,0,1]
	v_pk_fma_f32 v[34:35], v[34:35], v[6:7], v[148:149] op_sel_hi:[1,0,1]
	v_pk_fma_f32 v[32:33], v[32:33], v[6:7], v[146:147] op_sel_hi:[1,0,1]
	v_pk_fma_f32 v[30:31], v[30:31], v[6:7], v[144:145] op_sel_hi:[1,0,1]
	v_pk_fma_f32 v[28:29], v[28:29], v[6:7], v[142:143] op_sel_hi:[1,0,1]
	v_pk_fma_f32 v[26:27], v[26:27], v[6:7], v[140:141] op_sel_hi:[1,0,1]
	v_pk_fma_f32 v[24:25], v[24:25], v[6:7], v[138:139] op_sel_hi:[1,0,1]
	v_pk_mul_f32 v[38:39], s[16:17], v[38:39]
	v_pk_mul_f32 v[36:37], s[16:17], v[36:37]
	v_pk_mul_f32 v[34:35], s[16:17], v[34:35]
	v_pk_mul_f32 v[32:33], s[16:17], v[32:33]
	v_pk_mul_f32 v[30:31], s[16:17], v[30:31]
	v_pk_mul_f32 v[28:29], s[16:17], v[28:29]
	v_pk_mul_f32 v[26:27], s[16:17], v[26:27]
	v_pk_mul_f32 v[24:25], s[16:17], v[24:25]
	v_cvt_pk_bf16_f32 v234, v36, v37
	v_cvt_pk_bf16_f32 v235, v38, v39
	v_cvt_pk_bf16_f32 v236, v32, v33
	v_cvt_pk_bf16_f32 v237, v34, v35
	v_cvt_pk_bf16_f32 v238, v28, v29
	v_cvt_pk_bf16_f32 v239, v30, v31
	v_cvt_pk_bf16_f32 v240, v24, v25
	v_cvt_pk_bf16_f32 v241, v26, v27
	s_mov_b64 vcc, s[6:7]
	v_cndmask_b32_dpp v36, v238, v234, vcc row_ror:8 row_mask:0xf bank_mask:0xf
	v_cndmask_b32_dpp v37, v239, v235, vcc row_ror:8 row_mask:0xf bank_mask:0xf
	v_cndmask_b32_dpp v38, v240, v236, vcc row_ror:8 row_mask:0xf bank_mask:0xf
	v_cndmask_b32_dpp v39, v241, v237, vcc row_ror:8 row_mask:0xf bank_mask:0xf
	s_not_b64 vcc, s[6:7]
	v_cndmask_b32_dpp v32, v234, v238, vcc row_ror:8 row_mask:0xf bank_mask:0xf
	v_cndmask_b32_dpp v33, v235, v239, vcc row_ror:8 row_mask:0xf bank_mask:0xf
	v_cndmask_b32_dpp v34, v236, v240, vcc row_ror:8 row_mask:0xf bank_mask:0xf
	v_cndmask_b32_dpp v35, v237, v241, vcc row_ror:8 row_mask:0xf bank_mask:0xf
	global_store_dwordx4 v246, v[36:39], s[12:13]
	global_store_dwordx4 v247, v[32:35], s[12:13]
	v_add_f32_e32 v4, v230, v231
	v_add_f32_e32 v5, v232, v233
	v_add_f32_e32 v4, v4, v5
	v_fmamk_f32 v4, v4, 0x3a800000, v212
	v_rsq_f32_e32 v6, v4
	s_add_u32 s12, s12, 0x8000
	s_addc_u32 s13, s13, 0
	v_pk_fma_f32 v[22:23], v[22:23], v[6:7], v[152:153] op_sel_hi:[1,0,1]
	v_pk_fma_f32 v[20:21], v[20:21], v[6:7], v[150:151] op_sel_hi:[1,0,1]
	v_pk_fma_f32 v[18:19], v[18:19], v[6:7], v[148:149] op_sel_hi:[1,0,1]
	v_pk_fma_f32 v[16:17], v[16:17], v[6:7], v[146:147] op_sel_hi:[1,0,1]
	v_pk_fma_f32 v[14:15], v[14:15], v[6:7], v[144:145] op_sel_hi:[1,0,1]
	v_pk_fma_f32 v[12:13], v[12:13], v[6:7], v[142:143] op_sel_hi:[1,0,1]
	v_pk_fma_f32 v[10:11], v[10:11], v[6:7], v[140:141] op_sel_hi:[1,0,1]
	v_pk_fma_f32 v[8:9], v[8:9], v[6:7], v[138:139] op_sel_hi:[1,0,1]
	v_pk_mul_f32 v[22:23], s[16:17], v[22:23]
	v_pk_mul_f32 v[20:21], s[16:17], v[20:21]
	v_pk_mul_f32 v[18:19], s[16:17], v[18:19]
	v_pk_mul_f32 v[16:17], s[16:17], v[16:17]
	v_pk_mul_f32 v[14:15], s[16:17], v[14:15]
	v_pk_mul_f32 v[12:13], s[16:17], v[12:13]
	v_pk_mul_f32 v[10:11], s[16:17], v[10:11]
	v_pk_mul_f32 v[8:9], s[16:17], v[8:9]
	v_cvt_pk_bf16_f32 v234, v20, v21
	v_cvt_pk_bf16_f32 v235, v22, v23
	v_cvt_pk_bf16_f32 v236, v16, v17
	v_cvt_pk_bf16_f32 v237, v18, v19
	v_cvt_pk_bf16_f32 v238, v12, v13
	v_cvt_pk_bf16_f32 v239, v14, v15
	v_cvt_pk_bf16_f32 v240, v8, v9
	v_cvt_pk_bf16_f32 v241, v10, v11
	s_mov_b64 vcc, s[6:7]
	v_cndmask_b32_dpp v20, v238, v234, vcc row_ror:8 row_mask:0xf bank_mask:0xf
	v_cndmask_b32_dpp v21, v239, v235, vcc row_ror:8 row_mask:0xf bank_mask:0xf
	v_cndmask_b32_dpp v22, v240, v236, vcc row_ror:8 row_mask:0xf bank_mask:0xf
	v_cndmask_b32_dpp v23, v241, v237, vcc row_ror:8 row_mask:0xf bank_mask:0xf
	s_not_b64 vcc, s[6:7]
	v_cndmask_b32_dpp v16, v234, v238, vcc row_ror:8 row_mask:0xf bank_mask:0xf
	v_cndmask_b32_dpp v17, v235, v239, vcc row_ror:8 row_mask:0xf bank_mask:0xf
	v_cndmask_b32_dpp v18, v236, v240, vcc row_ror:8 row_mask:0xf bank_mask:0xf
	v_cndmask_b32_dpp v19, v237, v241, vcc row_ror:8 row_mask:0xf bank_mask:0xf
	global_store_dwordx4 v246, v[20:23], s[12:13]
	global_store_dwordx4 v247, v[16:19], s[12:13]
	s_mov_b32 s100, 1
	s_branch .LBB0_1422
.Lfi_kind1:
	s_and_b64 vcc, exec, s[18:19]
	s_cbranch_vccz .Lfi_plain
	v_add_f32_e32 v4, v186, v187
	v_add_f32_e32 v5, v188, v189
	v_add_f32_e32 v4, v4, v5
	v_fmamk_f32 v4, v4, 0x3a800000, v212
	v_rsq_f32_e32 v6, v4
	s_nop 1
	v_pk_fma_f32 v[136:137], v[136:137], v[6:7], v[152:153] op_sel_hi:[1,0,1]
	v_pk_fma_f32 v[134:135], v[134:135], v[6:7], v[150:151] op_sel_hi:[1,0,1]
	v_pk_fma_f32 v[132:133], v[132:133], v[6:7], v[148:149] op_sel_hi:[1,0,1]
	v_pk_fma_f32 v[130:131], v[130:131], v[6:7], v[146:147] op_sel_hi:[1,0,1]
	v_pk_fma_f32 v[128:129], v[128:129], v[6:7], v[144:145] op_sel_hi:[1,0,1]
	v_pk_fma_f32 v[126:127], v[126:127], v[6:7], v[142:143] op_sel_hi:[1,0,1]
	v_pk_fma_f32 v[124:125], v[124:125], v[6:7], v[140:141] op_sel_hi:[1,0,1]
	v_pk_fma_f32 v[122:123], v[122:123], v[6:7], v[138:139] op_sel_hi:[1,0,1]
	v_mul_f32_e32 v0, 0xbfb8aa3b, v134
	v_mul_f32_e32 v1, 0xbfb8aa3b, v135
	v_mul_f32_e32 v2, 0xbfb8aa3b, v136
	v_mul_f32_e32 v3, 0xbfb8aa3b, v137
	v_mul_f32_e32 v242, 0xbfb8aa3b, v130
	v_mul_f32_e32 v243, 0xbfb8aa3b, v131
	v_mul_f32_e32 v244, 0xbfb8aa3b, v132
	v_mul_f32_e32 v245, 0xbfb8aa3b, v133
	v_exp_f32_e32 v0, v0
	v_exp_f32_e32 v1, v1
	v_exp_f32_e32 v2, v2
	v_exp_f32_e32 v3, v3
	v_exp_f32_e32 v242, v242
	v_exp_f32_e32 v243, v243
	v_exp_f32_e32 v244, v244
	v_exp_f32_e32 v245, v245
	v_add_f32_e32 v0, 1.0, v0
	v_add_f32_e32 v1, 1.0, v1
	v_add_f32_e32 v2, 1.0, v2
	v_add_f32_e32 v3, 1.0, v3
	v_add_f32_e32 v242, 1.0, v242
	v_add_f32_e32 v243, 1.0, v243
	v_add_f32_e32 v244, 1.0, v244
	v_add_f32_e32 v245, 1.0, v245
	v_rcp_f32_e32 v0, v0
	v_rcp_f32_e32 v1, v1
	v_rcp_f32_e32 v2, v2
	v_rcp_f32_e32 v3, v3
	v_rcp_f32_e32 v242, v242
	v_rcp_f32_e32 v243, v243
	v_rcp_f32_e32 v244, v244
	v_rcp_f32_e32 v245, v245
	v_pk_mul_f32 v[134:135], v[134:135], v[0:1]
	v_pk_mul_f32 v[136:137], v[136:137], v[2:3]
	v_pk_mul_f32 v[130:131], v[130:131], v[242:243]
	v_pk_mul_f32 v[132:133], v[132:133], v[244:245]
	v_mul_f32_e32 v0, 0xbfb8aa3b, v126
	v_mul_f32_e32 v1, 0xbfb8aa3b, v127
	v_mul_f32_e32 v2, 0xbfb8aa3b, v128
	v_mul_f32_e32 v3, 0xbfb8aa3b, v129
	v_mul_f32_e32 v242, 0xbfb8aa3b, v122
	v_mul_f32_e32 v243, 0xbfb8aa3b, v123
	v_mul_f32_e32 v244, 0xbfb8aa3b, v124
	v_mul_f32_e32 v245, 0xbfb8aa3b, v125
	v_exp_f32_e32 v0, v0
	v_exp_f32_e32 v1, v1
	v_exp_f32_e32 v2, v2
	v_exp_f32_e32 v3, v3
	v_exp_f32_e32 v242, v242
	v_exp_f32_e32 v243, v243
	v_exp_f32_e32 v244, v244
	v_exp_f32_e32 v245, v245
	v_add_f32_e32 v0, 1.0, v0
	v_add_f32_e32 v1, 1.0, v1
	v_add_f32_e32 v2, 1.0, v2
	v_add_f32_e32 v3, 1.0, v3
	v_add_f32_e32 v242, 1.0, v242
	v_add_f32_e32 v243, 1.0, v243
	v_add_f32_e32 v244, 1.0, v244
	v_add_f32_e32 v245, 1.0, v245
	v_rcp_f32_e32 v0, v0
	v_rcp_f32_e32 v1, v1
	v_rcp_f32_e32 v2, v2
	v_rcp_f32_e32 v3, v3
	v_rcp_f32_e32 v242, v242
	v_rcp_f32_e32 v243, v243
	v_rcp_f32_e32 v244, v244
	v_rcp_f32_e32 v245, v245
	v_pk_mul_f32 v[126:127], v[126:127], v[0:1]
	v_pk_mul_f32 v[128:129], v[128:129], v[2:3]
	v_pk_mul_f32 v[122:123], v[122:123], v[242:243]
	v_pk_mul_f32 v[124:125], v[124:125], v[244:245]
	v_cvt_pk_bf16_f32 v234, v134, v135
	v_cvt_pk_bf16_f32 v235, v136, v137
	v_cvt_pk_bf16_f32 v236, v130, v131
	v_cvt_pk_bf16_f32 v237, v132, v133
	v_cvt_pk_bf16_f32 v238, v126, v127
	v_cvt_pk_bf16_f32 v239, v128, v129
	v_cvt_pk_bf16_f32 v240, v122, v123
	v_cvt_pk_bf16_f32 v241, v124, v125
	s_mov_b64 vcc, s[6:7]
	v_cndmask_b32_dpp v134, v238, v234, vcc row_ror:8 row_mask:0xf bank_mask:0xf
	v_cndmask_b32_dpp v135, v239, v235, vcc row_ror:8 row_mask:0xf bank_mask:0xf
	v_cndmask_b32_dpp v136, v240, v236, vcc row_ror:8 row_mask:0xf bank_mask:0xf
	v_cndmask_b32_dpp v137, v241, v237, vcc row_ror:8 row_mask:0xf bank_mask:0xf
	s_not_b64 vcc, s[6:7]
	v_cndmask_b32_dpp v130, v234, v238, vcc row_ror:8 row_mask:0xf bank_mask:0xf
	v_cndmask_b32_dpp v131, v235, v239, vcc row_ror:8 row_mask:0xf bank_mask:0xf
	v_cndmask_b32_dpp v132, v236, v240, vcc row_ror:8 row_mask:0xf bank_mask:0xf
	v_cndmask_b32_dpp v133, v237, v241, vcc row_ror:8 row_mask:0xf bank_mask:0xf
	global_store_dwordx4 v246, v[134:137], s[12:13]
	global_store_dwordx4 v247, v[130:133], s[12:13]
	v_add_f32_e32 v4, v190, v191
	v_add_f32_e32 v5, v192, v193
	v_add_f32_e32 v4, v4, v5
	v_fmamk_f32 v4, v4, 0x3a800000, v212
	v_rsq_f32_e32 v6, v4
	s_add_u32 s12, s12, 0x8000
	s_addc_u32 s13, s13, 0
	v_pk_fma_f32 v[120:121], v[120:121], v[6:7], v[152:153] op_sel_hi:[1,0,1]
	v_pk_fma_f32 v[118:119], v[118:119], v[6:7], v[150:151] op_sel_hi:[1,0,1]
	v_pk_fma_f32 v[116:117], v[116:117], v[6:7], v[148:149] op_sel_hi:[1,0,1]
	v_pk_fma_f32 v[114:115], v[114:115], v[6:7], v[146:147] op_sel_hi:[1,0,1]
	v_pk_fma_f32 v[112:113], v[112:113], v[6:7], v[144:145] op_sel_hi:[1,0,1]
	v_pk_fma_f32 v[110:111], v[110:111], v[6:7], v[142:143] op_sel_hi:[1,0,1]
	v_pk_fma_f32 v[108:109], v[108:109], v[6:7], v[140:141] op_sel_hi:[1,0,1]
	v_pk_fma_f32 v[106:107], v[106:107], v[6:7], v[138:139] op_sel_hi:[1,0,1]
	v_mul_f32_e32 v0, 0xbfb8aa3b, v118
	v_mul_f32_e32 v1, 0xbfb8aa3b, v119
	v_mul_f32_e32 v2, 0xbfb8aa3b, v120
	v_mul_f32_e32 v3, 0xbfb8aa3b, v121
	v_mul_f32_e32 v242, 0xbfb8aa3b, v114
	v_mul_f32_e32 v243, 0xbfb8aa3b, v115
	v_mul_f32_e32 v244, 0xbfb8aa3b, v116
	v_mul_f32_e32 v245, 0xbfb8aa3b, v117
	v_exp_f32_e32 v0, v0
	v_exp_f32_e32 v1, v1
	v_exp_f32_e32 v2, v2
	v_exp_f32_e32 v3, v3
	v_exp_f32_e32 v242, v242
	v_exp_f32_e32 v243, v243
	v_exp_f32_e32 v244, v244
	v_exp_f32_e32 v245, v245
	v_add_f32_e32 v0, 1.0, v0
	v_add_f32_e32 v1, 1.0, v1
	v_add_f32_e32 v2, 1.0, v2
	v_add_f32_e32 v3, 1.0, v3
	v_add_f32_e32 v242, 1.0, v242
	v_add_f32_e32 v243, 1.0, v243
	v_add_f32_e32 v244, 1.0, v244
	v_add_f32_e32 v245, 1.0, v245
	v_rcp_f32_e32 v0, v0
	v_rcp_f32_e32 v1, v1
	v_rcp_f32_e32 v2, v2
	v_rcp_f32_e32 v3, v3
	v_rcp_f32_e32 v242, v242
	v_rcp_f32_e32 v243, v243
	v_rcp_f32_e32 v244, v244
	v_rcp_f32_e32 v245, v245
	v_pk_mul_f32 v[118:119], v[118:119], v[0:1]
	v_pk_mul_f32 v[120:121], v[120:121], v[2:3]
	v_pk_mul_f32 v[114:115], v[114:115], v[242:243]
	v_pk_mul_f32 v[116:117], v[116:117], v[244:245]
	v_mul_f32_e32 v0, 0xbfb8aa3b, v110
	v_mul_f32_e32 v1, 0xbfb8aa3b, v111
	v_mul_f32_e32 v2, 0xbfb8aa3b, v112
	v_mul_f32_e32 v3, 0xbfb8aa3b, v113
	v_mul_f32_e32 v242, 0xbfb8aa3b, v106
	v_mul_f32_e32 v243, 0xbfb8aa3b, v107
	v_mul_f32_e32 v244, 0xbfb8aa3b, v108
	v_mul_f32_e32 v245, 0xbfb8aa3b, v109
	v_exp_f32_e32 v0, v0
	v_exp_f32_e32 v1, v1
	v_exp_f32_e32 v2, v2
	v_exp_f32_e32 v3, v3
	v_exp_f32_e32 v242, v242
	v_exp_f32_e32 v243, v243
	v_exp_f32_e32 v244, v244
	v_exp_f32_e32 v245, v245
	v_add_f32_e32 v0, 1.0, v0
	v_add_f32_e32 v1, 1.0, v1
	v_add_f32_e32 v2, 1.0, v2
	v_add_f32_e32 v3, 1.0, v3
	v_add_f32_e32 v242, 1.0, v242
	v_add_f32_e32 v243, 1.0, v243
	v_add_f32_e32 v244, 1.0, v244
	v_add_f32_e32 v245, 1.0, v245
	v_rcp_f32_e32 v0, v0
	v_rcp_f32_e32 v1, v1
	v_rcp_f32_e32 v2, v2
	v_rcp_f32_e32 v3, v3
	v_rcp_f32_e32 v242, v242
	v_rcp_f32_e32 v243, v243
	v_rcp_f32_e32 v244, v244
	v_rcp_f32_e32 v245, v245
	v_pk_mul_f32 v[110:111], v[110:111], v[0:1]
	v_pk_mul_f32 v[112:113], v[112:113], v[2:3]
	v_pk_mul_f32 v[106:107], v[106:107], v[242:243]
	v_pk_mul_f32 v[108:109], v[108:109], v[244:245]
	v_cvt_pk_bf16_f32 v234, v118, v119
	v_cvt_pk_bf16_f32 v235, v120, v121
	v_cvt_pk_bf16_f32 v236, v114, v115
	v_cvt_pk_bf16_f32 v237, v116, v117
	v_cvt_pk_bf16_f32 v238, v110, v111
	v_cvt_pk_bf16_f32 v239, v112, v113
	v_cvt_pk_bf16_f32 v240, v106, v107
	v_cvt_pk_bf16_f32 v241, v108, v109
	s_mov_b64 vcc, s[6:7]
	v_cndmask_b32_dpp v118, v238, v234, vcc row_ror:8 row_mask:0xf bank_mask:0xf
	v_cndmask_b32_dpp v119, v239, v235, vcc row_ror:8 row_mask:0xf bank_mask:0xf
	v_cndmask_b32_dpp v120, v240, v236, vcc row_ror:8 row_mask:0xf bank_mask:0xf
	v_cndmask_b32_dpp v121, v241, v237, vcc row_ror:8 row_mask:0xf bank_mask:0xf
	s_not_b64 vcc, s[6:7]
	v_cndmask_b32_dpp v114, v234, v238, vcc row_ror:8 row_mask:0xf bank_mask:0xf
	v_cndmask_b32_dpp v115, v235, v239, vcc row_ror:8 row_mask:0xf bank_mask:0xf
	v_cndmask_b32_dpp v116, v236, v240, vcc row_ror:8 row_mask:0xf bank_mask:0xf
	v_cndmask_b32_dpp v117, v237, v241, vcc row_ror:8 row_mask:0xf bank_mask:0xf
	global_store_dwordx4 v246, v[118:121], s[12:13]
	global_store_dwordx4 v247, v[114:117], s[12:13]
	v_add_f32_e32 v4, v194, v195
	v_add_f32_e32 v5, v196, v197
	v_add_f32_e32 v4, v4, v5
	v_fmamk_f32 v4, v4, 0x3a800000, v212
	v_rsq_f32_e32 v6, v4
	s_add_u32 s12, s12, 0x8000
	s_addc_u32 s13, s13, 0
	v_pk_fma_f32 v[104:105], v[104:105], v[6:7], v[152:153] op_sel_hi:[1,0,1]
	v_pk_fma_f32 v[102:103], v[102:103], v[6:7], v[150:151] op_sel_hi:[1,0,1]
	v_pk_fma_f32 v[100:101], v[100:101], v[6:7], v[148:149] op_sel_hi:[1,0,1]
	v_pk_fma_f32 v[98:99], v[98:99], v[6:7], v[146:147] op_sel_hi:[1,0,1]
	v_pk_fma_f32 v[94:95], v[94:95], v[6:7], v[144:145] op_sel_hi:[1,0,1]
	v_pk_fma_f32 v[92:93], v[92:93], v[6:7], v[142:143] op_sel_hi:[1,0,1]
	v_pk_fma_f32 v[90:91], v[90:91], v[6:7], v[140:141] op_sel_hi:[1,0,1]
	v_pk_fma_f32 v[88:89], v[88:89], v[6:7], v[138:139] op_sel_hi:[1,0,1]
	v_mul_f32_e32 v0, 0xbfb8aa3b, v102
	v_mul_f32_e32 v1, 0xbfb8aa3b, v103
	v_mul_f32_e32 v2, 0xbfb8aa3b, v104
	v_mul_f32_e32 v3, 0xbfb8aa3b, v105
	v_mul_f32_e32 v242, 0xbfb8aa3b, v98
	v_mul_f32_e32 v243, 0xbfb8aa3b, v99
	v_mul_f32_e32 v244, 0xbfb8aa3b, v100
	v_mul_f32_e32 v245, 0xbfb8aa3b, v101
	v_exp_f32_e32 v0, v0
	v_exp_f32_e32 v1, v1
	v_exp_f32_e32 v2, v2
	v_exp_f32_e32 v3, v3
	v_exp_f32_e32 v242, v242
	v_exp_f32_e32 v243, v243
	v_exp_f32_e32 v244, v244
	v_exp_f32_e32 v245, v245
	v_add_f32_e32 v0, 1.0, v0
	v_add_f32_e32 v1, 1.0, v1
	v_add_f32_e32 v2, 1.0, v2
	v_add_f32_e32 v3, 1.0, v3
	v_add_f32_e32 v242, 1.0, v242
	v_add_f32_e32 v243, 1.0, v243
	v_add_f32_e32 v244, 1.0, v244
	v_add_f32_e32 v245, 1.0, v245
	v_rcp_f32_e32 v0, v0
	v_rcp_f32_e32 v1, v1
	v_rcp_f32_e32 v2, v2
	v_rcp_f32_e32 v3, v3
	v_rcp_f32_e32 v242, v242
	v_rcp_f32_e32 v243, v243
	v_rcp_f32_e32 v244, v244
	v_rcp_f32_e32 v245, v245
	v_pk_mul_f32 v[102:103], v[102:103], v[0:1]
	v_pk_mul_f32 v[104:105], v[104:105], v[2:3]
	v_pk_mul_f32 v[98:99], v[98:99], v[242:243]
	v_pk_mul_f32 v[100:101], v[100:101], v[244:245]
	v_mul_f32_e32 v0, 0xbfb8aa3b, v92
	v_mul_f32_e32 v1, 0xbfb8aa3b, v93
	v_mul_f32_e32 v2, 0xbfb8aa3b, v94
	v_mul_f32_e32 v3, 0xbfb8aa3b, v95
	v_mul_f32_e32 v242, 0xbfb8aa3b, v88
	v_mul_f32_e32 v243, 0xbfb8aa3b, v89
	v_mul_f32_e32 v244, 0xbfb8aa3b, v90
	v_mul_f32_e32 v245, 0xbfb8aa3b, v91
	v_exp_f32_e32 v0, v0
	v_exp_f32_e32 v1, v1
	v_exp_f32_e32 v2, v2
	v_exp_f32_e32 v3, v3
	v_exp_f32_e32 v242, v242
	v_exp_f32_e32 v243, v243
	v_exp_f32_e32 v244, v244
	v_exp_f32_e32 v245, v245
	v_add_f32_e32 v0, 1.0, v0
	v_add_f32_e32 v1, 1.0, v1
	v_add_f32_e32 v2, 1.0, v2
	v_add_f32_e32 v3, 1.0, v3
	v_add_f32_e32 v242, 1.0, v242
	v_add_f32_e32 v243, 1.0, v243
	v_add_f32_e32 v244, 1.0, v244
	v_add_f32_e32 v245, 1.0, v245
	v_rcp_f32_e32 v0, v0
	v_rcp_f32_e32 v1, v1
	v_rcp_f32_e32 v2, v2
	v_rcp_f32_e32 v3, v3
	v_rcp_f32_e32 v242, v242
	v_rcp_f32_e32 v243, v243
	v_rcp_f32_e32 v244, v244
	v_rcp_f32_e32 v245, v245
	v_pk_mul_f32 v[92:93], v[92:93], v[0:1]
	v_pk_mul_f32 v[94:95], v[94:95], v[2:3]
	v_pk_mul_f32 v[88:89], v[88:89], v[242:243]
	v_pk_mul_f32 v[90:91], v[90:91], v[244:245]
	v_cvt_pk_bf16_f32 v234, v102, v103
	v_cvt_pk_bf16_f32 v235, v104, v105
	v_cvt_pk_bf16_f32 v236, v98, v99
	v_cvt_pk_bf16_f32 v237, v100, v101
	v_cvt_pk_bf16_f32 v238, v92, v93
	v_cvt_pk_bf16_f32 v239, v94, v95
	v_cvt_pk_bf16_f32 v240, v88, v89
	v_cvt_pk_bf16_f32 v241, v90, v91
	s_mov_b64 vcc, s[6:7]
	v_cndmask_b32_dpp v102, v238, v234, vcc row_ror:8 row_mask:0xf bank_mask:0xf
	v_cndmask_b32_dpp v103, v239, v235, vcc row_ror:8 row_mask:0xf bank_mask:0xf
	v_cndmask_b32_dpp v104, v240, v236, vcc row_ror:8 row_mask:0xf bank_mask:0xf
	v_cndmask_b32_dpp v105, v241, v237, vcc row_ror:8 row_mask:0xf bank_mask:0xf
	s_not_b64 vcc, s[6:7]
	v_cndmask_b32_dpp v98, v234, v238, vcc row_ror:8 row_mask:0xf bank_mask:0xf
	v_cndmask_b32_dpp v99, v235, v239, vcc row_ror:8 row_mask:0xf bank_mask:0xf
	v_cndmask_b32_dpp v100, v236, v240, vcc row_ror:8 row_mask:0xf bank_mask:0xf
	v_cndmask_b32_dpp v101, v237, v241, vcc row_ror:8 row_mask:0xf bank_mask:0xf
	global_store_dwordx4 v246, v[102:105], s[12:13]
	global_store_dwordx4 v247, v[98:101], s[12:13]
	v_add_f32_e32 v4, v198, v199
	v_add_f32_e32 v5, v200, v201
	v_add_f32_e32 v4, v4, v5
	v_fmamk_f32 v4, v4, 0x3a800000, v212
	v_rsq_f32_e32 v6, v4
	s_add_u32 s12, s12, 0x8000
	s_addc_u32 s13, s13, 0
	v_pk_fma_f32 v[86:87], v[86:87], v[6:7], v[152:153] op_sel_hi:[1,0,1]
	v_pk_fma_f32 v[84:85], v[84:85], v[6:7], v[150:151] op_sel_hi:[1,0,1]
	v_pk_fma_f32 v[82:83], v[82:83], v[6:7], v[148:149] op_sel_hi:[1,0,1]
	v_pk_fma_f32 v[80:81], v[80:81], v[6:7], v[146:147] op_sel_hi:[1,0,1]
	v_pk_fma_f32 v[78:79], v[78:79], v[6:7], v[144:145] op_sel_hi:[1,0,1]
	v_pk_fma_f32 v[76:77], v[76:77], v[6:7], v[142:143] op_sel_hi:[1,0,1]
	v_pk_fma_f32 v[74:75], v[74:75], v[6:7], v[140:141] op_sel_hi:[1,0,1]
	v_pk_fma_f32 v[72:73], v[72:73], v[6:7], v[138:139] op_sel_hi:[1,0,1]
	v_mul_f32_e32 v0, 0xbfb8aa3b, v84
	v_mul_f32_e32 v1, 0xbfb8aa3b, v85
	v_mul_f32_e32 v2, 0xbfb8aa3b, v86
	v_mul_f32_e32 v3, 0xbfb8aa3b, v87
	v_mul_f32_e32 v242, 0xbfb8aa3b, v80
	v_mul_f32_e32 v243, 0xbfb8aa3b, v81
	v_mul_f32_e32 v244, 0xbfb8aa3b, v82
	v_mul_f32_e32 v245, 0xbfb8aa3b, v83
	v_exp_f32_e32 v0, v0
	v_exp_f32_e32 v1, v1
	v_exp_f32_e32 v2, v2
	v_exp_f32_e32 v3, v3
	v_exp_f32_e32 v242, v242
	v_exp_f32_e32 v243, v243
	v_exp_f32_e32 v244, v244
	v_exp_f32_e32 v245, v245
	v_add_f32_e32 v0, 1.0, v0
	v_add_f32_e32 v1, 1.0, v1
	v_add_f32_e32 v2, 1.0, v2
	v_add_f32_e32 v3, 1.0, v3
	v_add_f32_e32 v242, 1.0, v242
	v_add_f32_e32 v243, 1.0, v243
	v_add_f32_e32 v244, 1.0, v244
	v_add_f32_e32 v245, 1.0, v245
	v_rcp_f32_e32 v0, v0
	v_rcp_f32_e32 v1, v1
	v_rcp_f32_e32 v2, v2
	v_rcp_f32_e32 v3, v3
	v_rcp_f32_e32 v242, v242
	v_rcp_f32_e32 v243, v243
	v_rcp_f32_e32 v244, v244
	v_rcp_f32_e32 v245, v245
	v_pk_mul_f32 v[84:85], v[84:85], v[0:1]
	v_pk_mul_f32 v[86:87], v[86:87], v[2:3]
	v_pk_mul_f32 v[80:81], v[80:81], v[242:243]
	v_pk_mul_f32 v[82:83], v[82:83], v[244:245]
	v_mul_f32_e32 v0, 0xbfb8aa3b, v76
	v_mul_f32_e32 v1, 0xbfb8aa3b, v77
	v_mul_f32_e32 v2, 0xbfb8aa3b, v78
	v_mul_f32_e32 v3, 0xbfb8aa3b, v79
	v_mul_f32_e32 v242, 0xbfb8aa3b, v72
	v_mul_f32_e32 v243, 0xbfb8aa3b, v73
	v_mul_f32_e32 v244, 0xbfb8aa3b, v74
	v_mul_f32_e32 v245, 0xbfb8aa3b, v75
	v_exp_f32_e32 v0, v0
	v_exp_f32_e32 v1, v1
	v_exp_f32_e32 v2, v2
	v_exp_f32_e32 v3, v3
	v_exp_f32_e32 v242, v242
	v_exp_f32_e32 v243, v243
	v_exp_f32_e32 v244, v244
	v_exp_f32_e32 v245, v245
	v_add_f32_e32 v0, 1.0, v0
	v_add_f32_e32 v1, 1.0, v1
	v_add_f32_e32 v2, 1.0, v2
	v_add_f32_e32 v3, 1.0, v3
	v_add_f32_e32 v242, 1.0, v242
	v_add_f32_e32 v243, 1.0, v243
	v_add_f32_e32 v244, 1.0, v244
	v_add_f32_e32 v245, 1.0, v245
	v_rcp_f32_e32 v0, v0
	v_rcp_f32_e32 v1, v1
	v_rcp_f32_e32 v2, v2
	v_rcp_f32_e32 v3, v3
	v_rcp_f32_e32 v242, v242
	v_rcp_f32_e32 v243, v243
	v_rcp_f32_e32 v244, v244
	v_rcp_f32_e32 v245, v245
	v_pk_mul_f32 v[76:77], v[76:77], v[0:1]
	v_pk_mul_f32 v[78:79], v[78:79], v[2:3]
	v_pk_mul_f32 v[72:73], v[72:73], v[242:243]
	v_pk_mul_f32 v[74:75], v[74:75], v[244:245]
	v_cvt_pk_bf16_f32 v234, v84, v85
	v_cvt_pk_bf16_f32 v235, v86, v87
	v_cvt_pk_bf16_f32 v236, v80, v81
	v_cvt_pk_bf16_f32 v237, v82, v83
	v_cvt_pk_bf16_f32 v238, v76, v77
	v_cvt_pk_bf16_f32 v239, v78, v79
	v_cvt_pk_bf16_f32 v240, v72, v73
	v_cvt_pk_bf16_f32 v241, v74, v75
	s_mov_b64 vcc, s[6:7]
	v_cndmask_b32_dpp v84, v238, v234, vcc row_ror:8 row_mask:0xf bank_mask:0xf
	v_cndmask_b32_dpp v85, v239, v235, vcc row_ror:8 row_mask:0xf bank_mask:0xf
	v_cndmask_b32_dpp v86, v240, v236, vcc row_ror:8 row_mask:0xf bank_mask:0xf
	v_cndmask_b32_dpp v87, v241, v237, vcc row_ror:8 row_mask:0xf bank_mask:0xf
	s_not_b64 vcc, s[6:7]
	v_cndmask_b32_dpp v80, v234, v238, vcc row_ror:8 row_mask:0xf bank_mask:0xf
	v_cndmask_b32_dpp v81, v235, v239, vcc row_ror:8 row_mask:0xf bank_mask:0xf
	v_cndmask_b32_dpp v82, v236, v240, vcc row_ror:8 row_mask:0xf bank_mask:0xf
	v_cndmask_b32_dpp v83, v237, v241, vcc row_ror:8 row_mask:0xf bank_mask:0xf
	global_store_dwordx4 v246, v[84:87], s[12:13]
	global_store_dwordx4 v247, v[80:83], s[12:13]
	v_add_f32_e32 v4, v202, v203
	v_add_f32_e32 v5, v204, v205
	v_add_f32_e32 v4, v4, v5
	v_fmamk_f32 v4, v4, 0x3a800000, v212
	v_rsq_f32_e32 v6, v4
	s_add_u32 s12, s12, 0x28000
	s_addc_u32 s13, s13, 0
	v_pk_fma_f32 v[70:71], v[70:71], v[6:7], v[152:153] op_sel_hi:[1,0,1]
	v_pk_fma_f32 v[68:69], v[68:69], v[6:7], v[150:151] op_sel_hi:[1,0,1]
	v_pk_fma_f32 v[66:67], v[66:67], v[6:7], v[148:149] op_sel_hi:[1,0,1]
	v_pk_fma_f32 v[64:65], v[64:65], v[6:7], v[146:147] op_sel_hi:[1,0,1]
	v_pk_fma_f32 v[62:63], v[62:63], v[6:7], v[144:145] op_sel_hi:[1,0,1]
	v_pk_fma_f32 v[60:61], v[60:61], v[6:7], v[142:143] op_sel_hi:[1,0,1]
	v_pk_fma_f32 v[58:59], v[58:59], v[6:7], v[140:141] op_sel_hi:[1,0,1]
	v_pk_fma_f32 v[56:57], v[56:57], v[6:7], v[138:139] op_sel_hi:[1,0,1]
	v_mul_f32_e32 v0, 0xbfb8aa3b, v68
	v_mul_f32_e32 v1, 0xbfb8aa3b, v69
	v_mul_f32_e32 v2, 0xbfb8aa3b, v70
	v_mul_f32_e32 v3, 0xbfb8aa3b, v71
	v_mul_f32_e32 v242, 0xbfb8aa3b, v64
	v_mul_f32_e32 v243, 0xbfb8aa3b, v65
	v_mul_f32_e32 v244, 0xbfb8aa3b, v66
	v_mul_f32_e32 v245, 0xbfb8aa3b, v67
	v_exp_f32_e32 v0, v0
	v_exp_f32_e32 v1, v1
	v_exp_f32_e32 v2, v2
	v_exp_f32_e32 v3, v3
	v_exp_f32_e32 v242, v242
	v_exp_f32_e32 v243, v243
	v_exp_f32_e32 v244, v244
	v_exp_f32_e32 v245, v245
	v_add_f32_e32 v0, 1.0, v0
	v_add_f32_e32 v1, 1.0, v1
	v_add_f32_e32 v2, 1.0, v2
	v_add_f32_e32 v3, 1.0, v3
	v_add_f32_e32 v242, 1.0, v242
	v_add_f32_e32 v243, 1.0, v243
	v_add_f32_e32 v244, 1.0, v244
	v_add_f32_e32 v245, 1.0, v245
	v_rcp_f32_e32 v0, v0
	v_rcp_f32_e32 v1, v1
	v_rcp_f32_e32 v2, v2
	v_rcp_f32_e32 v3, v3
	v_rcp_f32_e32 v242, v242
	v_rcp_f32_e32 v243, v243
	v_rcp_f32_e32 v244, v244
	v_rcp_f32_e32 v245, v245
	v_pk_mul_f32 v[68:69], v[68:69], v[0:1]
	v_pk_mul_f32 v[70:71], v[70:71], v[2:3]
	v_pk_mul_f32 v[64:65], v[64:65], v[242:243]
	v_pk_mul_f32 v[66:67], v[66:67], v[244:245]
	v_mul_f32_e32 v0, 0xbfb8aa3b, v60
	v_mul_f32_e32 v1, 0xbfb8aa3b, v61
	v_mul_f32_e32 v2, 0xbfb8aa3b, v62
	v_mul_f32_e32 v3, 0xbfb8aa3b, v63
	v_mul_f32_e32 v242, 0xbfb8aa3b, v56
	v_mul_f32_e32 v243, 0xbfb8aa3b, v57
	v_mul_f32_e32 v244, 0xbfb8aa3b, v58
	v_mul_f32_e32 v245, 0xbfb8aa3b, v59
	v_exp_f32_e32 v0, v0
	v_exp_f32_e32 v1, v1
	v_exp_f32_e32 v2, v2
	v_exp_f32_e32 v3, v3
	v_exp_f32_e32 v242, v242
	v_exp_f32_e32 v243, v243
	v_exp_f32_e32 v244, v244
	v_exp_f32_e32 v245, v245
	v_add_f32_e32 v0, 1.0, v0
	v_add_f32_e32 v1, 1.0, v1
	v_add_f32_e32 v2, 1.0, v2
	v_add_f32_e32 v3, 1.0, v3
	v_add_f32_e32 v242, 1.0, v242
	v_add_f32_e32 v243, 1.0, v243
	v_add_f32_e32 v244, 1.0, v244
	v_add_f32_e32 v245, 1.0, v245
	v_rcp_f32_e32 v0, v0
	v_rcp_f32_e32 v1, v1
	v_rcp_f32_e32 v2, v2
	v_rcp_f32_e32 v3, v3
	v_rcp_f32_e32 v242, v242
	v_rcp_f32_e32 v243, v243
	v_rcp_f32_e32 v244, v244
	v_rcp_f32_e32 v245, v245
	v_pk_mul_f32 v[60:61], v[60:61], v[0:1]
	v_pk_mul_f32 v[62:63], v[62:63], v[2:3]
	v_pk_mul_f32 v[56:57], v[56:57], v[242:243]
	v_pk_mul_f32 v[58:59], v[58:59], v[244:245]
	v_cvt_pk_bf16_f32 v234, v68, v69
	v_cvt_pk_bf16_f32 v235, v70, v71
	v_cvt_pk_bf16_f32 v236, v64, v65
	v_cvt_pk_bf16_f32 v237, v66, v67
	v_cvt_pk_bf16_f32 v238, v60, v61
	v_cvt_pk_bf16_f32 v239, v62, v63
	v_cvt_pk_bf16_f32 v240, v56, v57
	v_cvt_pk_bf16_f32 v241, v58, v59
	s_mov_b64 vcc, s[6:7]
	v_cndmask_b32_dpp v68, v238, v234, vcc row_ror:8 row_mask:0xf bank_mask:0xf
	v_cndmask_b32_dpp v69, v239, v235, vcc row_ror:8 row_mask:0xf bank_mask:0xf
	v_cndmask_b32_dpp v70, v240, v236, vcc row_ror:8 row_mask:0xf bank_mask:0xf
	v_cndmask_b32_dpp v71, v241, v237, vcc row_ror:8 row_mask:0xf bank_mask:0xf
	s_not_b64 vcc, s[6:7]
	v_cndmask_b32_dpp v64, v234, v238, vcc row_ror:8 row_mask:0xf bank_mask:0xf
	v_cndmask_b32_dpp v65, v235, v239, vcc row_ror:8 row_mask:0xf bank_mask:0xf
	v_cndmask_b32_dpp v66, v236, v240, vcc row_ror:8 row_mask:0xf bank_mask:0xf
	v_cndmask_b32_dpp v67, v237, v241, vcc row_ror:8 row_mask:0xf bank_mask:0xf
	global_store_dwordx4 v246, v[68:71], s[12:13]
	global_store_dwordx4 v247, v[64:67], s[12:13]
	v_add_f32_e32 v4, v222, v223
	v_add_f32_e32 v5, v224, v225
	v_add_f32_e32 v4, v4, v5
	v_fmamk_f32 v4, v4, 0x3a800000, v212
	v_rsq_f32_e32 v6, v4
	s_add_u32 s12, s12, 0x8000
	s_addc_u32 s13, s13, 0
	v_pk_fma_f32 v[54:55], v[54:55], v[6:7], v[152:153] op_sel_hi:[1,0,1]
	v_pk_fma_f32 v[52:53], v[52:53], v[6:7], v[150:151] op_sel_hi:[1,0,1]
	v_pk_fma_f32 v[50:51], v[50:51], v[6:7], v[148:149] op_sel_hi:[1,0,1]
	v_pk_fma_f32 v[48:49], v[48:49], v[6:7], v[146:147] op_sel_hi:[1,0,1]
	v_pk_fma_f32 v[46:47], v[46:47], v[6:7], v[144:145] op_sel_hi:[1,0,1]
	v_pk_fma_f32 v[44:45], v[44:45], v[6:7], v[142:143] op_sel_hi:[1,0,1]
	v_pk_fma_f32 v[42:43], v[42:43], v[6:7], v[140:141] op_sel_hi:[1,0,1]
	v_pk_fma_f32 v[40:41], v[40:41], v[6:7], v[138:139] op_sel_hi:[1,0,1]
	v_mul_f32_e32 v0, 0xbfb8aa3b, v52
	v_mul_f32_e32 v1, 0xbfb8aa3b, v53
	v_mul_f32_e32 v2, 0xbfb8aa3b, v54
	v_mul_f32_e32 v3, 0xbfb8aa3b, v55
	v_mul_f32_e32 v242, 0xbfb8aa3b, v48
	v_mul_f32_e32 v243, 0xbfb8aa3b, v49
	v_mul_f32_e32 v244, 0xbfb8aa3b, v50
	v_mul_f32_e32 v245, 0xbfb8aa3b, v51
	v_exp_f32_e32 v0, v0
	v_exp_f32_e32 v1, v1
	v_exp_f32_e32 v2, v2
	v_exp_f32_e32 v3, v3
	v_exp_f32_e32 v242, v242
	v_exp_f32_e32 v243, v243
	v_exp_f32_e32 v244, v244
	v_exp_f32_e32 v245, v245
	v_add_f32_e32 v0, 1.0, v0
	v_add_f32_e32 v1, 1.0, v1
	v_add_f32_e32 v2, 1.0, v2
	v_add_f32_e32 v3, 1.0, v3
	v_add_f32_e32 v242, 1.0, v242
	v_add_f32_e32 v243, 1.0, v243
	v_add_f32_e32 v244, 1.0, v244
	v_add_f32_e32 v245, 1.0, v245
	v_rcp_f32_e32 v0, v0
	v_rcp_f32_e32 v1, v1
	v_rcp_f32_e32 v2, v2
	v_rcp_f32_e32 v3, v3
	v_rcp_f32_e32 v242, v242
	v_rcp_f32_e32 v243, v243
	v_rcp_f32_e32 v244, v244
	v_rcp_f32_e32 v245, v245
	v_pk_mul_f32 v[52:53], v[52:53], v[0:1]
	v_pk_mul_f32 v[54:55], v[54:55], v[2:3]
	v_pk_mul_f32 v[48:49], v[48:49], v[242:243]
	v_pk_mul_f32 v[50:51], v[50:51], v[244:245]
	v_mul_f32_e32 v0, 0xbfb8aa3b, v44
	v_mul_f32_e32 v1, 0xbfb8aa3b, v45
	v_mul_f32_e32 v2, 0xbfb8aa3b, v46
	v_mul_f32_e32 v3, 0xbfb8aa3b, v47
	v_mul_f32_e32 v242, 0xbfb8aa3b, v40
	v_mul_f32_e32 v243, 0xbfb8aa3b, v41
	v_mul_f32_e32 v244, 0xbfb8aa3b, v42
	v_mul_f32_e32 v245, 0xbfb8aa3b, v43
	v_exp_f32_e32 v0, v0
	v_exp_f32_e32 v1, v1
	v_exp_f32_e32 v2, v2
	v_exp_f32_e32 v3, v3
	v_exp_f32_e32 v242, v242
	v_exp_f32_e32 v243, v243
	v_exp_f32_e32 v244, v244
	v_exp_f32_e32 v245, v245
	v_add_f32_e32 v0, 1.0, v0
	v_add_f32_e32 v1, 1.0, v1
	v_add_f32_e32 v2, 1.0, v2
	v_add_f32_e32 v3, 1.0, v3
	v_add_f32_e32 v242, 1.0, v242
	v_add_f32_e32 v243, 1.0, v243
	v_add_f32_e32 v244, 1.0, v244
	v_add_f32_e32 v245, 1.0, v245
	v_rcp_f32_e32 v0, v0
	v_rcp_f32_e32 v1, v1
	v_rcp_f32_e32 v2, v2
	v_rcp_f32_e32 v3, v3
	v_rcp_f32_e32 v242, v242
	v_rcp_f32_e32 v243, v243
	v_rcp_f32_e32 v244, v244
	v_rcp_f32_e32 v245, v245
	v_pk_mul_f32 v[44:45], v[44:45], v[0:1]
	v_pk_mul_f32 v[46:47], v[46:47], v[2:3]
	v_pk_mul_f32 v[40:41], v[40:41], v[242:243]
	v_pk_mul_f32 v[42:43], v[42:43], v[244:245]
	v_cvt_pk_bf16_f32 v234, v52, v53
	v_cvt_pk_bf16_f32 v235, v54, v55
	v_cvt_pk_bf16_f32 v236, v48, v49
	v_cvt_pk_bf16_f32 v237, v50, v51
	v_cvt_pk_bf16_f32 v238, v44, v45
	v_cvt_pk_bf16_f32 v239, v46, v47
	v_cvt_pk_bf16_f32 v240, v40, v41
	v_cvt_pk_bf16_f32 v241, v42, v43
	s_mov_b64 vcc, s[6:7]
	v_cndmask_b32_dpp v52, v238, v234, vcc row_ror:8 row_mask:0xf bank_mask:0xf
	v_cndmask_b32_dpp v53, v239, v235, vcc row_ror:8 row_mask:0xf bank_mask:0xf
	v_cndmask_b32_dpp v54, v240, v236, vcc row_ror:8 row_mask:0xf bank_mask:0xf
	v_cndmask_b32_dpp v55, v241, v237, vcc row_ror:8 row_mask:0xf bank_mask:0xf
	s_not_b64 vcc, s[6:7]
	v_cndmask_b32_dpp v48, v234, v238, vcc row_ror:8 row_mask:0xf bank_mask:0xf
	v_cndmask_b32_dpp v49, v235, v239, vcc row_ror:8 row_mask:0xf bank_mask:0xf
	v_cndmask_b32_dpp v50, v236, v240, vcc row_ror:8 row_mask:0xf bank_mask:0xf
	v_cndmask_b32_dpp v51, v237, v241, vcc row_ror:8 row_mask:0xf bank_mask:0xf
	global_store_dwordx4 v246, v[52:55], s[12:13]
	global_store_dwordx4 v247, v[48:51], s[12:13]
	v_add_f32_e32 v4, v226, v227
	v_add_f32_e32 v5, v228, v229
	v_add_f32_e32 v4, v4, v5
	v_fmamk_f32 v4, v4, 0x3a800000, v212
	v_rsq_f32_e32 v6, v4
	s_add_u32 s12, s12, 0x8000
	s_addc_u32 s13, s13, 0
	v_pk_fma_f32 v[38:39], v[38:39], v[6:7], v[152:153] op_sel_hi:[1,0,1]
	v_pk_fma_f32 v[36:37], v[36:37], v[6:7], v[150:151] op_sel_hi:[1,0,1]
	v_pk_fma_f32 v[34:35], v[34:35], v[6:7], v[148:149] op_sel_hi:[1,0,1]
	v_pk_fma_f32 v[32:33], v[32:33], v[6:7], v[146:147] op_sel_hi:[1,0,1]
	v_pk_fma_f32 v[30:31], v[30:31], v[6:7], v[144:145] op_sel_hi:[1,0,1]
	v_pk_fma_f32 v[28:29], v[28:29], v[6:7], v[142:143] op_sel_hi:[1,0,1]
	v_pk_fma_f32 v[26:27], v[26:27], v[6:7], v[140:141] op_sel_hi:[1,0,1]
	v_pk_fma_f32 v[24:25], v[24:25], v[6:7], v[138:139] op_sel_hi:[1,0,1]
	v_mul_f32_e32 v0, 0xbfb8aa3b, v36
	v_mul_f32_e32 v1, 0xbfb8aa3b, v37
	v_mul_f32_e32 v2, 0xbfb8aa3b, v38
	v_mul_f32_e32 v3, 0xbfb8aa3b, v39
	v_mul_f32_e32 v242, 0xbfb8aa3b, v32
	v_mul_f32_e32 v243, 0xbfb8aa3b, v33
	v_mul_f32_e32 v244, 0xbfb8aa3b, v34
	v_mul_f32_e32 v245, 0xbfb8aa3b, v35
	v_exp_f32_e32 v0, v0
	v_exp_f32_e32 v1, v1
	v_exp_f32_e32 v2, v2
	v_exp_f32_e32 v3, v3
	v_exp_f32_e32 v242, v242
	v_exp_f32_e32 v243, v243
	v_exp_f32_e32 v244, v244
	v_exp_f32_e32 v245, v245
	v_add_f32_e32 v0, 1.0, v0
	v_add_f32_e32 v1, 1.0, v1
	v_add_f32_e32 v2, 1.0, v2
	v_add_f32_e32 v3, 1.0, v3
	v_add_f32_e32 v242, 1.0, v242
	v_add_f32_e32 v243, 1.0, v243
	v_add_f32_e32 v244, 1.0, v244
	v_add_f32_e32 v245, 1.0, v245
	v_rcp_f32_e32 v0, v0
	v_rcp_f32_e32 v1, v1
	v_rcp_f32_e32 v2, v2
	v_rcp_f32_e32 v3, v3
	v_rcp_f32_e32 v242, v242
	v_rcp_f32_e32 v243, v243
	v_rcp_f32_e32 v244, v244
	v_rcp_f32_e32 v245, v245
	v_pk_mul_f32 v[36:37], v[36:37], v[0:1]
	v_pk_mul_f32 v[38:39], v[38:39], v[2:3]
	v_pk_mul_f32 v[32:33], v[32:33], v[242:243]
	v_pk_mul_f32 v[34:35], v[34:35], v[244:245]
	v_mul_f32_e32 v0, 0xbfb8aa3b, v28
	v_mul_f32_e32 v1, 0xbfb8aa3b, v29
	v_mul_f32_e32 v2, 0xbfb8aa3b, v30
	v_mul_f32_e32 v3, 0xbfb8aa3b, v31
	v_mul_f32_e32 v242, 0xbfb8aa3b, v24
	v_mul_f32_e32 v243, 0xbfb8aa3b, v25
	v_mul_f32_e32 v244, 0xbfb8aa3b, v26
	v_mul_f32_e32 v245, 0xbfb8aa3b, v27
	v_exp_f32_e32 v0, v0
	v_exp_f32_e32 v1, v1
	v_exp_f32_e32 v2, v2
	v_exp_f32_e32 v3, v3
	v_exp_f32_e32 v242, v242
	v_exp_f32_e32 v243, v243
	v_exp_f32_e32 v244, v244
	v_exp_f32_e32 v245, v245
	v_add_f32_e32 v0, 1.0, v0
	v_add_f32_e32 v1, 1.0, v1
	v_add_f32_e32 v2, 1.0, v2
	v_add_f32_e32 v3, 1.0, v3
	v_add_f32_e32 v242, 1.0, v242
	v_add_f32_e32 v243, 1.0, v243
	v_add_f32_e32 v244, 1.0, v244
	v_add_f32_e32 v245, 1.0, v245
	v_rcp_f32_e32 v0, v0
	v_rcp_f32_e32 v1, v1
	v_rcp_f32_e32 v2, v2
	v_rcp_f32_e32 v3, v3
	v_rcp_f32_e32 v242, v242
	v_rcp_f32_e32 v243, v243
	v_rcp_f32_e32 v244, v244
	v_rcp_f32_e32 v245, v245
	v_pk_mul_f32 v[28:29], v[28:29], v[0:1]
	v_pk_mul_f32 v[30:31], v[30:31], v[2:3]
	v_pk_mul_f32 v[24:25], v[24:25], v[242:243]
	v_pk_mul_f32 v[26:27], v[26:27], v[244:245]
	v_cvt_pk_bf16_f32 v234, v36, v37
	v_cvt_pk_bf16_f32 v235, v38, v39
	v_cvt_pk_bf16_f32 v236, v32, v33
	v_cvt_pk_bf16_f32 v237, v34, v35
	v_cvt_pk_bf16_f32 v238, v28, v29
	v_cvt_pk_bf16_f32 v239, v30, v31
	v_cvt_pk_bf16_f32 v240, v24, v25
	v_cvt_pk_bf16_f32 v241, v26, v27
	s_mov_b64 vcc, s[6:7]
	v_cndmask_b32_dpp v36, v238, v234, vcc row_ror:8 row_mask:0xf bank_mask:0xf
	v_cndmask_b32_dpp v37, v239, v235, vcc row_ror:8 row_mask:0xf bank_mask:0xf
	v_cndmask_b32_dpp v38, v240, v236, vcc row_ror:8 row_mask:0xf bank_mask:0xf
	v_cndmask_b32_dpp v39, v241, v237, vcc row_ror:8 row_mask:0xf bank_mask:0xf
	s_not_b64 vcc, s[6:7]
	v_cndmask_b32_dpp v32, v234, v238, vcc row_ror:8 row_mask:0xf bank_mask:0xf
	v_cndmask_b32_dpp v33, v235, v239, vcc row_ror:8 row_mask:0xf bank_mask:0xf
	v_cndmask_b32_dpp v34, v236, v240, vcc row_ror:8 row_mask:0xf bank_mask:0xf
	v_cndmask_b32_dpp v35, v237, v241, vcc row_ror:8 row_mask:0xf bank_mask:0xf
	global_store_dwordx4 v246, v[36:39], s[12:13]
	global_store_dwordx4 v247, v[32:35], s[12:13]
	v_add_f32_e32 v4, v230, v231
	v_add_f32_e32 v5, v232, v233
	v_add_f32_e32 v4, v4, v5
	v_fmamk_f32 v4, v4, 0x3a800000, v212
	v_rsq_f32_e32 v6, v4
	s_add_u32 s12, s12, 0x8000
	s_addc_u32 s13, s13, 0
	v_pk_fma_f32 v[22:23], v[22:23], v[6:7], v[152:153] op_sel_hi:[1,0,1]
	v_pk_fma_f32 v[20:21], v[20:21], v[6:7], v[150:151] op_sel_hi:[1,0,1]
	v_pk_fma_f32 v[18:19], v[18:19], v[6:7], v[148:149] op_sel_hi:[1,0,1]
	v_pk_fma_f32 v[16:17], v[16:17], v[6:7], v[146:147] op_sel_hi:[1,0,1]
	v_pk_fma_f32 v[14:15], v[14:15], v[6:7], v[144:145] op_sel_hi:[1,0,1]
	v_pk_fma_f32 v[12:13], v[12:13], v[6:7], v[142:143] op_sel_hi:[1,0,1]
	v_pk_fma_f32 v[10:11], v[10:11], v[6:7], v[140:141] op_sel_hi:[1,0,1]
	v_pk_fma_f32 v[8:9], v[8:9], v[6:7], v[138:139] op_sel_hi:[1,0,1]
	v_mul_f32_e32 v0, 0xbfb8aa3b, v20
	v_mul_f32_e32 v1, 0xbfb8aa3b, v21
	v_mul_f32_e32 v2, 0xbfb8aa3b, v22
	v_mul_f32_e32 v3, 0xbfb8aa3b, v23
	v_mul_f32_e32 v242, 0xbfb8aa3b, v16
	v_mul_f32_e32 v243, 0xbfb8aa3b, v17
	v_mul_f32_e32 v244, 0xbfb8aa3b, v18
	v_mul_f32_e32 v245, 0xbfb8aa3b, v19
	v_exp_f32_e32 v0, v0
	v_exp_f32_e32 v1, v1
	v_exp_f32_e32 v2, v2
	v_exp_f32_e32 v3, v3
	v_exp_f32_e32 v242, v242
	v_exp_f32_e32 v243, v243
	v_exp_f32_e32 v244, v244
	v_exp_f32_e32 v245, v245
	v_add_f32_e32 v0, 1.0, v0
	v_add_f32_e32 v1, 1.0, v1
	v_add_f32_e32 v2, 1.0, v2
	v_add_f32_e32 v3, 1.0, v3
	v_add_f32_e32 v242, 1.0, v242
	v_add_f32_e32 v243, 1.0, v243
	v_add_f32_e32 v244, 1.0, v244
	v_add_f32_e32 v245, 1.0, v245
	v_rcp_f32_e32 v0, v0
	v_rcp_f32_e32 v1, v1
	v_rcp_f32_e32 v2, v2
	v_rcp_f32_e32 v3, v3
	v_rcp_f32_e32 v242, v242
	v_rcp_f32_e32 v243, v243
	v_rcp_f32_e32 v244, v244
	v_rcp_f32_e32 v245, v245
	v_pk_mul_f32 v[20:21], v[20:21], v[0:1]
	v_pk_mul_f32 v[22:23], v[22:23], v[2:3]
	v_pk_mul_f32 v[16:17], v[16:17], v[242:243]
	v_pk_mul_f32 v[18:19], v[18:19], v[244:245]
	v_mul_f32_e32 v0, 0xbfb8aa3b, v12
	v_mul_f32_e32 v1, 0xbfb8aa3b, v13
	v_mul_f32_e32 v2, 0xbfb8aa3b, v14
	v_mul_f32_e32 v3, 0xbfb8aa3b, v15
	v_mul_f32_e32 v242, 0xbfb8aa3b, v8
	v_mul_f32_e32 v243, 0xbfb8aa3b, v9
	v_mul_f32_e32 v244, 0xbfb8aa3b, v10
	v_mul_f32_e32 v245, 0xbfb8aa3b, v11
	v_exp_f32_e32 v0, v0
	v_exp_f32_e32 v1, v1
	v_exp_f32_e32 v2, v2
	v_exp_f32_e32 v3, v3
	v_exp_f32_e32 v242, v242
	v_exp_f32_e32 v243, v243
	v_exp_f32_e32 v244, v244
	v_exp_f32_e32 v245, v245
	v_add_f32_e32 v0, 1.0, v0
	v_add_f32_e32 v1, 1.0, v1
	v_add_f32_e32 v2, 1.0, v2
	v_add_f32_e32 v3, 1.0, v3
	v_add_f32_e32 v242, 1.0, v242
	v_add_f32_e32 v243, 1.0, v243
	v_add_f32_e32 v244, 1.0, v244
	v_add_f32_e32 v245, 1.0, v245
	v_rcp_f32_e32 v0, v0
	v_rcp_f32_e32 v1, v1
	v_rcp_f32_e32 v2, v2
	v_rcp_f32_e32 v3, v3
	v_rcp_f32_e32 v242, v242
	v_rcp_f32_e32 v243, v243
	v_rcp_f32_e32 v244, v244
	v_rcp_f32_e32 v245, v245
	v_pk_mul_f32 v[12:13], v[12:13], v[0:1]
	v_pk_mul_f32 v[14:15], v[14:15], v[2:3]
	v_pk_mul_f32 v[8:9], v[8:9], v[242:243]
	v_pk_mul_f32 v[10:11], v[10:11], v[244:245]
	v_cvt_pk_bf16_f32 v234, v20, v21
	v_cvt_pk_bf16_f32 v235, v22, v23
	v_cvt_pk_bf16_f32 v236, v16, v17
	v_cvt_pk_bf16_f32 v237, v18, v19
	v_cvt_pk_bf16_f32 v238, v12, v13
	v_cvt_pk_bf16_f32 v239, v14, v15
	v_cvt_pk_bf16_f32 v240, v8, v9
	v_cvt_pk_bf16_f32 v241, v10, v11
	s_mov_b64 vcc, s[6:7]
	v_cndmask_b32_dpp v20, v238, v234, vcc row_ror:8 row_mask:0xf bank_mask:0xf
	v_cndmask_b32_dpp v21, v239, v235, vcc row_ror:8 row_mask:0xf bank_mask:0xf
	v_cndmask_b32_dpp v22, v240, v236, vcc row_ror:8 row_mask:0xf bank_mask:0xf
	v_cndmask_b32_dpp v23, v241, v237, vcc row_ror:8 row_mask:0xf bank_mask:0xf
	s_not_b64 vcc, s[6:7]
	v_cndmask_b32_dpp v16, v234, v238, vcc row_ror:8 row_mask:0xf bank_mask:0xf
	v_cndmask_b32_dpp v17, v235, v239, vcc row_ror:8 row_mask:0xf bank_mask:0xf
	v_cndmask_b32_dpp v18, v236, v240, vcc row_ror:8 row_mask:0xf bank_mask:0xf
	v_cndmask_b32_dpp v19, v237, v241, vcc row_ror:8 row_mask:0xf bank_mask:0xf
	global_store_dwordx4 v246, v[20:23], s[12:13]
	global_store_dwordx4 v247, v[16:19], s[12:13]
	s_mov_b32 s100, 1
	s_branch .LBB0_1422
.Lfi_plain:
	v_add_f32_e32 v4, v186, v187
	v_add_f32_e32 v5, v188, v189
	v_add_f32_e32 v4, v4, v5
	v_fmamk_f32 v4, v4, 0x3a800000, v212
	v_rsq_f32_e32 v6, v4
	s_nop 1
	v_pk_fma_f32 v[136:137], v[136:137], v[6:7], v[152:153] op_sel_hi:[1,0,1]
	v_pk_fma_f32 v[134:135], v[134:135], v[6:7], v[150:151] op_sel_hi:[1,0,1]
	v_pk_fma_f32 v[132:133], v[132:133], v[6:7], v[148:149] op_sel_hi:[1,0,1]
	v_pk_fma_f32 v[130:131], v[130:131], v[6:7], v[146:147] op_sel_hi:[1,0,1]
	v_pk_fma_f32 v[128:129], v[128:129], v[6:7], v[144:145] op_sel_hi:[1,0,1]
	v_pk_fma_f32 v[126:127], v[126:127], v[6:7], v[142:143] op_sel_hi:[1,0,1]
	v_pk_fma_f32 v[124:125], v[124:125], v[6:7], v[140:141] op_sel_hi:[1,0,1]
	v_pk_fma_f32 v[122:123], v[122:123], v[6:7], v[138:139] op_sel_hi:[1,0,1]
	v_cvt_pk_bf16_f32 v234, v134, v135
	v_cvt_pk_bf16_f32 v235, v136, v137
	v_cvt_pk_bf16_f32 v236, v130, v131
	v_cvt_pk_bf16_f32 v237, v132, v133
	v_cvt_pk_bf16_f32 v238, v126, v127
	v_cvt_pk_bf16_f32 v239, v128, v129
	v_cvt_pk_bf16_f32 v240, v122, v123
	v_cvt_pk_bf16_f32 v241, v124, v125
	s_mov_b64 vcc, s[6:7]
	v_cndmask_b32_dpp v134, v238, v234, vcc row_ror:8 row_mask:0xf bank_mask:0xf
	v_cndmask_b32_dpp v135, v239, v235, vcc row_ror:8 row_mask:0xf bank_mask:0xf
	v_cndmask_b32_dpp v136, v240, v236, vcc row_ror:8 row_mask:0xf bank_mask:0xf
	v_cndmask_b32_dpp v137, v241, v237, vcc row_ror:8 row_mask:0xf bank_mask:0xf
	s_not_b64 vcc, s[6:7]
	v_cndmask_b32_dpp v130, v234, v238, vcc row_ror:8 row_mask:0xf bank_mask:0xf
	v_cndmask_b32_dpp v131, v235, v239, vcc row_ror:8 row_mask:0xf bank_mask:0xf
	v_cndmask_b32_dpp v132, v236, v240, vcc row_ror:8 row_mask:0xf bank_mask:0xf
	v_cndmask_b32_dpp v133, v237, v241, vcc row_ror:8 row_mask:0xf bank_mask:0xf
	global_store_dwordx4 v246, v[134:137], s[12:13]
	global_store_dwordx4 v247, v[130:133], s[12:13]
	v_add_f32_e32 v4, v190, v191
	v_add_f32_e32 v5, v192, v193
	v_add_f32_e32 v4, v4, v5
	v_fmamk_f32 v4, v4, 0x3a800000, v212
	v_rsq_f32_e32 v6, v4
	s_add_u32 s12, s12, 0x8000
	s_addc_u32 s13, s13, 0
	v_pk_fma_f32 v[120:121], v[120:121], v[6:7], v[152:153] op_sel_hi:[1,0,1]
	v_pk_fma_f32 v[118:119], v[118:119], v[6:7], v[150:151] op_sel_hi:[1,0,1]
	v_pk_fma_f32 v[116:117], v[116:117], v[6:7], v[148:149] op_sel_hi:[1,0,1]
	v_pk_fma_f32 v[114:115], v[114:115], v[6:7], v[146:147] op_sel_hi:[1,0,1]
	v_pk_fma_f32 v[112:113], v[112:113], v[6:7], v[144:145] op_sel_hi:[1,0,1]
	v_pk_fma_f32 v[110:111], v[110:111], v[6:7], v[142:143] op_sel_hi:[1,0,1]
	v_pk_fma_f32 v[108:109], v[108:109], v[6:7], v[140:141] op_sel_hi:[1,0,1]
	v_pk_fma_f32 v[106:107], v[106:107], v[6:7], v[138:139] op_sel_hi:[1,0,1]
	v_cvt_pk_bf16_f32 v234, v118, v119
	v_cvt_pk_bf16_f32 v235, v120, v121
	v_cvt_pk_bf16_f32 v236, v114, v115
	v_cvt_pk_bf16_f32 v237, v116, v117
	v_cvt_pk_bf16_f32 v238, v110, v111
	v_cvt_pk_bf16_f32 v239, v112, v113
	v_cvt_pk_bf16_f32 v240, v106, v107
	v_cvt_pk_bf16_f32 v241, v108, v109
	s_mov_b64 vcc, s[6:7]
	v_cndmask_b32_dpp v118, v238, v234, vcc row_ror:8 row_mask:0xf bank_mask:0xf
	v_cndmask_b32_dpp v119, v239, v235, vcc row_ror:8 row_mask:0xf bank_mask:0xf
	v_cndmask_b32_dpp v120, v240, v236, vcc row_ror:8 row_mask:0xf bank_mask:0xf
	v_cndmask_b32_dpp v121, v241, v237, vcc row_ror:8 row_mask:0xf bank_mask:0xf
	s_not_b64 vcc, s[6:7]
	v_cndmask_b32_dpp v114, v234, v238, vcc row_ror:8 row_mask:0xf bank_mask:0xf
	v_cndmask_b32_dpp v115, v235, v239, vcc row_ror:8 row_mask:0xf bank_mask:0xf
	v_cndmask_b32_dpp v116, v236, v240, vcc row_ror:8 row_mask:0xf bank_mask:0xf
	v_cndmask_b32_dpp v117, v237, v241, vcc row_ror:8 row_mask:0xf bank_mask:0xf
	global_store_dwordx4 v246, v[118:121], s[12:13]
	global_store_dwordx4 v247, v[114:117], s[12:13]
	v_add_f32_e32 v4, v194, v195
	v_add_f32_e32 v5, v196, v197
	v_add_f32_e32 v4, v4, v5
	v_fmamk_f32 v4, v4, 0x3a800000, v212
	v_rsq_f32_e32 v6, v4
	s_add_u32 s12, s12, 0x8000
	s_addc_u32 s13, s13, 0
	v_pk_fma_f32 v[104:105], v[104:105], v[6:7], v[152:153] op_sel_hi:[1,0,1]
	v_pk_fma_f32 v[102:103], v[102:103], v[6:7], v[150:151] op_sel_hi:[1,0,1]
	v_pk_fma_f32 v[100:101], v[100:101], v[6:7], v[148:149] op_sel_hi:[1,0,1]
	v_pk_fma_f32 v[98:99], v[98:99], v[6:7], v[146:147] op_sel_hi:[1,0,1]
	v_pk_fma_f32 v[94:95], v[94:95], v[6:7], v[144:145] op_sel_hi:[1,0,1]
	v_pk_fma_f32 v[92:93], v[92:93], v[6:7], v[142:143] op_sel_hi:[1,0,1]
	v_pk_fma_f32 v[90:91], v[90:91], v[6:7], v[140:141] op_sel_hi:[1,0,1]
	v_pk_fma_f32 v[88:89], v[88:89], v[6:7], v[138:139] op_sel_hi:[1,0,1]
	v_cvt_pk_bf16_f32 v234, v102, v103
	v_cvt_pk_bf16_f32 v235, v104, v105
	v_cvt_pk_bf16_f32 v236, v98, v99
	v_cvt_pk_bf16_f32 v237, v100, v101
	v_cvt_pk_bf16_f32 v238, v92, v93
	v_cvt_pk_bf16_f32 v239, v94, v95
	v_cvt_pk_bf16_f32 v240, v88, v89
	v_cvt_pk_bf16_f32 v241, v90, v91
	s_mov_b64 vcc, s[6:7]
	v_cndmask_b32_dpp v102, v238, v234, vcc row_ror:8 row_mask:0xf bank_mask:0xf
	v_cndmask_b32_dpp v103, v239, v235, vcc row_ror:8 row_mask:0xf bank_mask:0xf
	v_cndmask_b32_dpp v104, v240, v236, vcc row_ror:8 row_mask:0xf bank_mask:0xf
	v_cndmask_b32_dpp v105, v241, v237, vcc row_ror:8 row_mask:0xf bank_mask:0xf
	s_not_b64 vcc, s[6:7]
	v_cndmask_b32_dpp v98, v234, v238, vcc row_ror:8 row_mask:0xf bank_mask:0xf
	v_cndmask_b32_dpp v99, v235, v239, vcc row_ror:8 row_mask:0xf bank_mask:0xf
	v_cndmask_b32_dpp v100, v236, v240, vcc row_ror:8 row_mask:0xf bank_mask:0xf
	v_cndmask_b32_dpp v101, v237, v241, vcc row_ror:8 row_mask:0xf bank_mask:0xf
	global_store_dwordx4 v246, v[102:105], s[12:13]
	global_store_dwordx4 v247, v[98:101], s[12:13]
	v_add_f32_e32 v4, v198, v199
	v_add_f32_e32 v5, v200, v201
	v_add_f32_e32 v4, v4, v5
	v_fmamk_f32 v4, v4, 0x3a800000, v212
	v_rsq_f32_e32 v6, v4
	s_add_u32 s12, s12, 0x8000
	s_addc_u32 s13, s13, 0
	v_pk_fma_f32 v[86:87], v[86:87], v[6:7], v[152:153] op_sel_hi:[1,0,1]
	v_pk_fma_f32 v[84:85], v[84:85], v[6:7], v[150:151] op_sel_hi:[1,0,1]
	v_pk_fma_f32 v[82:83], v[82:83], v[6:7], v[148:149] op_sel_hi:[1,0,1]
	v_pk_fma_f32 v[80:81], v[80:81], v[6:7], v[146:147] op_sel_hi:[1,0,1]
	v_pk_fma_f32 v[78:79], v[78:79], v[6:7], v[144:145] op_sel_hi:[1,0,1]
	v_pk_fma_f32 v[76:77], v[76:77], v[6:7], v[142:143] op_sel_hi:[1,0,1]
	v_pk_fma_f32 v[74:75], v[74:75], v[6:7], v[140:141] op_sel_hi:[1,0,1]
	v_pk_fma_f32 v[72:73], v[72:73], v[6:7], v[138:139] op_sel_hi:[1,0,1]
	v_cvt_pk_bf16_f32 v234, v84, v85
	v_cvt_pk_bf16_f32 v235, v86, v87
	v_cvt_pk_bf16_f32 v236, v80, v81
	v_cvt_pk_bf16_f32 v237, v82, v83
	v_cvt_pk_bf16_f32 v238, v76, v77
	v_cvt_pk_bf16_f32 v239, v78, v79
	v_cvt_pk_bf16_f32 v240, v72, v73
	v_cvt_pk_bf16_f32 v241, v74, v75
	s_mov_b64 vcc, s[6:7]
	v_cndmask_b32_dpp v84, v238, v234, vcc row_ror:8 row_mask:0xf bank_mask:0xf
	v_cndmask_b32_dpp v85, v239, v235, vcc row_ror:8 row_mask:0xf bank_mask:0xf
	v_cndmask_b32_dpp v86, v240, v236, vcc row_ror:8 row_mask:0xf bank_mask:0xf
	v_cndmask_b32_dpp v87, v241, v237, vcc row_ror:8 row_mask:0xf bank_mask:0xf
	s_not_b64 vcc, s[6:7]
	v_cndmask_b32_dpp v80, v234, v238, vcc row_ror:8 row_mask:0xf bank_mask:0xf
	v_cndmask_b32_dpp v81, v235, v239, vcc row_ror:8 row_mask:0xf bank_mask:0xf
	v_cndmask_b32_dpp v82, v236, v240, vcc row_ror:8 row_mask:0xf bank_mask:0xf
	v_cndmask_b32_dpp v83, v237, v241, vcc row_ror:8 row_mask:0xf bank_mask:0xf
	global_store_dwordx4 v246, v[84:87], s[12:13]
	global_store_dwordx4 v247, v[80:83], s[12:13]
	v_add_f32_e32 v4, v202, v203
	v_add_f32_e32 v5, v204, v205
	v_add_f32_e32 v4, v4, v5
	v_fmamk_f32 v4, v4, 0x3a800000, v212
	v_rsq_f32_e32 v6, v4
	s_add_u32 s12, s12, 0x28000
	s_addc_u32 s13, s13, 0
	v_pk_fma_f32 v[70:71], v[70:71], v[6:7], v[152:153] op_sel_hi:[1,0,1]
	v_pk_fma_f32 v[68:69], v[68:69], v[6:7], v[150:151] op_sel_hi:[1,0,1]
	v_pk_fma_f32 v[66:67], v[66:67], v[6:7], v[148:149] op_sel_hi:[1,0,1]
	v_pk_fma_f32 v[64:65], v[64:65], v[6:7], v[146:147] op_sel_hi:[1,0,1]
	v_pk_fma_f32 v[62:63], v[62:63], v[6:7], v[144:145] op_sel_hi:[1,0,1]
	v_pk_fma_f32 v[60:61], v[60:61], v[6:7], v[142:143] op_sel_hi:[1,0,1]
	v_pk_fma_f32 v[58:59], v[58:59], v[6:7], v[140:141] op_sel_hi:[1,0,1]
	v_pk_fma_f32 v[56:57], v[56:57], v[6:7], v[138:139] op_sel_hi:[1,0,1]
	v_cvt_pk_bf16_f32 v234, v68, v69
	v_cvt_pk_bf16_f32 v235, v70, v71
	v_cvt_pk_bf16_f32 v236, v64, v65
	v_cvt_pk_bf16_f32 v237, v66, v67
	v_cvt_pk_bf16_f32 v238, v60, v61
	v_cvt_pk_bf16_f32 v239, v62, v63
	v_cvt_pk_bf16_f32 v240, v56, v57
	v_cvt_pk_bf16_f32 v241, v58, v59
	s_mov_b64 vcc, s[6:7]
	v_cndmask_b32_dpp v68, v238, v234, vcc row_ror:8 row_mask:0xf bank_mask:0xf
	v_cndmask_b32_dpp v69, v239, v235, vcc row_ror:8 row_mask:0xf bank_mask:0xf
	v_cndmask_b32_dpp v70, v240, v236, vcc row_ror:8 row_mask:0xf bank_mask:0xf
	v_cndmask_b32_dpp v71, v241, v237, vcc row_ror:8 row_mask:0xf bank_mask:0xf
	s_not_b64 vcc, s[6:7]
	v_cndmask_b32_dpp v64, v234, v238, vcc row_ror:8 row_mask:0xf bank_mask:0xf
	v_cndmask_b32_dpp v65, v235, v239, vcc row_ror:8 row_mask:0xf bank_mask:0xf
	v_cndmask_b32_dpp v66, v236, v240, vcc row_ror:8 row_mask:0xf bank_mask:0xf
	v_cndmask_b32_dpp v67, v237, v241, vcc row_ror:8 row_mask:0xf bank_mask:0xf
	global_store_dwordx4 v246, v[68:71], s[12:13]
	global_store_dwordx4 v247, v[64:67], s[12:13]
	v_add_f32_e32 v4, v222, v223
	v_add_f32_e32 v5, v224, v225
	v_add_f32_e32 v4, v4, v5
	v_fmamk_f32 v4, v4, 0x3a800000, v212
	v_rsq_f32_e32 v6, v4
	s_add_u32 s12, s12, 0x8000
	s_addc_u32 s13, s13, 0
	v_pk_fma_f32 v[54:55], v[54:55], v[6:7], v[152:153] op_sel_hi:[1,0,1]
	v_pk_fma_f32 v[52:53], v[52:53], v[6:7], v[150:151] op_sel_hi:[1,0,1]
	v_pk_fma_f32 v[50:51], v[50:51], v[6:7], v[148:149] op_sel_hi:[1,0,1]
	v_pk_fma_f32 v[48:49], v[48:49], v[6:7], v[146:147] op_sel_hi:[1,0,1]
	v_pk_fma_f32 v[46:47], v[46:47], v[6:7], v[144:145] op_sel_hi:[1,0,1]
	v_pk_fma_f32 v[44:45], v[44:45], v[6:7], v[142:143] op_sel_hi:[1,0,1]
	v_pk_fma_f32 v[42:43], v[42:43], v[6:7], v[140:141] op_sel_hi:[1,0,1]
	v_pk_fma_f32 v[40:41], v[40:41], v[6:7], v[138:139] op_sel_hi:[1,0,1]
	v_cvt_pk_bf16_f32 v234, v52, v53
	v_cvt_pk_bf16_f32 v235, v54, v55
	v_cvt_pk_bf16_f32 v236, v48, v49
	v_cvt_pk_bf16_f32 v237, v50, v51
	v_cvt_pk_bf16_f32 v238, v44, v45
	v_cvt_pk_bf16_f32 v239, v46, v47
	v_cvt_pk_bf16_f32 v240, v40, v41
	v_cvt_pk_bf16_f32 v241, v42, v43
	s_mov_b64 vcc, s[6:7]
	v_cndmask_b32_dpp v52, v238, v234, vcc row_ror:8 row_mask:0xf bank_mask:0xf
	v_cndmask_b32_dpp v53, v239, v235, vcc row_ror:8 row_mask:0xf bank_mask:0xf
	v_cndmask_b32_dpp v54, v240, v236, vcc row_ror:8 row_mask:0xf bank_mask:0xf
	v_cndmask_b32_dpp v55, v241, v237, vcc row_ror:8 row_mask:0xf bank_mask:0xf
	s_not_b64 vcc, s[6:7]
	v_cndmask_b32_dpp v48, v234, v238, vcc row_ror:8 row_mask:0xf bank_mask:0xf
	v_cndmask_b32_dpp v49, v235, v239, vcc row_ror:8 row_mask:0xf bank_mask:0xf
	v_cndmask_b32_dpp v50, v236, v240, vcc row_ror:8 row_mask:0xf bank_mask:0xf
	v_cndmask_b32_dpp v51, v237, v241, vcc row_ror:8 row_mask:0xf bank_mask:0xf
	global_store_dwordx4 v246, v[52:55], s[12:13]
	global_store_dwordx4 v247, v[48:51], s[12:13]
	v_add_f32_e32 v4, v226, v227
	v_add_f32_e32 v5, v228, v229
	v_add_f32_e32 v4, v4, v5
	v_fmamk_f32 v4, v4, 0x3a800000, v212
	v_rsq_f32_e32 v6, v4
	s_add_u32 s12, s12, 0x8000
	s_addc_u32 s13, s13, 0
	v_pk_fma_f32 v[38:39], v[38:39], v[6:7], v[152:153] op_sel_hi:[1,0,1]
	v_pk_fma_f32 v[36:37], v[36:37], v[6:7], v[150:151] op_sel_hi:[1,0,1]
	v_pk_fma_f32 v[34:35], v[34:35], v[6:7], v[148:149] op_sel_hi:[1,0,1]
	v_pk_fma_f32 v[32:33], v[32:33], v[6:7], v[146:147] op_sel_hi:[1,0,1]
	v_pk_fma_f32 v[30:31], v[30:31], v[6:7], v[144:145] op_sel_hi:[1,0,1]
	v_pk_fma_f32 v[28:29], v[28:29], v[6:7], v[142:143] op_sel_hi:[1,0,1]
	v_pk_fma_f32 v[26:27], v[26:27], v[6:7], v[140:141] op_sel_hi:[1,0,1]
	v_pk_fma_f32 v[24:25], v[24:25], v[6:7], v[138:139] op_sel_hi:[1,0,1]
	v_cvt_pk_bf16_f32 v234, v36, v37
	v_cvt_pk_bf16_f32 v235, v38, v39
	v_cvt_pk_bf16_f32 v236, v32, v33
	v_cvt_pk_bf16_f32 v237, v34, v35
	v_cvt_pk_bf16_f32 v238, v28, v29
	v_cvt_pk_bf16_f32 v239, v30, v31
	v_cvt_pk_bf16_f32 v240, v24, v25
	v_cvt_pk_bf16_f32 v241, v26, v27
	s_mov_b64 vcc, s[6:7]
	v_cndmask_b32_dpp v36, v238, v234, vcc row_ror:8 row_mask:0xf bank_mask:0xf
	v_cndmask_b32_dpp v37, v239, v235, vcc row_ror:8 row_mask:0xf bank_mask:0xf
	v_cndmask_b32_dpp v38, v240, v236, vcc row_ror:8 row_mask:0xf bank_mask:0xf
	v_cndmask_b32_dpp v39, v241, v237, vcc row_ror:8 row_mask:0xf bank_mask:0xf
	s_not_b64 vcc, s[6:7]
	v_cndmask_b32_dpp v32, v234, v238, vcc row_ror:8 row_mask:0xf bank_mask:0xf
	v_cndmask_b32_dpp v33, v235, v239, vcc row_ror:8 row_mask:0xf bank_mask:0xf
	v_cndmask_b32_dpp v34, v236, v240, vcc row_ror:8 row_mask:0xf bank_mask:0xf
	v_cndmask_b32_dpp v35, v237, v241, vcc row_ror:8 row_mask:0xf bank_mask:0xf
	global_store_dwordx4 v246, v[36:39], s[12:13]
	global_store_dwordx4 v247, v[32:35], s[12:13]
	v_add_f32_e32 v4, v230, v231
	v_add_f32_e32 v5, v232, v233
	v_add_f32_e32 v4, v4, v5
	v_fmamk_f32 v4, v4, 0x3a800000, v212
	v_rsq_f32_e32 v6, v4
	s_add_u32 s12, s12, 0x8000
	s_addc_u32 s13, s13, 0
	v_pk_fma_f32 v[22:23], v[22:23], v[6:7], v[152:153] op_sel_hi:[1,0,1]
	v_pk_fma_f32 v[20:21], v[20:21], v[6:7], v[150:151] op_sel_hi:[1,0,1]
	v_pk_fma_f32 v[18:19], v[18:19], v[6:7], v[148:149] op_sel_hi:[1,0,1]
	v_pk_fma_f32 v[16:17], v[16:17], v[6:7], v[146:147] op_sel_hi:[1,0,1]
	v_pk_fma_f32 v[14:15], v[14:15], v[6:7], v[144:145] op_sel_hi:[1,0,1]
	v_pk_fma_f32 v[12:13], v[12:13], v[6:7], v[142:143] op_sel_hi:[1,0,1]
	v_pk_fma_f32 v[10:11], v[10:11], v[6:7], v[140:141] op_sel_hi:[1,0,1]
	v_pk_fma_f32 v[8:9], v[8:9], v[6:7], v[138:139] op_sel_hi:[1,0,1]
	v_cvt_pk_bf16_f32 v234, v20, v21
	v_cvt_pk_bf16_f32 v235, v22, v23
	v_cvt_pk_bf16_f32 v236, v16, v17
	v_cvt_pk_bf16_f32 v237, v18, v19
	v_cvt_pk_bf16_f32 v238, v12, v13
	v_cvt_pk_bf16_f32 v239, v14, v15
	v_cvt_pk_bf16_f32 v240, v8, v9
	v_cvt_pk_bf16_f32 v241, v10, v11
	s_mov_b64 vcc, s[6:7]
	v_cndmask_b32_dpp v20, v238, v234, vcc row_ror:8 row_mask:0xf bank_mask:0xf
	v_cndmask_b32_dpp v21, v239, v235, vcc row_ror:8 row_mask:0xf bank_mask:0xf
	v_cndmask_b32_dpp v22, v240, v236, vcc row_ror:8 row_mask:0xf bank_mask:0xf
	v_cndmask_b32_dpp v23, v241, v237, vcc row_ror:8 row_mask:0xf bank_mask:0xf
	s_not_b64 vcc, s[6:7]
	v_cndmask_b32_dpp v16, v234, v238, vcc row_ror:8 row_mask:0xf bank_mask:0xf
	v_cndmask_b32_dpp v17, v235, v239, vcc row_ror:8 row_mask:0xf bank_mask:0xf
	v_cndmask_b32_dpp v18, v236, v240, vcc row_ror:8 row_mask:0xf bank_mask:0xf
	v_cndmask_b32_dpp v19, v237, v241, vcc row_ror:8 row_mask:0xf bank_mask:0xf
	global_store_dwordx4 v246, v[20:23], s[12:13]
	global_store_dwordx4 v247, v[16:19], s[12:13]
	s_mov_b32 s100, 1
	s_branch .LBB0_1422
